# K-loops: 52 LDS-DMA loads switched to saddr form (SGPR base + lane-offset VGPR), removing the per-load 64-bit VALU address add from the load segments
# speedup vs baseline: 1.0146x; 1.0030x over previous
.LBB0_124:
	s_ashr_i32 s79, s78, 31
	s_lshl_b64 s[10:11], s[78:79], 19
	s_add_u32 s80, s54, s10
	v_cmp_lt_i64_e32 vcc, s[72:73], v[178:179]
	s_addc_u32 s81, s55, s11
	s_and_b64 s[10:11], vcc, exec
	s_cselect_b32 s1, s81, s87
	s_cselect_b32 s10, s80, s86
	s_ashr_i32 s77, s76, 31
	s_lshl_b64 s[36:37], s[76:77], 19
	s_add_u32 s72, s66, s36
	s_addc_u32 s73, s59, s37
	s_and_b64 s[36:37], vcc, exec
	s_cselect_b32 s11, s73, s83
	s_cselect_b32 s25, s72, s82
	s_add_u32 s86, s86, 0x40080
	s_addc_u32 s87, s87, 0
	s_add_u32 s33, s82, 0x100
	s_addc_u32 s36, s83, 0
	s_mov_b32 s37, -2
	s_add_u32 s27, s86, 0xfffc0080
	s_addc_u32 s56, s87, -1
	s_add_i32 s57, 0, 0x10000
	v_add_u32_e32 v76, s57, v217
	ds_read_b128 v[64:67], v76
	ds_read_b128 v[68:71], v76 offset:1024
	ds_read_b128 v[72:75], v76 offset:2048
	ds_read_b128 v[76:79], v76 offset:3072
	s_cmp_eq_u32 s37, 12
	s_cselect_b32 vcc_hi, s1, s56
	s_cselect_b32 vcc_lo, s10, s27
	s_cselect_b32 s83, s11, s36
	s_cselect_b32 s82, s25, s33
	s_add_i32 m0, s75, 0xc000
	ds_read_b128 v[80:83], v220
	ds_read_b128 v[84:87], v220 offset:1024
	ds_read_b128 v[88:91], v220 offset:2048
	ds_read_b128 v[92:95], v220 offset:3072
	ds_read_b128 v[188:191], v220 offset:4096
	ds_read_b128 v[192:195], v220 offset:5120
	ds_read_b128 v[196:199], v220 offset:6144
	ds_read_b128 v[200:203], v220 offset:7168
	global_load_lds_dwordx4 v164, s[86:87]
	s_add_i32 m0, s75, 0xe000
	s_nop 0
	global_load_lds_dwordx4 v166, s[86:87]
	s_waitcnt lgkmcnt(8)
	s_barrier
	s_waitcnt lgkmcnt(0)
	v_mfma_f32_16x16x32_bf16 v[146:149], v[64:67], v[80:83], 0
	v_mfma_f32_16x16x32_bf16 v[116:119], v[72:75], v[80:83], 0
	v_mfma_f32_16x16x32_bf16 v[158:161], v[64:67], v[88:91], 0
	v_mfma_f32_16x16x32_bf16 v[124:127], v[72:75], v[88:91], 0
	v_mfma_f32_16x16x32_bf16 v[154:157], v[64:67], v[188:191], 0
	v_mfma_f32_16x16x32_bf16 v[112:115], v[72:75], v[188:191], 0
	v_mfma_f32_16x16x32_bf16 v[150:153], v[64:67], v[196:199], 0
	v_mfma_f32_16x16x32_bf16 v[120:123], v[72:75], v[196:199], 0
	v_mfma_f32_16x16x32_bf16 v[146:149], v[68:71], v[84:87], v[146:149]
	v_mfma_f32_16x16x32_bf16 v[116:119], v[76:79], v[84:87], v[116:119]
	v_mfma_f32_16x16x32_bf16 v[158:161], v[68:71], v[92:95], v[158:161]
	v_mfma_f32_16x16x32_bf16 v[124:127], v[76:79], v[92:95], v[124:127]
	v_mfma_f32_16x16x32_bf16 v[154:157], v[68:71], v[192:195], v[154:157]
	v_mfma_f32_16x16x32_bf16 v[112:115], v[76:79], v[192:195], v[112:115]
	v_mfma_f32_16x16x32_bf16 v[150:153], v[68:71], v[200:203], v[150:153]
	v_mfma_f32_16x16x32_bf16 v[120:123], v[76:79], v[200:203], v[120:123]
	s_barrier
	s_add_i32 s27, 0, 0x14000
	v_add_u32_e32 v168, s27, v217
	s_add_i32 s56, s57, s74
	ds_read_b128 v[204:207], v168
	ds_read_b128 v[222:225], v168 offset:1024
	ds_read_b128 v[228:231], v168 offset:2048
	ds_read_b128 v[232:235], v168 offset:3072
	v_lshl_add_u64 v[168:169], s[82:83], 0, v[144:145]
	s_mov_b32 m0, s56
	v_lshl_add_u64 v[176:177], s[82:83], 0, v[162:163]
	global_load_lds_dwordx4 v[168:169], off
	s_add_i32 m0, s56, 0x2000
	s_nop 0
	global_load_lds_dwordx4 v[176:177], off
	s_barrier
	s_waitcnt lgkmcnt(0)
	v_mfma_f32_16x16x32_bf16 v[140:143], v[204:207], v[80:83], 0
	v_mfma_f32_16x16x32_bf16 v[80:83], v[228:231], v[80:83], 0
	v_mfma_f32_16x16x32_bf16 v[140:143], v[222:225], v[84:87], v[140:143]
	v_mfma_f32_16x16x32_bf16 v[80:83], v[232:235], v[84:87], v[80:83]
	v_mfma_f32_16x16x32_bf16 v[84:87], v[204:207], v[88:91], 0
	v_mfma_f32_16x16x32_bf16 v[88:91], v[228:231], v[88:91], 0
	v_mfma_f32_16x16x32_bf16 v[100:103], v[228:231], v[188:191], 0
	v_mfma_f32_16x16x32_bf16 v[104:107], v[204:207], v[196:199], 0
	v_mfma_f32_16x16x32_bf16 v[96:99], v[228:231], v[196:199], 0
	v_mfma_f32_16x16x32_bf16 v[84:87], v[222:225], v[92:95], v[84:87]
	v_mfma_f32_16x16x32_bf16 v[88:91], v[232:235], v[92:95], v[88:91]
	v_mfma_f32_16x16x32_bf16 v[92:95], v[204:207], v[188:191], 0
	v_mfma_f32_16x16x32_bf16 v[100:103], v[232:235], v[192:195], v[100:103]
	v_mfma_f32_16x16x32_bf16 v[128:131], v[222:225], v[200:203], v[104:107]
	v_mfma_f32_16x16x32_bf16 v[96:99], v[232:235], v[200:203], v[96:99]
	v_mfma_f32_16x16x32_bf16 v[92:95], v[222:225], v[192:195], v[92:95]
	s_barrier
	s_mov_b32 m0, s75
	v_lshl_add_u64 v[240:241], vcc, 0, v[144:145]
	ds_read_b128 v[104:107], v220 offset:16384
	ds_read_b128 v[108:111], v220 offset:17408
	ds_read_b128 v[132:135], v220 offset:18432
	ds_read_b128 v[136:139], v220 offset:19456
	ds_read_b128 v[188:191], v220 offset:20480
	ds_read_b128 v[192:195], v220 offset:21504
	ds_read_b128 v[196:199], v220 offset:22528
	ds_read_b128 v[200:203], v220 offset:23552
	global_load_lds_dwordx4 v[240:241], off
	v_lshl_add_u64 v[242:243], vcc, 0, v[162:163]
	s_mov_b32 m0, s85
	s_nop 0
	global_load_lds_dwordx4 v[242:243], off
	s_barrier
	s_waitcnt lgkmcnt(0)
	v_mfma_f32_16x16x32_bf16 v[48:51], v[64:67], v[104:107], 0
	v_mfma_f32_16x16x32_bf16 v[20:23], v[72:75], v[104:107], 0
	v_mfma_f32_16x16x32_bf16 v[60:63], v[64:67], v[132:135], 0
	v_mfma_f32_16x16x32_bf16 v[28:31], v[72:75], v[132:135], 0
	v_mfma_f32_16x16x32_bf16 v[56:59], v[64:67], v[188:191], 0
	v_mfma_f32_16x16x32_bf16 v[16:19], v[72:75], v[188:191], 0
	v_mfma_f32_16x16x32_bf16 v[52:55], v[64:67], v[196:199], 0
	v_mfma_f32_16x16x32_bf16 v[24:27], v[72:75], v[196:199], 0
	v_mfma_f32_16x16x32_bf16 v[48:51], v[68:71], v[108:111], v[48:51]
	v_mfma_f32_16x16x32_bf16 v[20:23], v[76:79], v[108:111], v[20:23]
	v_mfma_f32_16x16x32_bf16 v[60:63], v[68:71], v[136:139], v[60:63]
	v_mfma_f32_16x16x32_bf16 v[28:31], v[76:79], v[136:139], v[28:31]
	v_mfma_f32_16x16x32_bf16 v[56:59], v[68:71], v[192:195], v[56:59]
	v_mfma_f32_16x16x32_bf16 v[16:19], v[76:79], v[192:195], v[16:19]
	v_mfma_f32_16x16x32_bf16 v[52:55], v[68:71], v[200:203], v[52:55]
	v_mfma_f32_16x16x32_bf16 v[24:27], v[76:79], v[200:203], v[24:27]
	s_barrier
	s_add_u32 s56, s82, 0x40000
	s_addc_u32 s57, s83, 0
	s_add_i32 s27, s27, s74
	s_mov_b32 m0, s27
	s_nop 0
	global_load_lds_dwordx4 v144, s[56:57]
	s_add_i32 m0, s27, 0x2000
	s_nop 0
	global_load_lds_dwordx4 v162, s[56:57]
	s_waitcnt vmcnt(6)
	s_barrier
	v_mfma_f32_16x16x32_bf16 v[44:47], v[204:207], v[104:107], 0
	v_mfma_f32_16x16x32_bf16 v[12:15], v[228:231], v[104:107], 0
	v_mfma_f32_16x16x32_bf16 v[40:43], v[204:207], v[132:135], 0
	v_mfma_f32_16x16x32_bf16 v[8:11], v[228:231], v[132:135], 0
	v_mfma_f32_16x16x32_bf16 v[36:39], v[204:207], v[188:191], 0
	v_mfma_f32_16x16x32_bf16 v[4:7], v[228:231], v[188:191], 0
	v_mfma_f32_16x16x32_bf16 v[32:35], v[204:207], v[196:199], 0
	v_mfma_f32_16x16x32_bf16 v[0:3], v[228:231], v[196:199], 0
	v_mfma_f32_16x16x32_bf16 v[44:47], v[222:225], v[108:111], v[44:47]
	v_mfma_f32_16x16x32_bf16 v[12:15], v[232:235], v[108:111], v[12:15]
	v_mfma_f32_16x16x32_bf16 v[40:43], v[222:225], v[136:139], v[40:43]
	v_mfma_f32_16x16x32_bf16 v[8:11], v[232:235], v[136:139], v[8:11]
	v_mfma_f32_16x16x32_bf16 v[36:39], v[222:225], v[192:195], v[36:39]
	v_mfma_f32_16x16x32_bf16 v[4:7], v[232:235], v[192:195], v[4:7]
	v_mfma_f32_16x16x32_bf16 v[32:35], v[222:225], v[200:203], v[32:35]
	v_mfma_f32_16x16x32_bf16 v[0:3], v[232:235], v[200:203], v[0:3]
	s_barrier
	s_add_i32 s27, 0, 0x18000
	v_add_u32_e32 v76, s27, v217
	ds_read_b128 v[64:67], v76
	ds_read_b128 v[68:71], v76 offset:1024
	ds_read_b128 v[72:75], v76 offset:2048
	ds_read_b128 v[76:79], v76 offset:3072
	s_add_u32 s56, vcc_lo, 0x40000
	s_addc_u32 s57, vcc_hi, 0
	s_mov_b32 m0, s98
	ds_read_b128 v[104:107], v220 offset:32768
	ds_read_b128 v[108:111], v220 offset:33792
	ds_read_b128 v[132:135], v220 offset:34816
	ds_read_b128 v[188:191], v220 offset:35840
	ds_read_b128 v[192:195], v220 offset:36864
	ds_read_b128 v[196:199], v220 offset:37888
	ds_read_b128 v[200:203], v220 offset:38912
	ds_read_b128 v[204:207], v220 offset:39936
	global_load_lds_dwordx4 v144, s[56:57]
	s_mov_b32 m0, s29
	s_nop 0
	global_load_lds_dwordx4 v162, s[56:57]
	s_waitcnt lgkmcnt(8)
	s_barrier
	s_waitcnt lgkmcnt(0)
	v_mfma_f32_16x16x32_bf16 v[136:139], v[64:67], v[104:107], v[146:149]
	v_mfma_f32_16x16x32_bf16 v[146:149], v[68:71], v[108:111], v[136:139]
	v_mfma_f32_16x16x32_bf16 v[136:139], v[64:67], v[132:135], v[158:161]
	v_mfma_f32_16x16x32_bf16 v[158:161], v[68:71], v[188:191], v[136:139]
	v_mfma_f32_16x16x32_bf16 v[136:139], v[64:67], v[192:195], v[154:157]
	v_mfma_f32_16x16x32_bf16 v[116:119], v[72:75], v[104:107], v[116:119]
	v_mfma_f32_16x16x32_bf16 v[124:127], v[72:75], v[132:135], v[124:127]
	v_mfma_f32_16x16x32_bf16 v[154:157], v[68:71], v[196:199], v[136:139]
	v_mfma_f32_16x16x32_bf16 v[112:115], v[72:75], v[192:195], v[112:115]
	v_mfma_f32_16x16x32_bf16 v[136:139], v[64:67], v[200:203], v[150:153]
	v_mfma_f32_16x16x32_bf16 v[120:123], v[72:75], v[200:203], v[120:123]
	v_mfma_f32_16x16x32_bf16 v[116:119], v[76:79], v[108:111], v[116:119]
	v_mfma_f32_16x16x32_bf16 v[124:127], v[76:79], v[188:191], v[124:127]
	v_mfma_f32_16x16x32_bf16 v[112:115], v[76:79], v[196:199], v[112:115]
	v_mfma_f32_16x16x32_bf16 v[150:153], v[68:71], v[204:207], v[136:139]
	v_mfma_f32_16x16x32_bf16 v[120:123], v[76:79], v[204:207], v[120:123]
	s_barrier
	s_add_i32 s58, 0, 0x1c000
	v_add_u32_e32 v136, s58, v217
	s_add_i32 s27, s27, s74
	ds_read_b128 v[222:225], v136
	ds_read_b128 v[228:231], v136 offset:1024
	ds_read_b128 v[232:235], v136 offset:2048
	ds_read_b128 v[236:239], v136 offset:3072
	v_lshl_add_u64 v[136:137], v[168:169], 0, s[18:19]
	s_mov_b32 m0, s27
	s_nop 0
	global_load_lds_dwordx4 v[136:137], off
	v_lshl_add_u64 v[136:137], v[176:177], 0, s[18:19]
	s_add_i32 m0, s27, 0x2000
	s_nop 0
	global_load_lds_dwordx4 v[136:137], off
	s_barrier
	s_waitcnt lgkmcnt(0)
	v_mfma_f32_16x16x32_bf16 v[136:139], v[222:225], v[104:107], v[140:143]
	v_mfma_f32_16x16x32_bf16 v[80:83], v[232:235], v[104:107], v[80:83]
	v_mfma_f32_16x16x32_bf16 v[140:143], v[228:231], v[108:111], v[136:139]
	v_mfma_f32_16x16x32_bf16 v[108:111], v[236:239], v[108:111], v[80:83]
	v_mfma_f32_16x16x32_bf16 v[80:83], v[222:225], v[132:135], v[84:87]
	v_mfma_f32_16x16x32_bf16 v[136:139], v[228:231], v[188:191], v[80:83]
	v_mfma_f32_16x16x32_bf16 v[80:83], v[232:235], v[132:135], v[88:91]
	v_mfma_f32_16x16x32_bf16 v[104:107], v[236:239], v[188:191], v[80:83]
	v_mfma_f32_16x16x32_bf16 v[80:83], v[222:225], v[192:195], v[92:95]
	v_mfma_f32_16x16x32_bf16 v[132:135], v[228:231], v[196:199], v[80:83]
	v_mfma_f32_16x16x32_bf16 v[80:83], v[232:235], v[192:195], v[100:103]
	v_mfma_f32_16x16x32_bf16 v[100:103], v[236:239], v[196:199], v[80:83]
	v_mfma_f32_16x16x32_bf16 v[80:83], v[222:225], v[200:203], v[128:131]
	v_mfma_f32_16x16x32_bf16 v[128:131], v[228:231], v[204:207], v[80:83]
	v_mfma_f32_16x16x32_bf16 v[80:83], v[232:235], v[200:203], v[96:99]
	v_mfma_f32_16x16x32_bf16 v[96:99], v[236:239], v[204:207], v[80:83]
	s_barrier
	s_mov_b32 m0, s31
	v_lshl_add_u64 v[168:169], v[240:241], 0, s[18:19]
	s_nop 2
	ds_read_b128 v[80:83], v220 offset:49152
	ds_read_b128 v[84:87], v220 offset:50176
	ds_read_b128 v[88:91], v220 offset:51200
	ds_read_b128 v[92:95], v220 offset:52224
	ds_read_b128 v[188:191], v220 offset:53248
	ds_read_b128 v[192:195], v220 offset:54272
	ds_read_b128 v[196:199], v220 offset:55296
	ds_read_b128 v[200:203], v220 offset:56320
	global_load_lds_dwordx4 v[168:169], off
	v_lshl_add_u64 v[168:169], v[242:243], 0, s[18:19]
	s_mov_b32 m0, s34
	s_nop 0
	global_load_lds_dwordx4 v[168:169], off
	s_barrier
	s_waitcnt lgkmcnt(0)
	v_mfma_f32_16x16x32_bf16 v[48:51], v[64:67], v[80:83], v[48:51]
	v_mfma_f32_16x16x32_bf16 v[20:23], v[72:75], v[80:83], v[20:23]
	v_mfma_f32_16x16x32_bf16 v[60:63], v[64:67], v[88:91], v[60:63]
	v_mfma_f32_16x16x32_bf16 v[28:31], v[72:75], v[88:91], v[28:31]
	v_mfma_f32_16x16x32_bf16 v[56:59], v[64:67], v[188:191], v[56:59]
	v_mfma_f32_16x16x32_bf16 v[16:19], v[72:75], v[188:191], v[16:19]
	v_mfma_f32_16x16x32_bf16 v[52:55], v[64:67], v[196:199], v[52:55]
	v_mfma_f32_16x16x32_bf16 v[24:27], v[72:75], v[196:199], v[24:27]
	v_mfma_f32_16x16x32_bf16 v[48:51], v[68:71], v[84:87], v[48:51]
	v_mfma_f32_16x16x32_bf16 v[20:23], v[76:79], v[84:87], v[20:23]
	v_mfma_f32_16x16x32_bf16 v[60:63], v[68:71], v[92:95], v[60:63]
	v_mfma_f32_16x16x32_bf16 v[28:31], v[76:79], v[92:95], v[28:31]
	v_mfma_f32_16x16x32_bf16 v[56:59], v[68:71], v[192:195], v[56:59]
	v_mfma_f32_16x16x32_bf16 v[16:19], v[76:79], v[192:195], v[16:19]
	v_mfma_f32_16x16x32_bf16 v[52:55], v[68:71], v[200:203], v[52:55]
	v_mfma_f32_16x16x32_bf16 v[24:27], v[76:79], v[200:203], v[24:27]
	s_barrier
	s_add_u32 s56, s82, 0x40080
	s_addc_u32 s57, s83, 0
	s_add_i32 s27, s58, s74
	s_mov_b32 m0, s27
	s_nop 0
	global_load_lds_dwordx4 v144, s[56:57]
	s_add_i32 m0, s27, 0x2000
	s_nop 0
	global_load_lds_dwordx4 v162, s[56:57]
	s_waitcnt vmcnt(6)
	s_barrier
	v_mfma_f32_16x16x32_bf16 v[44:47], v[222:225], v[80:83], v[44:47]
	v_mfma_f32_16x16x32_bf16 v[12:15], v[232:235], v[80:83], v[12:15]
	v_mfma_f32_16x16x32_bf16 v[40:43], v[222:225], v[88:91], v[40:43]
	v_mfma_f32_16x16x32_bf16 v[8:11], v[232:235], v[88:91], v[8:11]
	v_mfma_f32_16x16x32_bf16 v[36:39], v[222:225], v[188:191], v[36:39]
	v_mfma_f32_16x16x32_bf16 v[4:7], v[232:235], v[188:191], v[4:7]
	v_mfma_f32_16x16x32_bf16 v[32:35], v[222:225], v[196:199], v[32:35]
	v_mfma_f32_16x16x32_bf16 v[0:3], v[232:235], v[196:199], v[0:3]
	v_mfma_f32_16x16x32_bf16 v[44:47], v[228:231], v[84:87], v[44:47]
	v_mfma_f32_16x16x32_bf16 v[12:15], v[236:239], v[84:87], v[12:15]
	v_mfma_f32_16x16x32_bf16 v[40:43], v[228:231], v[92:95], v[40:43]
	v_mfma_f32_16x16x32_bf16 v[8:11], v[236:239], v[92:95], v[8:11]
	v_mfma_f32_16x16x32_bf16 v[36:39], v[228:231], v[192:195], v[36:39]
	v_mfma_f32_16x16x32_bf16 v[4:7], v[236:239], v[192:195], v[4:7]
	v_mfma_f32_16x16x32_bf16 v[32:35], v[228:231], v[200:203], v[32:35]
	v_mfma_f32_16x16x32_bf16 v[0:3], v[236:239], v[200:203], v[0:3]
	s_barrier
	s_add_i32 s37, s37, 2
	s_add_u32 s86, s86, 0x100
	s_addc_u32 s87, s87, 0
	s_add_u32 s33, s33, 0x100
	s_addc_u32 s36, s36, 0
	s_cmp_gt_u32 s37, 13
.LBB0_125:
	s_add_u32 s27, s86, 0xfffc0080
	s_addc_u32 s56, s87, -1
	s_add_i32 s57, 0, 0x10000
	v_add_u32_e32 v76, s57, v217
	ds_read_b128 v[64:67], v76
	ds_read_b128 v[68:71], v76 offset:1024
	ds_read_b128 v[72:75], v76 offset:2048
	ds_read_b128 v[76:79], v76 offset:3072
	s_cmp_eq_u32 s37, 12
	s_cselect_b32 vcc_hi, s1, s56
	s_cselect_b32 vcc_lo, s10, s27
	s_cselect_b32 s83, s11, s36
	s_cselect_b32 s82, s25, s33
	s_add_i32 m0, s75, 0xc000
	ds_read_b128 v[80:83], v220
	ds_read_b128 v[84:87], v220 offset:1024
	ds_read_b128 v[88:91], v220 offset:2048
	ds_read_b128 v[92:95], v220 offset:3072
	ds_read_b128 v[188:191], v220 offset:4096
	ds_read_b128 v[192:195], v220 offset:5120
	ds_read_b128 v[196:199], v220 offset:6144
	ds_read_b128 v[200:203], v220 offset:7168
	global_load_lds_dwordx4 v164, s[86:87]
	s_add_i32 m0, s75, 0xe000
	s_nop 0
	global_load_lds_dwordx4 v166, s[86:87]
	s_waitcnt lgkmcnt(8)
	s_barrier
	s_waitcnt lgkmcnt(0)
	v_mfma_f32_16x16x32_bf16 v[146:149], v[64:67], v[80:83], v[146:149]
	v_mfma_f32_16x16x32_bf16 v[116:119], v[72:75], v[80:83], v[116:119]
	v_mfma_f32_16x16x32_bf16 v[158:161], v[64:67], v[88:91], v[158:161]
	v_mfma_f32_16x16x32_bf16 v[124:127], v[72:75], v[88:91], v[124:127]
	v_mfma_f32_16x16x32_bf16 v[154:157], v[64:67], v[188:191], v[154:157]
	v_mfma_f32_16x16x32_bf16 v[112:115], v[72:75], v[188:191], v[112:115]
	v_mfma_f32_16x16x32_bf16 v[150:153], v[64:67], v[196:199], v[150:153]
	v_mfma_f32_16x16x32_bf16 v[120:123], v[72:75], v[196:199], v[120:123]
	v_mfma_f32_16x16x32_bf16 v[146:149], v[68:71], v[84:87], v[146:149]
	v_mfma_f32_16x16x32_bf16 v[116:119], v[76:79], v[84:87], v[116:119]
	v_mfma_f32_16x16x32_bf16 v[158:161], v[68:71], v[92:95], v[158:161]
	v_mfma_f32_16x16x32_bf16 v[124:127], v[76:79], v[92:95], v[124:127]
	v_mfma_f32_16x16x32_bf16 v[154:157], v[68:71], v[192:195], v[154:157]
	v_mfma_f32_16x16x32_bf16 v[112:115], v[76:79], v[192:195], v[112:115]
	v_mfma_f32_16x16x32_bf16 v[150:153], v[68:71], v[200:203], v[150:153]
	v_mfma_f32_16x16x32_bf16 v[120:123], v[76:79], v[200:203], v[120:123]
	s_barrier
	s_add_i32 s27, 0, 0x14000
	v_add_u32_e32 v168, s27, v217
	s_add_i32 s56, s57, s74
	ds_read_b128 v[204:207], v168
	ds_read_b128 v[222:225], v168 offset:1024
	ds_read_b128 v[228:231], v168 offset:2048
	ds_read_b128 v[232:235], v168 offset:3072
	v_lshl_add_u64 v[168:169], s[82:83], 0, v[144:145]
	s_mov_b32 m0, s56
	v_lshl_add_u64 v[176:177], s[82:83], 0, v[162:163]
	global_load_lds_dwordx4 v[168:169], off
	s_add_i32 m0, s56, 0x2000
	s_nop 0
	global_load_lds_dwordx4 v[176:177], off
	s_barrier
	s_waitcnt lgkmcnt(0)
	v_mfma_f32_16x16x32_bf16 v[140:143], v[204:207], v[80:83], v[140:143]
	v_mfma_f32_16x16x32_bf16 v[80:83], v[228:231], v[80:83], v[108:111]
	v_mfma_f32_16x16x32_bf16 v[140:143], v[222:225], v[84:87], v[140:143]
	v_mfma_f32_16x16x32_bf16 v[80:83], v[232:235], v[84:87], v[80:83]
	v_mfma_f32_16x16x32_bf16 v[84:87], v[204:207], v[88:91], v[136:139]
	v_mfma_f32_16x16x32_bf16 v[88:91], v[228:231], v[88:91], v[104:107]
	v_mfma_f32_16x16x32_bf16 v[100:103], v[228:231], v[188:191], v[100:103]
	v_mfma_f32_16x16x32_bf16 v[104:107], v[204:207], v[196:199], v[128:131]
	v_mfma_f32_16x16x32_bf16 v[96:99], v[228:231], v[196:199], v[96:99]
	v_mfma_f32_16x16x32_bf16 v[84:87], v[222:225], v[92:95], v[84:87]
	v_mfma_f32_16x16x32_bf16 v[88:91], v[232:235], v[92:95], v[88:91]
	v_mfma_f32_16x16x32_bf16 v[92:95], v[204:207], v[188:191], v[132:135]
	v_mfma_f32_16x16x32_bf16 v[100:103], v[232:235], v[192:195], v[100:103]
	v_mfma_f32_16x16x32_bf16 v[128:131], v[222:225], v[200:203], v[104:107]
	v_mfma_f32_16x16x32_bf16 v[96:99], v[232:235], v[200:203], v[96:99]
	v_mfma_f32_16x16x32_bf16 v[92:95], v[222:225], v[192:195], v[92:95]
	s_barrier
	s_mov_b32 m0, s75
	v_lshl_add_u64 v[240:241], vcc, 0, v[144:145]
	ds_read_b128 v[104:107], v220 offset:16384
	ds_read_b128 v[108:111], v220 offset:17408
	ds_read_b128 v[132:135], v220 offset:18432
	ds_read_b128 v[136:139], v220 offset:19456
	ds_read_b128 v[188:191], v220 offset:20480
	ds_read_b128 v[192:195], v220 offset:21504
	ds_read_b128 v[196:199], v220 offset:22528
	ds_read_b128 v[200:203], v220 offset:23552
	global_load_lds_dwordx4 v[240:241], off
	v_lshl_add_u64 v[242:243], vcc, 0, v[162:163]
	s_mov_b32 m0, s85
	s_nop 0
	global_load_lds_dwordx4 v[242:243], off
	s_barrier
	s_waitcnt lgkmcnt(0)
	v_mfma_f32_16x16x32_bf16 v[48:51], v[64:67], v[104:107], v[48:51]
	v_mfma_f32_16x16x32_bf16 v[20:23], v[72:75], v[104:107], v[20:23]
	v_mfma_f32_16x16x32_bf16 v[60:63], v[64:67], v[132:135], v[60:63]
	v_mfma_f32_16x16x32_bf16 v[28:31], v[72:75], v[132:135], v[28:31]
	v_mfma_f32_16x16x32_bf16 v[56:59], v[64:67], v[188:191], v[56:59]
	v_mfma_f32_16x16x32_bf16 v[16:19], v[72:75], v[188:191], v[16:19]
	v_mfma_f32_16x16x32_bf16 v[52:55], v[64:67], v[196:199], v[52:55]
	v_mfma_f32_16x16x32_bf16 v[24:27], v[72:75], v[196:199], v[24:27]
	v_mfma_f32_16x16x32_bf16 v[48:51], v[68:71], v[108:111], v[48:51]
	v_mfma_f32_16x16x32_bf16 v[20:23], v[76:79], v[108:111], v[20:23]
	v_mfma_f32_16x16x32_bf16 v[60:63], v[68:71], v[136:139], v[60:63]
	v_mfma_f32_16x16x32_bf16 v[28:31], v[76:79], v[136:139], v[28:31]
	v_mfma_f32_16x16x32_bf16 v[56:59], v[68:71], v[192:195], v[56:59]
	v_mfma_f32_16x16x32_bf16 v[16:19], v[76:79], v[192:195], v[16:19]
	v_mfma_f32_16x16x32_bf16 v[52:55], v[68:71], v[200:203], v[52:55]
	v_mfma_f32_16x16x32_bf16 v[24:27], v[76:79], v[200:203], v[24:27]
	s_barrier
	s_add_u32 s56, s82, 0x40000
	s_addc_u32 s57, s83, 0
	s_add_i32 s27, s27, s74
	s_mov_b32 m0, s27
	s_nop 0
	global_load_lds_dwordx4 v144, s[56:57]
	s_add_i32 m0, s27, 0x2000
	s_nop 0
	global_load_lds_dwordx4 v162, s[56:57]
	s_waitcnt vmcnt(6)
	s_barrier
	v_mfma_f32_16x16x32_bf16 v[44:47], v[204:207], v[104:107], v[44:47]
	v_mfma_f32_16x16x32_bf16 v[12:15], v[228:231], v[104:107], v[12:15]
	v_mfma_f32_16x16x32_bf16 v[40:43], v[204:207], v[132:135], v[40:43]
	v_mfma_f32_16x16x32_bf16 v[8:11], v[228:231], v[132:135], v[8:11]
	v_mfma_f32_16x16x32_bf16 v[36:39], v[204:207], v[188:191], v[36:39]
	v_mfma_f32_16x16x32_bf16 v[4:7], v[228:231], v[188:191], v[4:7]
	v_mfma_f32_16x16x32_bf16 v[32:35], v[204:207], v[196:199], v[32:35]
	v_mfma_f32_16x16x32_bf16 v[0:3], v[228:231], v[196:199], v[0:3]
	v_mfma_f32_16x16x32_bf16 v[44:47], v[222:225], v[108:111], v[44:47]
	v_mfma_f32_16x16x32_bf16 v[12:15], v[232:235], v[108:111], v[12:15]
	v_mfma_f32_16x16x32_bf16 v[40:43], v[222:225], v[136:139], v[40:43]
	v_mfma_f32_16x16x32_bf16 v[8:11], v[232:235], v[136:139], v[8:11]
	v_mfma_f32_16x16x32_bf16 v[36:39], v[222:225], v[192:195], v[36:39]
	v_mfma_f32_16x16x32_bf16 v[4:7], v[232:235], v[192:195], v[4:7]
	v_mfma_f32_16x16x32_bf16 v[32:35], v[222:225], v[200:203], v[32:35]
	v_mfma_f32_16x16x32_bf16 v[0:3], v[232:235], v[200:203], v[0:3]
	s_barrier
	s_add_i32 s27, 0, 0x18000
	v_add_u32_e32 v76, s27, v217
	ds_read_b128 v[64:67], v76
	ds_read_b128 v[68:71], v76 offset:1024
	ds_read_b128 v[72:75], v76 offset:2048
	ds_read_b128 v[76:79], v76 offset:3072
	s_add_u32 s56, vcc_lo, 0x40000
	s_addc_u32 s57, vcc_hi, 0
	s_mov_b32 m0, s98
	ds_read_b128 v[104:107], v220 offset:32768
	ds_read_b128 v[108:111], v220 offset:33792
	ds_read_b128 v[132:135], v220 offset:34816
	ds_read_b128 v[188:191], v220 offset:35840
	ds_read_b128 v[192:195], v220 offset:36864
	ds_read_b128 v[196:199], v220 offset:37888
	ds_read_b128 v[200:203], v220 offset:38912
	ds_read_b128 v[204:207], v220 offset:39936
	global_load_lds_dwordx4 v144, s[56:57]
	s_mov_b32 m0, s29
	s_nop 0
	global_load_lds_dwordx4 v162, s[56:57]
	s_waitcnt lgkmcnt(8)
	s_barrier
	s_waitcnt lgkmcnt(0)
	v_mfma_f32_16x16x32_bf16 v[136:139], v[64:67], v[104:107], v[146:149]
	v_mfma_f32_16x16x32_bf16 v[146:149], v[68:71], v[108:111], v[136:139]
	v_mfma_f32_16x16x32_bf16 v[136:139], v[64:67], v[132:135], v[158:161]
	v_mfma_f32_16x16x32_bf16 v[158:161], v[68:71], v[188:191], v[136:139]
	v_mfma_f32_16x16x32_bf16 v[136:139], v[64:67], v[192:195], v[154:157]
	v_mfma_f32_16x16x32_bf16 v[116:119], v[72:75], v[104:107], v[116:119]
	v_mfma_f32_16x16x32_bf16 v[124:127], v[72:75], v[132:135], v[124:127]
	v_mfma_f32_16x16x32_bf16 v[154:157], v[68:71], v[196:199], v[136:139]
	v_mfma_f32_16x16x32_bf16 v[112:115], v[72:75], v[192:195], v[112:115]
	v_mfma_f32_16x16x32_bf16 v[136:139], v[64:67], v[200:203], v[150:153]
	v_mfma_f32_16x16x32_bf16 v[120:123], v[72:75], v[200:203], v[120:123]
	v_mfma_f32_16x16x32_bf16 v[116:119], v[76:79], v[108:111], v[116:119]
	v_mfma_f32_16x16x32_bf16 v[124:127], v[76:79], v[188:191], v[124:127]
	v_mfma_f32_16x16x32_bf16 v[112:115], v[76:79], v[196:199], v[112:115]
	v_mfma_f32_16x16x32_bf16 v[150:153], v[68:71], v[204:207], v[136:139]
	v_mfma_f32_16x16x32_bf16 v[120:123], v[76:79], v[204:207], v[120:123]
	s_barrier
	s_add_i32 s58, 0, 0x1c000
	v_add_u32_e32 v136, s58, v217
	s_add_i32 s27, s27, s74
	ds_read_b128 v[222:225], v136
	ds_read_b128 v[228:231], v136 offset:1024
	ds_read_b128 v[232:235], v136 offset:2048
	ds_read_b128 v[236:239], v136 offset:3072
	v_lshl_add_u64 v[136:137], v[168:169], 0, s[18:19]
	s_mov_b32 m0, s27
	s_nop 0
	global_load_lds_dwordx4 v[136:137], off
	v_lshl_add_u64 v[136:137], v[176:177], 0, s[18:19]
	s_add_i32 m0, s27, 0x2000
	s_nop 0
	global_load_lds_dwordx4 v[136:137], off
	s_barrier
	s_waitcnt lgkmcnt(0)
	v_mfma_f32_16x16x32_bf16 v[136:139], v[222:225], v[104:107], v[140:143]
	v_mfma_f32_16x16x32_bf16 v[80:83], v[232:235], v[104:107], v[80:83]
	v_mfma_f32_16x16x32_bf16 v[140:143], v[228:231], v[108:111], v[136:139]
	v_mfma_f32_16x16x32_bf16 v[108:111], v[236:239], v[108:111], v[80:83]
	v_mfma_f32_16x16x32_bf16 v[80:83], v[222:225], v[132:135], v[84:87]
	v_mfma_f32_16x16x32_bf16 v[136:139], v[228:231], v[188:191], v[80:83]
	v_mfma_f32_16x16x32_bf16 v[80:83], v[232:235], v[132:135], v[88:91]
	v_mfma_f32_16x16x32_bf16 v[104:107], v[236:239], v[188:191], v[80:83]
	v_mfma_f32_16x16x32_bf16 v[80:83], v[222:225], v[192:195], v[92:95]
	v_mfma_f32_16x16x32_bf16 v[132:135], v[228:231], v[196:199], v[80:83]
	v_mfma_f32_16x16x32_bf16 v[80:83], v[232:235], v[192:195], v[100:103]
	v_mfma_f32_16x16x32_bf16 v[100:103], v[236:239], v[196:199], v[80:83]
	v_mfma_f32_16x16x32_bf16 v[80:83], v[222:225], v[200:203], v[128:131]
	v_mfma_f32_16x16x32_bf16 v[128:131], v[228:231], v[204:207], v[80:83]
	v_mfma_f32_16x16x32_bf16 v[80:83], v[232:235], v[200:203], v[96:99]
	v_mfma_f32_16x16x32_bf16 v[96:99], v[236:239], v[204:207], v[80:83]
	s_barrier
	s_mov_b32 m0, s31
	v_lshl_add_u64 v[168:169], v[240:241], 0, s[18:19]
	s_nop 2
	ds_read_b128 v[80:83], v220 offset:49152
	ds_read_b128 v[84:87], v220 offset:50176
	ds_read_b128 v[88:91], v220 offset:51200
	ds_read_b128 v[92:95], v220 offset:52224
	ds_read_b128 v[188:191], v220 offset:53248
	ds_read_b128 v[192:195], v220 offset:54272
	ds_read_b128 v[196:199], v220 offset:55296
	ds_read_b128 v[200:203], v220 offset:56320
	global_load_lds_dwordx4 v[168:169], off
	v_lshl_add_u64 v[168:169], v[242:243], 0, s[18:19]
	s_mov_b32 m0, s34
	s_nop 0
	global_load_lds_dwordx4 v[168:169], off
	s_barrier
	s_waitcnt lgkmcnt(0)
	v_mfma_f32_16x16x32_bf16 v[48:51], v[64:67], v[80:83], v[48:51]
	v_mfma_f32_16x16x32_bf16 v[20:23], v[72:75], v[80:83], v[20:23]
	v_mfma_f32_16x16x32_bf16 v[60:63], v[64:67], v[88:91], v[60:63]
	v_mfma_f32_16x16x32_bf16 v[28:31], v[72:75], v[88:91], v[28:31]
	v_mfma_f32_16x16x32_bf16 v[56:59], v[64:67], v[188:191], v[56:59]
	v_mfma_f32_16x16x32_bf16 v[16:19], v[72:75], v[188:191], v[16:19]
	v_mfma_f32_16x16x32_bf16 v[52:55], v[64:67], v[196:199], v[52:55]
	v_mfma_f32_16x16x32_bf16 v[24:27], v[72:75], v[196:199], v[24:27]
	v_mfma_f32_16x16x32_bf16 v[48:51], v[68:71], v[84:87], v[48:51]
	v_mfma_f32_16x16x32_bf16 v[20:23], v[76:79], v[84:87], v[20:23]
	v_mfma_f32_16x16x32_bf16 v[60:63], v[68:71], v[92:95], v[60:63]
	v_mfma_f32_16x16x32_bf16 v[28:31], v[76:79], v[92:95], v[28:31]
	v_mfma_f32_16x16x32_bf16 v[56:59], v[68:71], v[192:195], v[56:59]
	v_mfma_f32_16x16x32_bf16 v[16:19], v[76:79], v[192:195], v[16:19]
	v_mfma_f32_16x16x32_bf16 v[52:55], v[68:71], v[200:203], v[52:55]
	v_mfma_f32_16x16x32_bf16 v[24:27], v[76:79], v[200:203], v[24:27]
	s_barrier
	s_add_u32 s56, s82, 0x40080
	s_addc_u32 s57, s83, 0
	s_add_i32 s27, s58, s74
	s_mov_b32 m0, s27
	s_nop 0
	global_load_lds_dwordx4 v144, s[56:57]
	s_add_i32 m0, s27, 0x2000
	s_nop 0
	global_load_lds_dwordx4 v162, s[56:57]
	s_waitcnt vmcnt(6)
	s_barrier
	v_mfma_f32_16x16x32_bf16 v[44:47], v[222:225], v[80:83], v[44:47]
	v_mfma_f32_16x16x32_bf16 v[12:15], v[232:235], v[80:83], v[12:15]
	v_mfma_f32_16x16x32_bf16 v[40:43], v[222:225], v[88:91], v[40:43]
	v_mfma_f32_16x16x32_bf16 v[8:11], v[232:235], v[88:91], v[8:11]
	v_mfma_f32_16x16x32_bf16 v[36:39], v[222:225], v[188:191], v[36:39]
	v_mfma_f32_16x16x32_bf16 v[4:7], v[232:235], v[188:191], v[4:7]
	v_mfma_f32_16x16x32_bf16 v[32:35], v[222:225], v[196:199], v[32:35]
	v_mfma_f32_16x16x32_bf16 v[0:3], v[232:235], v[196:199], v[0:3]
	v_mfma_f32_16x16x32_bf16 v[44:47], v[228:231], v[84:87], v[44:47]
	v_mfma_f32_16x16x32_bf16 v[12:15], v[236:239], v[84:87], v[12:15]
	v_mfma_f32_16x16x32_bf16 v[40:43], v[228:231], v[92:95], v[40:43]
	v_mfma_f32_16x16x32_bf16 v[8:11], v[236:239], v[92:95], v[8:11]
	v_mfma_f32_16x16x32_bf16 v[36:39], v[228:231], v[192:195], v[36:39]
	v_mfma_f32_16x16x32_bf16 v[4:7], v[236:239], v[192:195], v[4:7]
	v_mfma_f32_16x16x32_bf16 v[32:35], v[228:231], v[200:203], v[32:35]
	v_mfma_f32_16x16x32_bf16 v[0:3], v[236:239], v[200:203], v[0:3]
	s_barrier
	s_add_i32 s37, s37, 2
	s_add_u32 s86, s86, 0x100
	s_addc_u32 s87, s87, 0
	s_add_u32 s33, s33, 0x100
	s_addc_u32 s36, s36, 0
	s_cmp_gt_u32 s37, 13
	s_cbranch_scc0 .LBB0_125
	s_lshl_b32 s1, s84, 8
	v_readlane_b32 s10, v254, 61
	s_add_i32 s1, s1, s10
	v_or_b32_e32 v198, s1, v216
	s_add_i32 s10, s1, 0x80
	v_or_b32_e32 v168, s10, v216
	v_lshl_or_b32 v188, s0, 7, v219
	v_lshlrev_b32_e32 v190, 2, v188
	v_lshlrev_b32_e32 v189, 1, v188
	s_ashr_i32 s11, s1, 5
	s_movk_i32 s10, 0xb00
	s_movk_i32 s20, 0x1600
	s_mov_b32 s101, 0xbfb8aa3b
	s_cmp_eq_u32 s84, s100
	s_cbranch_scc1 .Ldepi_w
	v_ashrrev_i32_e32 v199, 31, v198
	v_ashrrev_i32_e32 v169, 31, v168
	v_lshl_add_u64 v[170:171], v[198:199], 3, s[48:49]
	v_lshl_add_u64 v[172:173], v[168:169], 3, s[48:49]
	global_load_dwordx2 v[176:177], v[170:171], off
	global_load_dwordx2 v[202:203], v[170:171], off offset:128
	global_load_dwordx2 v[206:207], v[170:171], off offset:256
	global_load_dwordx2 v[222:223], v[170:171], off offset:384
	global_load_dwordx2 v[200:201], v[172:173], off
	global_load_dwordx2 v[196:197], v[172:173], off offset:128
	global_load_dwordx2 v[194:195], v[172:173], off offset:256
	global_load_dwordx2 v[192:193], v[172:173], off offset:384

.LBB0_195:
	s_add_u32 s42, s78, 0x80
	s_addc_u32 s43, s79, 0
	s_add_u32 s33, s44, 0x100
	s_addc_u32 s37, s45, 0
	s_mov_b32 s27, 0
	s_waitcnt lgkmcnt(0)
	s_add_i32 s56, s27, 2
	s_add_u32 s44, s42, 0x80
	s_addc_u32 s45, s43, 0
	s_add_i32 s57, 0, 0x10000
	v_add_u32_e32 v140, s57, v207
	ds_read_b128 v[128:131], v140
	ds_read_b128 v[132:135], v140 offset:1024
	ds_read_b128 v[136:139], v140 offset:2048
	ds_read_b128 v[140:143], v140 offset:3072
	s_cmp_eq_u32 s82, s27
	s_cselect_b32 s45, s77, s45
	s_cselect_b32 s44, s76, s44
	s_cselect_b32 s79, s1, s37
	s_cselect_b32 s78, s0, s33
	v_lshl_add_u64 v[176:177], s[42:43], 0, v[190:191]
	s_add_i32 m0, s85, 0xc000
	ds_read_b128 v[146:149], v217
	ds_read_b128 v[150:153], v217 offset:1024
	ds_read_b128 v[154:157], v217 offset:2048
	ds_read_b128 v[158:161], v217 offset:3072
	ds_read_b128 v[162:165], v217 offset:4096
	ds_read_b128 v[166:169], v217 offset:5120
	ds_read_b128 v[194:197], v217 offset:6144
	ds_read_b128 v[198:201], v217 offset:7168
	global_load_lds_dwordx4 v[176:177], off
	v_lshl_add_u64 v[176:177], s[42:43], 0, v[192:193]
	s_add_i32 m0, s85, 0xe000
	s_nop 0
	global_load_lds_dwordx4 v[176:177], off
	s_waitcnt lgkmcnt(8)
	s_barrier
	s_waitcnt lgkmcnt(0)
	v_mfma_f32_16x16x32_bf16 v[124:127], v[128:131], v[146:149], 0
	v_mfma_f32_16x16x32_bf16 v[120:123], v[136:139], v[146:149], 0
	v_mfma_f32_16x16x32_bf16 v[108:111], v[128:131], v[154:157], 0
	v_mfma_f32_16x16x32_bf16 v[104:107], v[136:139], v[154:157], 0
	v_mfma_f32_16x16x32_bf16 v[92:95], v[128:131], v[162:165], 0
	v_mfma_f32_16x16x32_bf16 v[88:91], v[136:139], v[162:165], 0
	v_mfma_f32_16x16x32_bf16 v[76:79], v[128:131], v[194:197], 0
	v_mfma_f32_16x16x32_bf16 v[72:75], v[136:139], v[194:197], 0
	v_mfma_f32_16x16x32_bf16 v[124:127], v[132:135], v[150:153], v[124:127]
	v_mfma_f32_16x16x32_bf16 v[120:123], v[140:143], v[150:153], v[120:123]
	v_mfma_f32_16x16x32_bf16 v[108:111], v[132:135], v[158:161], v[108:111]
	v_mfma_f32_16x16x32_bf16 v[104:107], v[140:143], v[158:161], v[104:107]
	v_mfma_f32_16x16x32_bf16 v[92:95], v[132:135], v[166:169], v[92:95]
	v_mfma_f32_16x16x32_bf16 v[88:91], v[140:143], v[166:169], v[88:91]
	v_mfma_f32_16x16x32_bf16 v[76:79], v[132:135], v[198:201], v[76:79]
	v_mfma_f32_16x16x32_bf16 v[72:75], v[140:143], v[198:201], v[72:75]
	s_barrier
	s_add_i32 s27, 0, 0x14000
	v_add_u32_e32 v176, s27, v207
	s_add_i32 s57, s57, s84
	ds_read_b128 v[202:205], v176
	ds_read_b128 v[218:221], v176 offset:1024
	ds_read_b128 v[222:225], v176 offset:2048
	ds_read_b128 v[228:231], v176 offset:3072
	v_lshl_add_u64 v[176:177], s[78:79], 0, v[144:145]
	s_mov_b32 m0, s57
	v_lshl_add_u64 v[232:233], s[78:79], 0, v[188:189]
	global_load_lds_dwordx4 v[176:177], off
	s_add_i32 m0, s57, 0x2000
	s_nop 0
	global_load_lds_dwordx4 v[232:233], off
	s_barrier
	s_waitcnt lgkmcnt(0)
	v_mfma_f32_16x16x32_bf16 v[116:119], v[202:205], v[146:149], 0
	v_mfma_f32_16x16x32_bf16 v[112:115], v[222:225], v[146:149], 0
	v_mfma_f32_16x16x32_bf16 v[100:103], v[202:205], v[154:157], 0
	v_mfma_f32_16x16x32_bf16 v[96:99], v[222:225], v[154:157], 0
	v_mfma_f32_16x16x32_bf16 v[84:87], v[202:205], v[162:165], 0
	v_mfma_f32_16x16x32_bf16 v[80:83], v[222:225], v[162:165], 0
	v_mfma_f32_16x16x32_bf16 v[68:71], v[202:205], v[194:197], 0
	v_mfma_f32_16x16x32_bf16 v[64:67], v[222:225], v[194:197], 0
	v_mfma_f32_16x16x32_bf16 v[116:119], v[218:221], v[150:153], v[116:119]
	v_mfma_f32_16x16x32_bf16 v[112:115], v[228:231], v[150:153], v[112:115]
	v_mfma_f32_16x16x32_bf16 v[100:103], v[218:221], v[158:161], v[100:103]
	v_mfma_f32_16x16x32_bf16 v[96:99], v[228:231], v[158:161], v[96:99]
	v_mfma_f32_16x16x32_bf16 v[84:87], v[218:221], v[166:169], v[84:87]
	v_mfma_f32_16x16x32_bf16 v[80:83], v[228:231], v[166:169], v[80:83]
	v_mfma_f32_16x16x32_bf16 v[68:71], v[218:221], v[198:201], v[68:71]
	v_mfma_f32_16x16x32_bf16 v[64:67], v[228:231], v[198:201], v[64:67]
	s_barrier
	s_mov_b32 m0, s85
	v_lshl_add_u64 v[234:235], s[44:45], 0, v[144:145]
	ds_read_b128 v[146:149], v217 offset:16384
	ds_read_b128 v[150:153], v217 offset:17408
	ds_read_b128 v[154:157], v217 offset:18432
	ds_read_b128 v[158:161], v217 offset:19456
	ds_read_b128 v[162:165], v217 offset:20480
	ds_read_b128 v[166:169], v217 offset:21504
	ds_read_b128 v[194:197], v217 offset:22528
	ds_read_b128 v[198:201], v217 offset:23552
	global_load_lds_dwordx4 v[234:235], off
	v_lshl_add_u64 v[236:237], s[44:45], 0, v[188:189]
	s_mov_b32 m0, s86
	s_nop 0
	global_load_lds_dwordx4 v[236:237], off
	s_barrier
	s_waitcnt lgkmcnt(0)
	v_mfma_f32_16x16x32_bf16 v[60:63], v[128:131], v[146:149], 0
	v_mfma_f32_16x16x32_bf16 v[56:59], v[136:139], v[146:149], 0
	v_mfma_f32_16x16x32_bf16 v[44:47], v[128:131], v[154:157], 0
	v_mfma_f32_16x16x32_bf16 v[40:43], v[136:139], v[154:157], 0
	v_mfma_f32_16x16x32_bf16 v[28:31], v[128:131], v[162:165], 0
	v_mfma_f32_16x16x32_bf16 v[24:27], v[136:139], v[162:165], 0
	v_mfma_f32_16x16x32_bf16 v[12:15], v[128:131], v[194:197], 0
	v_mfma_f32_16x16x32_bf16 v[8:11], v[136:139], v[194:197], 0
	v_mfma_f32_16x16x32_bf16 v[60:63], v[132:135], v[150:153], v[60:63]
	v_mfma_f32_16x16x32_bf16 v[56:59], v[140:143], v[150:153], v[56:59]
	v_mfma_f32_16x16x32_bf16 v[44:47], v[132:135], v[158:161], v[44:47]
	v_mfma_f32_16x16x32_bf16 v[40:43], v[140:143], v[158:161], v[40:43]
	v_mfma_f32_16x16x32_bf16 v[28:31], v[132:135], v[166:169], v[28:31]
	v_mfma_f32_16x16x32_bf16 v[24:27], v[140:143], v[166:169], v[24:27]
	v_mfma_f32_16x16x32_bf16 v[12:15], v[132:135], v[198:201], v[12:15]
	v_mfma_f32_16x16x32_bf16 v[8:11], v[140:143], v[198:201], v[8:11]
	s_barrier
	s_add_u32 s58, s78, s98
	s_addc_u32 s59, s79, 0
	s_add_i32 s27, s27, s84
	v_lshl_add_u64 v[238:239], s[58:59], 0, v[144:145]
	s_mov_b32 m0, s27
	v_lshl_add_u64 v[240:241], s[58:59], 0, v[188:189]
	global_load_lds_dwordx4 v[238:239], off
	s_add_i32 m0, s27, 0x2000
	s_nop 0
	global_load_lds_dwordx4 v[240:241], off
	s_waitcnt vmcnt(6)
	s_barrier
	v_mfma_f32_16x16x32_bf16 v[52:55], v[202:205], v[146:149], 0
	v_mfma_f32_16x16x32_bf16 v[48:51], v[222:225], v[146:149], 0
	v_mfma_f32_16x16x32_bf16 v[36:39], v[202:205], v[154:157], 0
	v_mfma_f32_16x16x32_bf16 v[32:35], v[222:225], v[154:157], 0
	v_mfma_f32_16x16x32_bf16 v[20:23], v[202:205], v[162:165], 0
	v_mfma_f32_16x16x32_bf16 v[16:19], v[222:225], v[162:165], 0
	v_mfma_f32_16x16x32_bf16 v[4:7], v[202:205], v[194:197], 0
	v_mfma_f32_16x16x32_bf16 v[0:3], v[222:225], v[194:197], 0
	v_mfma_f32_16x16x32_bf16 v[52:55], v[218:221], v[150:153], v[52:55]
	v_mfma_f32_16x16x32_bf16 v[48:51], v[228:231], v[150:153], v[48:51]
	v_mfma_f32_16x16x32_bf16 v[36:39], v[218:221], v[158:161], v[36:39]
	v_mfma_f32_16x16x32_bf16 v[32:35], v[228:231], v[158:161], v[32:35]
	v_mfma_f32_16x16x32_bf16 v[20:23], v[218:221], v[166:169], v[20:23]
	v_mfma_f32_16x16x32_bf16 v[16:19], v[228:231], v[166:169], v[16:19]
	v_mfma_f32_16x16x32_bf16 v[4:7], v[218:221], v[198:201], v[4:7]
	v_mfma_f32_16x16x32_bf16 v[0:3], v[228:231], v[198:201], v[0:3]
	s_barrier
	s_add_i32 s27, 0, 0x18000
	v_add_u32_e32 v140, s27, v207
	ds_read_b128 v[128:131], v140
	ds_read_b128 v[132:135], v140 offset:1024
	ds_read_b128 v[136:139], v140 offset:2048
	ds_read_b128 v[140:143], v140 offset:3072
	s_add_u32 s44, s44, s98
	s_addc_u32 s45, s45, 0
	s_mov_b32 m0, s87
	ds_read_b128 v[146:149], v217 offset:32768
	ds_read_b128 v[150:153], v217 offset:33792
	ds_read_b128 v[154:157], v217 offset:34816
	ds_read_b128 v[158:161], v217 offset:35840
	ds_read_b128 v[162:165], v217 offset:36864
	ds_read_b128 v[166:169], v217 offset:37888
	ds_read_b128 v[194:197], v217 offset:38912
	ds_read_b128 v[198:201], v217 offset:39936
	global_load_lds_dwordx4 v144, s[44:45]
	s_mov_b32 m0, s80
	s_nop 0
	global_load_lds_dwordx4 v188, s[44:45]
	s_waitcnt lgkmcnt(8)
	s_barrier
	s_waitcnt lgkmcnt(0)
	v_mfma_f32_16x16x32_bf16 v[124:127], v[128:131], v[146:149], v[124:127]
	v_mfma_f32_16x16x32_bf16 v[120:123], v[136:139], v[146:149], v[120:123]
	v_mfma_f32_16x16x32_bf16 v[108:111], v[128:131], v[154:157], v[108:111]
	v_mfma_f32_16x16x32_bf16 v[104:107], v[136:139], v[154:157], v[104:107]
	v_mfma_f32_16x16x32_bf16 v[92:95], v[128:131], v[162:165], v[92:95]
	v_mfma_f32_16x16x32_bf16 v[88:91], v[136:139], v[162:165], v[88:91]
	v_mfma_f32_16x16x32_bf16 v[76:79], v[128:131], v[194:197], v[76:79]
	v_mfma_f32_16x16x32_bf16 v[72:75], v[136:139], v[194:197], v[72:75]
	v_mfma_f32_16x16x32_bf16 v[124:127], v[132:135], v[150:153], v[124:127]
	v_mfma_f32_16x16x32_bf16 v[120:123], v[140:143], v[150:153], v[120:123]
	v_mfma_f32_16x16x32_bf16 v[108:111], v[132:135], v[158:161], v[108:111]
	v_mfma_f32_16x16x32_bf16 v[104:107], v[140:143], v[158:161], v[104:107]
	v_mfma_f32_16x16x32_bf16 v[92:95], v[132:135], v[166:169], v[92:95]
	v_mfma_f32_16x16x32_bf16 v[88:91], v[140:143], v[166:169], v[88:91]
	v_mfma_f32_16x16x32_bf16 v[76:79], v[132:135], v[198:201], v[76:79]
	v_mfma_f32_16x16x32_bf16 v[72:75], v[140:143], v[198:201], v[72:75]
	s_barrier
	s_add_i32 s44, 0, 0x1c000
	s_add_i32 s27, s27, s84
	v_add_u32_e32 v228, s44, v207
	v_lshl_add_u64 v[176:177], v[176:177], 0, s[18:19]
	s_mov_b32 m0, s27
	ds_read_b128 v[202:205], v228
	ds_read_b128 v[218:221], v228 offset:1024
	ds_read_b128 v[222:225], v228 offset:2048
	ds_read_b128 v[228:231], v228 offset:3072
	global_load_lds_dwordx4 v[176:177], off
	v_lshl_add_u64 v[176:177], v[232:233], 0, s[18:19]
	s_add_i32 m0, s27, 0x2000
	s_nop 0
	global_load_lds_dwordx4 v[176:177], off
	s_barrier
	s_waitcnt lgkmcnt(0)
	v_mfma_f32_16x16x32_bf16 v[116:119], v[202:205], v[146:149], v[116:119]
	v_mfma_f32_16x16x32_bf16 v[112:115], v[222:225], v[146:149], v[112:115]
	v_mfma_f32_16x16x32_bf16 v[100:103], v[202:205], v[154:157], v[100:103]
	v_mfma_f32_16x16x32_bf16 v[96:99], v[222:225], v[154:157], v[96:99]
	v_mfma_f32_16x16x32_bf16 v[84:87], v[202:205], v[162:165], v[84:87]
	v_mfma_f32_16x16x32_bf16 v[80:83], v[222:225], v[162:165], v[80:83]
	v_mfma_f32_16x16x32_bf16 v[68:71], v[202:205], v[194:197], v[68:71]
	v_mfma_f32_16x16x32_bf16 v[64:67], v[222:225], v[194:197], v[64:67]
	v_mfma_f32_16x16x32_bf16 v[116:119], v[218:221], v[150:153], v[116:119]
	v_mfma_f32_16x16x32_bf16 v[112:115], v[228:231], v[150:153], v[112:115]
	v_mfma_f32_16x16x32_bf16 v[100:103], v[218:221], v[158:161], v[100:103]
	v_mfma_f32_16x16x32_bf16 v[96:99], v[228:231], v[158:161], v[96:99]
	v_mfma_f32_16x16x32_bf16 v[84:87], v[218:221], v[166:169], v[84:87]
	v_mfma_f32_16x16x32_bf16 v[80:83], v[228:231], v[166:169], v[80:83]
	v_mfma_f32_16x16x32_bf16 v[68:71], v[218:221], v[198:201], v[68:71]
	v_mfma_f32_16x16x32_bf16 v[64:67], v[228:231], v[198:201], v[64:67]
	s_barrier
	s_mov_b32 m0, s30
	v_lshl_add_u64 v[176:177], v[234:235], 0, s[18:19]
	ds_read_b128 v[146:149], v217 offset:49152
	ds_read_b128 v[150:153], v217 offset:50176
	ds_read_b128 v[154:157], v217 offset:51200
	ds_read_b128 v[158:161], v217 offset:52224
	ds_read_b128 v[162:165], v217 offset:53248
	ds_read_b128 v[166:169], v217 offset:54272
	ds_read_b128 v[194:197], v217 offset:55296
	ds_read_b128 v[198:201], v217 offset:56320
	global_load_lds_dwordx4 v[176:177], off
	v_lshl_add_u64 v[176:177], v[236:237], 0, s[18:19]
	s_mov_b32 m0, s31
	s_nop 0
	global_load_lds_dwordx4 v[176:177], off
	s_barrier
	s_waitcnt lgkmcnt(0)
	v_mfma_f32_16x16x32_bf16 v[60:63], v[128:131], v[146:149], v[60:63]
	v_mfma_f32_16x16x32_bf16 v[56:59], v[136:139], v[146:149], v[56:59]
	v_mfma_f32_16x16x32_bf16 v[44:47], v[128:131], v[154:157], v[44:47]
	v_mfma_f32_16x16x32_bf16 v[40:43], v[136:139], v[154:157], v[40:43]
	v_mfma_f32_16x16x32_bf16 v[28:31], v[128:131], v[162:165], v[28:31]
	v_mfma_f32_16x16x32_bf16 v[24:27], v[136:139], v[162:165], v[24:27]
	v_mfma_f32_16x16x32_bf16 v[12:15], v[128:131], v[194:197], v[12:15]
	v_mfma_f32_16x16x32_bf16 v[8:11], v[136:139], v[194:197], v[8:11]
	v_mfma_f32_16x16x32_bf16 v[60:63], v[132:135], v[150:153], v[60:63]
	v_mfma_f32_16x16x32_bf16 v[56:59], v[140:143], v[150:153], v[56:59]
	v_mfma_f32_16x16x32_bf16 v[44:47], v[132:135], v[158:161], v[44:47]
	v_mfma_f32_16x16x32_bf16 v[40:43], v[140:143], v[158:161], v[40:43]
	v_mfma_f32_16x16x32_bf16 v[28:31], v[132:135], v[166:169], v[28:31]
	v_mfma_f32_16x16x32_bf16 v[24:27], v[140:143], v[166:169], v[24:27]
	v_mfma_f32_16x16x32_bf16 v[12:15], v[132:135], v[198:201], v[12:15]
	v_mfma_f32_16x16x32_bf16 v[8:11], v[140:143], v[198:201], v[8:11]
	s_barrier
	s_add_i32 s27, s44, s84
	v_lshl_add_u64 v[128:129], v[238:239], 0, s[18:19]
	s_mov_b32 m0, s27
	s_nop 0
	global_load_lds_dwordx4 v[128:129], off
	v_lshl_add_u64 v[128:129], v[240:241], 0, s[18:19]
	s_add_i32 m0, s27, 0x2000
	s_nop 0
	global_load_lds_dwordx4 v[128:129], off
	s_waitcnt vmcnt(6)
	s_barrier
	v_mfma_f32_16x16x32_bf16 v[52:55], v[202:205], v[146:149], v[52:55]
	v_mfma_f32_16x16x32_bf16 v[48:51], v[222:225], v[146:149], v[48:51]
	v_mfma_f32_16x16x32_bf16 v[36:39], v[202:205], v[154:157], v[36:39]
	v_mfma_f32_16x16x32_bf16 v[32:35], v[222:225], v[154:157], v[32:35]
	v_mfma_f32_16x16x32_bf16 v[20:23], v[202:205], v[162:165], v[20:23]
	v_mfma_f32_16x16x32_bf16 v[16:19], v[222:225], v[162:165], v[16:19]
	v_mfma_f32_16x16x32_bf16 v[4:7], v[202:205], v[194:197], v[4:7]
	v_mfma_f32_16x16x32_bf16 v[0:3], v[222:225], v[194:197], v[0:3]
	v_mfma_f32_16x16x32_bf16 v[52:55], v[218:221], v[150:153], v[52:55]
	v_mfma_f32_16x16x32_bf16 v[48:51], v[228:231], v[150:153], v[48:51]
	v_mfma_f32_16x16x32_bf16 v[36:39], v[218:221], v[158:161], v[36:39]
	v_mfma_f32_16x16x32_bf16 v[32:35], v[228:231], v[158:161], v[32:35]
	v_mfma_f32_16x16x32_bf16 v[20:23], v[218:221], v[166:169], v[20:23]
	v_mfma_f32_16x16x32_bf16 v[16:19], v[228:231], v[166:169], v[16:19]
	v_mfma_f32_16x16x32_bf16 v[4:7], v[218:221], v[198:201], v[4:7]
	v_mfma_f32_16x16x32_bf16 v[0:3], v[228:231], v[198:201], v[0:3]
	s_barrier
	s_add_u32 s42, s42, 0x100
	s_addc_u32 s43, s43, 0
	s_add_u32 s33, s33, 0x100
	s_addc_u32 s37, s37, 0
	s_cmp_ge_u32 s56, s34
	s_mov_b32 s27, s56
.LBB0_196:
	s_add_i32 s56, s27, 2
	s_add_u32 s44, s42, 0x80
	s_addc_u32 s45, s43, 0
	s_add_i32 s57, 0, 0x10000
	v_add_u32_e32 v140, s57, v207
	ds_read_b128 v[128:131], v140
	ds_read_b128 v[132:135], v140 offset:1024
	ds_read_b128 v[136:139], v140 offset:2048
	ds_read_b128 v[140:143], v140 offset:3072
	s_cmp_eq_u32 s82, s27
	s_cselect_b32 s45, s77, s45
	s_cselect_b32 s44, s76, s44
	s_cselect_b32 s79, s1, s37
	s_cselect_b32 s78, s0, s33
	v_lshl_add_u64 v[176:177], s[42:43], 0, v[190:191]
	s_add_i32 m0, s85, 0xc000
	ds_read_b128 v[146:149], v217
	ds_read_b128 v[150:153], v217 offset:1024
	ds_read_b128 v[154:157], v217 offset:2048
	ds_read_b128 v[158:161], v217 offset:3072
	ds_read_b128 v[162:165], v217 offset:4096
	ds_read_b128 v[166:169], v217 offset:5120
	ds_read_b128 v[194:197], v217 offset:6144
	ds_read_b128 v[198:201], v217 offset:7168
	global_load_lds_dwordx4 v[176:177], off
	v_lshl_add_u64 v[176:177], s[42:43], 0, v[192:193]
	s_add_i32 m0, s85, 0xe000
	s_nop 0
	global_load_lds_dwordx4 v[176:177], off
	s_waitcnt lgkmcnt(8)
	s_barrier
	s_waitcnt lgkmcnt(0)
	v_mfma_f32_16x16x32_bf16 v[124:127], v[128:131], v[146:149], v[124:127]
	v_mfma_f32_16x16x32_bf16 v[120:123], v[136:139], v[146:149], v[120:123]
	v_mfma_f32_16x16x32_bf16 v[108:111], v[128:131], v[154:157], v[108:111]
	v_mfma_f32_16x16x32_bf16 v[104:107], v[136:139], v[154:157], v[104:107]
	v_mfma_f32_16x16x32_bf16 v[92:95], v[128:131], v[162:165], v[92:95]
	v_mfma_f32_16x16x32_bf16 v[88:91], v[136:139], v[162:165], v[88:91]
	v_mfma_f32_16x16x32_bf16 v[76:79], v[128:131], v[194:197], v[76:79]
	v_mfma_f32_16x16x32_bf16 v[72:75], v[136:139], v[194:197], v[72:75]
	v_mfma_f32_16x16x32_bf16 v[124:127], v[132:135], v[150:153], v[124:127]
	v_mfma_f32_16x16x32_bf16 v[120:123], v[140:143], v[150:153], v[120:123]
	v_mfma_f32_16x16x32_bf16 v[108:111], v[132:135], v[158:161], v[108:111]
	v_mfma_f32_16x16x32_bf16 v[104:107], v[140:143], v[158:161], v[104:107]
	v_mfma_f32_16x16x32_bf16 v[92:95], v[132:135], v[166:169], v[92:95]
	v_mfma_f32_16x16x32_bf16 v[88:91], v[140:143], v[166:169], v[88:91]
	v_mfma_f32_16x16x32_bf16 v[76:79], v[132:135], v[198:201], v[76:79]
	v_mfma_f32_16x16x32_bf16 v[72:75], v[140:143], v[198:201], v[72:75]
	s_barrier
	s_add_i32 s27, 0, 0x14000
	v_add_u32_e32 v176, s27, v207
	s_add_i32 s57, s57, s84
	ds_read_b128 v[202:205], v176
	ds_read_b128 v[218:221], v176 offset:1024
	ds_read_b128 v[222:225], v176 offset:2048
	ds_read_b128 v[228:231], v176 offset:3072
	v_lshl_add_u64 v[176:177], s[78:79], 0, v[144:145]
	s_mov_b32 m0, s57
	v_lshl_add_u64 v[232:233], s[78:79], 0, v[188:189]
	global_load_lds_dwordx4 v[176:177], off
	s_add_i32 m0, s57, 0x2000
	s_nop 0
	global_load_lds_dwordx4 v[232:233], off
	s_barrier
	s_waitcnt lgkmcnt(0)
	v_mfma_f32_16x16x32_bf16 v[116:119], v[202:205], v[146:149], v[116:119]
	v_mfma_f32_16x16x32_bf16 v[112:115], v[222:225], v[146:149], v[112:115]
	v_mfma_f32_16x16x32_bf16 v[100:103], v[202:205], v[154:157], v[100:103]
	v_mfma_f32_16x16x32_bf16 v[96:99], v[222:225], v[154:157], v[96:99]
	v_mfma_f32_16x16x32_bf16 v[84:87], v[202:205], v[162:165], v[84:87]
	v_mfma_f32_16x16x32_bf16 v[80:83], v[222:225], v[162:165], v[80:83]
	v_mfma_f32_16x16x32_bf16 v[68:71], v[202:205], v[194:197], v[68:71]
	v_mfma_f32_16x16x32_bf16 v[64:67], v[222:225], v[194:197], v[64:67]
	v_mfma_f32_16x16x32_bf16 v[116:119], v[218:221], v[150:153], v[116:119]
	v_mfma_f32_16x16x32_bf16 v[112:115], v[228:231], v[150:153], v[112:115]
	v_mfma_f32_16x16x32_bf16 v[100:103], v[218:221], v[158:161], v[100:103]
	v_mfma_f32_16x16x32_bf16 v[96:99], v[228:231], v[158:161], v[96:99]
	v_mfma_f32_16x16x32_bf16 v[84:87], v[218:221], v[166:169], v[84:87]
	v_mfma_f32_16x16x32_bf16 v[80:83], v[228:231], v[166:169], v[80:83]
	v_mfma_f32_16x16x32_bf16 v[68:71], v[218:221], v[198:201], v[68:71]
	v_mfma_f32_16x16x32_bf16 v[64:67], v[228:231], v[198:201], v[64:67]
	s_barrier
	s_mov_b32 m0, s85
	v_lshl_add_u64 v[234:235], s[44:45], 0, v[144:145]
	ds_read_b128 v[146:149], v217 offset:16384
	ds_read_b128 v[150:153], v217 offset:17408
	ds_read_b128 v[154:157], v217 offset:18432
	ds_read_b128 v[158:161], v217 offset:19456
	ds_read_b128 v[162:165], v217 offset:20480
	ds_read_b128 v[166:169], v217 offset:21504
	ds_read_b128 v[194:197], v217 offset:22528
	ds_read_b128 v[198:201], v217 offset:23552
	global_load_lds_dwordx4 v[234:235], off
	v_lshl_add_u64 v[236:237], s[44:45], 0, v[188:189]
	s_mov_b32 m0, s86
	s_nop 0
	global_load_lds_dwordx4 v[236:237], off
	s_barrier
	s_waitcnt lgkmcnt(0)
	v_mfma_f32_16x16x32_bf16 v[60:63], v[128:131], v[146:149], v[60:63]
	v_mfma_f32_16x16x32_bf16 v[56:59], v[136:139], v[146:149], v[56:59]
	v_mfma_f32_16x16x32_bf16 v[44:47], v[128:131], v[154:157], v[44:47]
	v_mfma_f32_16x16x32_bf16 v[40:43], v[136:139], v[154:157], v[40:43]
	v_mfma_f32_16x16x32_bf16 v[28:31], v[128:131], v[162:165], v[28:31]
	v_mfma_f32_16x16x32_bf16 v[24:27], v[136:139], v[162:165], v[24:27]
	v_mfma_f32_16x16x32_bf16 v[12:15], v[128:131], v[194:197], v[12:15]
	v_mfma_f32_16x16x32_bf16 v[8:11], v[136:139], v[194:197], v[8:11]
	v_mfma_f32_16x16x32_bf16 v[60:63], v[132:135], v[150:153], v[60:63]
	v_mfma_f32_16x16x32_bf16 v[56:59], v[140:143], v[150:153], v[56:59]
	v_mfma_f32_16x16x32_bf16 v[44:47], v[132:135], v[158:161], v[44:47]
	v_mfma_f32_16x16x32_bf16 v[40:43], v[140:143], v[158:161], v[40:43]
	v_mfma_f32_16x16x32_bf16 v[28:31], v[132:135], v[166:169], v[28:31]
	v_mfma_f32_16x16x32_bf16 v[24:27], v[140:143], v[166:169], v[24:27]
	v_mfma_f32_16x16x32_bf16 v[12:15], v[132:135], v[198:201], v[12:15]
	v_mfma_f32_16x16x32_bf16 v[8:11], v[140:143], v[198:201], v[8:11]
	s_barrier
	s_add_u32 s58, s78, s98
	s_addc_u32 s59, s79, 0
	s_add_i32 s27, s27, s84
	v_lshl_add_u64 v[238:239], s[58:59], 0, v[144:145]
	s_mov_b32 m0, s27
	v_lshl_add_u64 v[240:241], s[58:59], 0, v[188:189]
	global_load_lds_dwordx4 v[238:239], off
	s_add_i32 m0, s27, 0x2000
	s_nop 0
	global_load_lds_dwordx4 v[240:241], off
	s_waitcnt vmcnt(6)
	s_barrier
	v_mfma_f32_16x16x32_bf16 v[52:55], v[202:205], v[146:149], v[52:55]
	v_mfma_f32_16x16x32_bf16 v[48:51], v[222:225], v[146:149], v[48:51]
	v_mfma_f32_16x16x32_bf16 v[36:39], v[202:205], v[154:157], v[36:39]
	v_mfma_f32_16x16x32_bf16 v[32:35], v[222:225], v[154:157], v[32:35]
	v_mfma_f32_16x16x32_bf16 v[20:23], v[202:205], v[162:165], v[20:23]
	v_mfma_f32_16x16x32_bf16 v[16:19], v[222:225], v[162:165], v[16:19]
	v_mfma_f32_16x16x32_bf16 v[4:7], v[202:205], v[194:197], v[4:7]
	v_mfma_f32_16x16x32_bf16 v[0:3], v[222:225], v[194:197], v[0:3]
	v_mfma_f32_16x16x32_bf16 v[52:55], v[218:221], v[150:153], v[52:55]
	v_mfma_f32_16x16x32_bf16 v[48:51], v[228:231], v[150:153], v[48:51]
	v_mfma_f32_16x16x32_bf16 v[36:39], v[218:221], v[158:161], v[36:39]
	v_mfma_f32_16x16x32_bf16 v[32:35], v[228:231], v[158:161], v[32:35]
	v_mfma_f32_16x16x32_bf16 v[20:23], v[218:221], v[166:169], v[20:23]
	v_mfma_f32_16x16x32_bf16 v[16:19], v[228:231], v[166:169], v[16:19]
	v_mfma_f32_16x16x32_bf16 v[4:7], v[218:221], v[198:201], v[4:7]
	v_mfma_f32_16x16x32_bf16 v[0:3], v[228:231], v[198:201], v[0:3]
	s_barrier
	s_add_i32 s27, 0, 0x18000
	v_add_u32_e32 v140, s27, v207
	ds_read_b128 v[128:131], v140
	ds_read_b128 v[132:135], v140 offset:1024
	ds_read_b128 v[136:139], v140 offset:2048
	ds_read_b128 v[140:143], v140 offset:3072
	s_add_u32 s44, s44, s98
	s_addc_u32 s45, s45, 0
	s_mov_b32 m0, s87
	ds_read_b128 v[146:149], v217 offset:32768
	ds_read_b128 v[150:153], v217 offset:33792
	ds_read_b128 v[154:157], v217 offset:34816
	ds_read_b128 v[158:161], v217 offset:35840
	ds_read_b128 v[162:165], v217 offset:36864
	ds_read_b128 v[166:169], v217 offset:37888
	ds_read_b128 v[194:197], v217 offset:38912
	ds_read_b128 v[198:201], v217 offset:39936
	global_load_lds_dwordx4 v144, s[44:45]
	s_mov_b32 m0, s80
	s_nop 0
	global_load_lds_dwordx4 v188, s[44:45]
	s_waitcnt lgkmcnt(8)
	s_barrier
	s_waitcnt lgkmcnt(0)
	v_mfma_f32_16x16x32_bf16 v[124:127], v[128:131], v[146:149], v[124:127]
	v_mfma_f32_16x16x32_bf16 v[120:123], v[136:139], v[146:149], v[120:123]
	v_mfma_f32_16x16x32_bf16 v[108:111], v[128:131], v[154:157], v[108:111]
	v_mfma_f32_16x16x32_bf16 v[104:107], v[136:139], v[154:157], v[104:107]
	v_mfma_f32_16x16x32_bf16 v[92:95], v[128:131], v[162:165], v[92:95]
	v_mfma_f32_16x16x32_bf16 v[88:91], v[136:139], v[162:165], v[88:91]
	v_mfma_f32_16x16x32_bf16 v[76:79], v[128:131], v[194:197], v[76:79]
	v_mfma_f32_16x16x32_bf16 v[72:75], v[136:139], v[194:197], v[72:75]
	v_mfma_f32_16x16x32_bf16 v[124:127], v[132:135], v[150:153], v[124:127]
	v_mfma_f32_16x16x32_bf16 v[120:123], v[140:143], v[150:153], v[120:123]
	v_mfma_f32_16x16x32_bf16 v[108:111], v[132:135], v[158:161], v[108:111]
	v_mfma_f32_16x16x32_bf16 v[104:107], v[140:143], v[158:161], v[104:107]
	v_mfma_f32_16x16x32_bf16 v[92:95], v[132:135], v[166:169], v[92:95]
	v_mfma_f32_16x16x32_bf16 v[88:91], v[140:143], v[166:169], v[88:91]
	v_mfma_f32_16x16x32_bf16 v[76:79], v[132:135], v[198:201], v[76:79]
	v_mfma_f32_16x16x32_bf16 v[72:75], v[140:143], v[198:201], v[72:75]
	s_barrier
	s_add_i32 s44, 0, 0x1c000
	s_add_i32 s27, s27, s84
	v_add_u32_e32 v228, s44, v207
	v_lshl_add_u64 v[176:177], v[176:177], 0, s[18:19]
	s_mov_b32 m0, s27
	ds_read_b128 v[202:205], v228
	ds_read_b128 v[218:221], v228 offset:1024
	ds_read_b128 v[222:225], v228 offset:2048
	ds_read_b128 v[228:231], v228 offset:3072
	global_load_lds_dwordx4 v[176:177], off
	v_lshl_add_u64 v[176:177], v[232:233], 0, s[18:19]
	s_add_i32 m0, s27, 0x2000
	s_nop 0
	global_load_lds_dwordx4 v[176:177], off
	s_barrier
	s_waitcnt lgkmcnt(0)
	v_mfma_f32_16x16x32_bf16 v[116:119], v[202:205], v[146:149], v[116:119]
	v_mfma_f32_16x16x32_bf16 v[112:115], v[222:225], v[146:149], v[112:115]
	v_mfma_f32_16x16x32_bf16 v[100:103], v[202:205], v[154:157], v[100:103]
	v_mfma_f32_16x16x32_bf16 v[96:99], v[222:225], v[154:157], v[96:99]
	v_mfma_f32_16x16x32_bf16 v[84:87], v[202:205], v[162:165], v[84:87]
	v_mfma_f32_16x16x32_bf16 v[80:83], v[222:225], v[162:165], v[80:83]
	v_mfma_f32_16x16x32_bf16 v[68:71], v[202:205], v[194:197], v[68:71]
	v_mfma_f32_16x16x32_bf16 v[64:67], v[222:225], v[194:197], v[64:67]
	v_mfma_f32_16x16x32_bf16 v[116:119], v[218:221], v[150:153], v[116:119]
	v_mfma_f32_16x16x32_bf16 v[112:115], v[228:231], v[150:153], v[112:115]
	v_mfma_f32_16x16x32_bf16 v[100:103], v[218:221], v[158:161], v[100:103]
	v_mfma_f32_16x16x32_bf16 v[96:99], v[228:231], v[158:161], v[96:99]
	v_mfma_f32_16x16x32_bf16 v[84:87], v[218:221], v[166:169], v[84:87]
	v_mfma_f32_16x16x32_bf16 v[80:83], v[228:231], v[166:169], v[80:83]
	v_mfma_f32_16x16x32_bf16 v[68:71], v[218:221], v[198:201], v[68:71]
	v_mfma_f32_16x16x32_bf16 v[64:67], v[228:231], v[198:201], v[64:67]
	s_barrier
	s_mov_b32 m0, s30
	v_lshl_add_u64 v[176:177], v[234:235], 0, s[18:19]
	ds_read_b128 v[146:149], v217 offset:49152
	ds_read_b128 v[150:153], v217 offset:50176
	ds_read_b128 v[154:157], v217 offset:51200
	ds_read_b128 v[158:161], v217 offset:52224
	ds_read_b128 v[162:165], v217 offset:53248
	ds_read_b128 v[166:169], v217 offset:54272
	ds_read_b128 v[194:197], v217 offset:55296
	ds_read_b128 v[198:201], v217 offset:56320
	global_load_lds_dwordx4 v[176:177], off
	v_lshl_add_u64 v[176:177], v[236:237], 0, s[18:19]
	s_mov_b32 m0, s31
	s_nop 0
	global_load_lds_dwordx4 v[176:177], off
	s_barrier
	s_waitcnt lgkmcnt(0)
	v_mfma_f32_16x16x32_bf16 v[60:63], v[128:131], v[146:149], v[60:63]
	v_mfma_f32_16x16x32_bf16 v[56:59], v[136:139], v[146:149], v[56:59]
	v_mfma_f32_16x16x32_bf16 v[44:47], v[128:131], v[154:157], v[44:47]
	v_mfma_f32_16x16x32_bf16 v[40:43], v[136:139], v[154:157], v[40:43]
	v_mfma_f32_16x16x32_bf16 v[28:31], v[128:131], v[162:165], v[28:31]
	v_mfma_f32_16x16x32_bf16 v[24:27], v[136:139], v[162:165], v[24:27]
	v_mfma_f32_16x16x32_bf16 v[12:15], v[128:131], v[194:197], v[12:15]
	v_mfma_f32_16x16x32_bf16 v[8:11], v[136:139], v[194:197], v[8:11]
	v_mfma_f32_16x16x32_bf16 v[60:63], v[132:135], v[150:153], v[60:63]
	v_mfma_f32_16x16x32_bf16 v[56:59], v[140:143], v[150:153], v[56:59]
	v_mfma_f32_16x16x32_bf16 v[44:47], v[132:135], v[158:161], v[44:47]
	v_mfma_f32_16x16x32_bf16 v[40:43], v[140:143], v[158:161], v[40:43]
	v_mfma_f32_16x16x32_bf16 v[28:31], v[132:135], v[166:169], v[28:31]
	v_mfma_f32_16x16x32_bf16 v[24:27], v[140:143], v[166:169], v[24:27]
	v_mfma_f32_16x16x32_bf16 v[12:15], v[132:135], v[198:201], v[12:15]
	v_mfma_f32_16x16x32_bf16 v[8:11], v[140:143], v[198:201], v[8:11]
	s_barrier
	s_add_i32 s27, s44, s84
	v_lshl_add_u64 v[128:129], v[238:239], 0, s[18:19]
	s_mov_b32 m0, s27
	s_nop 0
	global_load_lds_dwordx4 v[128:129], off
	v_lshl_add_u64 v[128:129], v[240:241], 0, s[18:19]
	s_add_i32 m0, s27, 0x2000
	s_nop 0
	global_load_lds_dwordx4 v[128:129], off
	s_waitcnt vmcnt(6)
	s_barrier
	v_mfma_f32_16x16x32_bf16 v[52:55], v[202:205], v[146:149], v[52:55]
	v_mfma_f32_16x16x32_bf16 v[48:51], v[222:225], v[146:149], v[48:51]
	v_mfma_f32_16x16x32_bf16 v[36:39], v[202:205], v[154:157], v[36:39]
	v_mfma_f32_16x16x32_bf16 v[32:35], v[222:225], v[154:157], v[32:35]
	v_mfma_f32_16x16x32_bf16 v[20:23], v[202:205], v[162:165], v[20:23]
	v_mfma_f32_16x16x32_bf16 v[16:19], v[222:225], v[162:165], v[16:19]
	v_mfma_f32_16x16x32_bf16 v[4:7], v[202:205], v[194:197], v[4:7]
	v_mfma_f32_16x16x32_bf16 v[0:3], v[222:225], v[194:197], v[0:3]
	v_mfma_f32_16x16x32_bf16 v[52:55], v[218:221], v[150:153], v[52:55]
	v_mfma_f32_16x16x32_bf16 v[48:51], v[228:231], v[150:153], v[48:51]
	v_mfma_f32_16x16x32_bf16 v[36:39], v[218:221], v[158:161], v[36:39]
	v_mfma_f32_16x16x32_bf16 v[32:35], v[228:231], v[158:161], v[32:35]
	v_mfma_f32_16x16x32_bf16 v[20:23], v[218:221], v[166:169], v[20:23]
	v_mfma_f32_16x16x32_bf16 v[16:19], v[228:231], v[166:169], v[16:19]
	v_mfma_f32_16x16x32_bf16 v[4:7], v[218:221], v[198:201], v[4:7]
	v_mfma_f32_16x16x32_bf16 v[0:3], v[228:231], v[198:201], v[0:3]
	s_barrier
	s_add_u32 s42, s42, 0x100
	s_addc_u32 s43, s43, 0
	s_add_u32 s33, s33, 0x100
	s_addc_u32 s37, s37, 0
	s_cmp_ge_u32 s56, s34
	s_mov_b32 s27, s56
	s_cbranch_scc0 .LBB0_196
	v_lshl_add_u32 v194, s11, 8, v206
	v_ashrrev_i32_e32 v195, 31, v194
	v_lshl_or_b32 v196, s10, 8, v216
	v_lshlrev_b64 v[128:129], 11, v[194:195]
	v_ashrrev_i32_e32 v197, 31, v196
	s_and_b64 vcc, exec, s[92:93]
	v_or_b32_e32 v198, 16, v194
	v_lshl_add_u64 v[200:201], s[54:55], 0, v[128:129]
	s_cbranch_vccz .LBB0_215
	v_lshlrev_b64 v[128:129], 12, v[194:195]
	v_lshl_add_u64 v[128:129], s[50:51], 0, v[128:129]
	v_lshlrev_b64 v[130:131], 2, v[196:197]
	v_lshl_add_u64 v[128:129], v[128:129], 0, v[130:131]
	global_load_dwordx4 v[146:149], v[128:129], off offset:16
	global_load_dwordx4 v[150:153], v[128:129], off
	global_load_dwordx4 v[154:157], v[128:129], off offset:528
	global_load_dwordx4 v[158:161], v[128:129], off offset:512
	v_ashrrev_i32_e32 v199, 31, v198
	v_lshlrev_b64 v[128:129], 12, v[198:199]
	v_lshl_add_u64 v[128:129], s[50:51], 0, v[128:129]
	v_lshl_add_u64 v[132:133], v[128:129], 0, v[130:131]
	global_load_dwordx4 v[136:139], v[132:133], off offset:16
	global_load_dwordx4 v[140:143], v[132:133], off
	global_load_dwordx4 v[128:131], v[132:133], off offset:528
	s_nop 0
	global_load_dwordx4 v[132:135], v[132:133], off offset:512
	v_lshl_add_u64 v[166:167], v[196:197], 1, v[200:201]
	s_waitcnt vmcnt(0)
	v_pk_add_f32 v[164:165], v[120:121], v[146:147]
	v_pk_add_f32 v[152:153], v[126:127], v[152:153]
	v_pk_add_f32 v[150:151], v[124:125], v[150:151]
	v_pk_add_f32 v[162:163], v[122:123], v[148:149]
	v_cvt_pk_bf16_f32 v146, v150, v151
	v_cvt_pk_bf16_f32 v147, v152, v153
	v_cvt_pk_bf16_f32 v148, v164, v165
	v_pk_add_f32 v[156:157], v[114:115], v[156:157]
	v_cvt_pk_bf16_f32 v149, v162, v163
	global_store_dwordx4 v[166:167], v[146:149], off
	v_pk_add_f32 v[154:155], v[112:113], v[154:155]
	s_nop 0
	v_mul_f32_e32 v146, v151, v151
	v_mul_f32_e32 v147, v153, v153
	v_fmac_f32_e32 v146, v150, v150
	v_fmac_f32_e32 v147, v152, v152
	v_add_f32_e32 v146, v146, v147
	v_mul_f32_e32 v147, v165, v165
	v_mul_f32_e32 v148, v163, v163
	v_fmac_f32_e32 v147, v164, v164
	v_fmac_f32_e32 v148, v162, v162
	v_add_f32_e32 v147, v147, v148
	v_add_f32_e32 v162, v146, v147
	v_pk_add_f32 v[150:151], v[118:119], v[160:161]
	v_pk_add_f32 v[152:153], v[116:117], v[158:159]
	s_nop 0
	v_cvt_pk_bf16_f32 v146, v152, v153
	v_cvt_pk_bf16_f32 v147, v150, v151
	v_cvt_pk_bf16_f32 v148, v154, v155
	v_cvt_pk_bf16_f32 v149, v156, v157
	global_store_dwordx4 v[166:167], v[146:149], off offset:256
	s_nop 1
	v_mul_f32_e32 v146, v153, v153
	v_mul_f32_e32 v147, v151, v151
	v_fmac_f32_e32 v146, v152, v152
	v_fmac_f32_e32 v147, v150, v150
	v_add_f32_e32 v146, v146, v147
	v_mul_f32_e32 v147, v155, v155
	v_mul_f32_e32 v148, v157, v157
	v_fmac_f32_e32 v147, v154, v154
	v_fmac_f32_e32 v148, v156, v156
	v_add_f32_e32 v147, v147, v148
	v_and_b32_e32 v148, 64, v214
	v_add_f32_e32 v146, v146, v147
	v_xor_b32_e32 v147, 16, v214
	v_add_u32_e32 v148, 64, v148
	v_cmp_lt_i32_e32 vcc, v147, v148
	v_add_f32_e32 v146, v162, v146
	s_nop 0
	v_cndmask_b32_e32 v147, v214, v147, vcc
	v_lshlrev_b32_e32 v218, 2, v147
	ds_bpermute_b32 v147, v218, v146
	s_waitcnt lgkmcnt(0)
	v_add_f32_e32 v146, v146, v147
	v_xor_b32_e32 v147, 32, v214
	v_cmp_lt_i32_e32 vcc, v147, v148
	s_nop 1
	v_cndmask_b32_e32 v147, v214, v147, vcc
	v_lshlrev_b32_e32 v219, 2, v147
	ds_bpermute_b32 v147, v219, v146
	s_and_saveexec_b64 s[42:43], s[38:39]
	s_cbranch_execz .LBB0_200
	s_waitcnt lgkmcnt(0)
	v_add_f32_e32 v146, v146, v147
	v_fma_f32 v146, v146, s91, 0.5
	v_trunc_f32_e32 v146, v146
	v_mul_f32_e32 v147, 0x2f800000, v146
	v_floor_f32_e32 v147, v147
	v_fmac_f32_e32 v146, 0xcf800000, v147
	v_cvt_u32_f32_e32 v146, v146
	v_cvt_u32_f32_e32 v147, v147
	v_lshl_add_u64 v[148:149], v[194:195], 3, s[52:53]
	global_atomic_add_x2 v[148:149], v[146:147], off

.LBB0_325:
	s_ashr_i32 s93, s92, 31
	s_lshl_b64 s[30:31], s[92:93], 19
	s_add_u32 s94, s54, s30
	v_cmp_lt_i64_e32 vcc, s[50:51], v[186:187]
	s_addc_u32 s95, s55, s31
	s_and_b64 s[30:31], vcc, exec
	s_cselect_b32 s1, s95, s53
	s_cselect_b32 s11, s94, s52
	s_ashr_i32 s9, s8, 31
	s_lshl_b64 s[30:31], s[8:9], 19
	s_add_u32 s28, s80, s30
	s_addc_u32 s29, s78, s31
	s_and_b64 s[30:31], vcc, exec
	s_cselect_b32 s25, s29, s73
	s_cselect_b32 s30, s28, s72
	s_add_u32 s52, s52, 0x40080
	s_addc_u32 s53, s53, 0
	s_add_u32 s31, s72, 0x100
	s_addc_u32 s33, s73, 0
	s_mov_b32 s34, -2
	s_add_u32 s27, s52, 0xfffc0080
	s_addc_u32 s35, s53, -1
	s_add_i32 s36, 0, 0x10000
	v_add_u32_e32 v140, s36, v216
	ds_read_b128 v[128:131], v140
	ds_read_b128 v[132:135], v140 offset:1024
	ds_read_b128 v[136:139], v140 offset:2048
	ds_read_b128 v[140:143], v140 offset:3072
	s_cmp_eq_u32 s34, 12
	s_cselect_b32 s75, s1, s35
	s_cselect_b32 s74, s11, s27
	s_cselect_b32 s73, s25, s33
	s_cselect_b32 s72, s30, s31
	s_add_i32 m0, s83, 0xc000
	ds_read_b128 v[156:159], v217
	ds_read_b128 v[160:163], v217 offset:1024
	ds_read_b128 v[164:167], v217 offset:2048
	ds_read_b128 v[188:191], v217 offset:3072
	ds_read_b128 v[192:195], v217 offset:4096
	ds_read_b128 v[196:199], v217 offset:5120
	ds_read_b128 v[200:203], v217 offset:6144
	ds_read_b128 v[204:207], v217 offset:7168
	global_load_lds_dwordx4 v152, s[52:53]
	s_add_i32 m0, s83, 0xe000
	s_nop 0
	global_load_lds_dwordx4 v154, s[52:53]
	s_waitcnt lgkmcnt(8)
	s_barrier
	s_waitcnt lgkmcnt(0)
	v_mfma_f32_16x16x32_bf16 v[124:127], v[128:131], v[156:159], 0
	v_mfma_f32_16x16x32_bf16 v[120:123], v[136:139], v[156:159], 0
	v_mfma_f32_16x16x32_bf16 v[108:111], v[128:131], v[164:167], 0
	v_mfma_f32_16x16x32_bf16 v[104:107], v[136:139], v[164:167], 0
	v_mfma_f32_16x16x32_bf16 v[92:95], v[128:131], v[192:195], 0
	v_mfma_f32_16x16x32_bf16 v[88:91], v[136:139], v[192:195], 0
	v_mfma_f32_16x16x32_bf16 v[76:79], v[128:131], v[200:203], 0
	v_mfma_f32_16x16x32_bf16 v[72:75], v[136:139], v[200:203], 0
	v_mfma_f32_16x16x32_bf16 v[124:127], v[132:135], v[160:163], v[124:127]
	v_mfma_f32_16x16x32_bf16 v[120:123], v[140:143], v[160:163], v[120:123]
	v_mfma_f32_16x16x32_bf16 v[108:111], v[132:135], v[188:191], v[108:111]
	v_mfma_f32_16x16x32_bf16 v[104:107], v[140:143], v[188:191], v[104:107]
	v_mfma_f32_16x16x32_bf16 v[92:95], v[132:135], v[196:199], v[92:95]
	v_mfma_f32_16x16x32_bf16 v[88:91], v[140:143], v[196:199], v[88:91]
	v_mfma_f32_16x16x32_bf16 v[76:79], v[132:135], v[204:207], v[76:79]
	v_mfma_f32_16x16x32_bf16 v[72:75], v[140:143], v[204:207], v[72:75]
	s_barrier
	s_add_i32 s27, 0, 0x14000
	s_add_i32 s35, s36, s81
	v_add_u32_e32 v144, s27, v216
	v_lshl_add_u64 v[168:169], s[72:73], 0, v[148:149]
	s_mov_b32 m0, s35
	ds_read_b128 v[220:223], v144
	ds_read_b128 v[228:231], v144 offset:1024
	ds_read_b128 v[232:235], v144 offset:2048
	ds_read_b128 v[236:239], v144 offset:3072
	global_load_lds_dwordx4 v[168:169], off
	v_lshl_add_u64 v[176:177], s[72:73], 0, v[146:147]
	s_add_i32 m0, s35, 0x2000
	s_nop 0
	global_load_lds_dwordx4 v[176:177], off
	s_barrier
	s_waitcnt lgkmcnt(0)
	v_mfma_f32_16x16x32_bf16 v[116:119], v[220:223], v[156:159], 0
	v_mfma_f32_16x16x32_bf16 v[112:115], v[232:235], v[156:159], 0
	v_mfma_f32_16x16x32_bf16 v[100:103], v[220:223], v[164:167], 0
	v_mfma_f32_16x16x32_bf16 v[96:99], v[232:235], v[164:167], 0
	v_mfma_f32_16x16x32_bf16 v[84:87], v[220:223], v[192:195], 0
	v_mfma_f32_16x16x32_bf16 v[80:83], v[232:235], v[192:195], 0
	v_mfma_f32_16x16x32_bf16 v[68:71], v[220:223], v[200:203], 0
	v_mfma_f32_16x16x32_bf16 v[64:67], v[232:235], v[200:203], 0
	v_mfma_f32_16x16x32_bf16 v[116:119], v[228:231], v[160:163], v[116:119]
	v_mfma_f32_16x16x32_bf16 v[112:115], v[236:239], v[160:163], v[112:115]
	v_mfma_f32_16x16x32_bf16 v[100:103], v[228:231], v[188:191], v[100:103]
	v_mfma_f32_16x16x32_bf16 v[96:99], v[236:239], v[188:191], v[96:99]
	v_mfma_f32_16x16x32_bf16 v[84:87], v[228:231], v[196:199], v[84:87]
	v_mfma_f32_16x16x32_bf16 v[80:83], v[236:239], v[196:199], v[80:83]
	v_mfma_f32_16x16x32_bf16 v[68:71], v[228:231], v[204:207], v[68:71]
	v_mfma_f32_16x16x32_bf16 v[64:67], v[236:239], v[204:207], v[64:67]
	s_barrier
	s_mov_b32 m0, s83
	v_lshl_add_u64 v[224:225], s[74:75], 0, v[148:149]
	ds_read_b128 v[156:159], v217 offset:16384
	ds_read_b128 v[160:163], v217 offset:17408
	ds_read_b128 v[164:167], v217 offset:18432
	ds_read_b128 v[188:191], v217 offset:19456
	ds_read_b128 v[192:195], v217 offset:20480
	ds_read_b128 v[196:199], v217 offset:21504
	ds_read_b128 v[200:203], v217 offset:22528
	ds_read_b128 v[204:207], v217 offset:23552
	global_load_lds_dwordx4 v[224:225], off
	v_lshl_add_u64 v[240:241], s[74:75], 0, v[146:147]
	s_mov_b32 m0, s84
	s_nop 0
	global_load_lds_dwordx4 v[240:241], off
	s_barrier
	s_waitcnt lgkmcnt(0)
	v_mfma_f32_16x16x32_bf16 v[60:63], v[128:131], v[156:159], 0
	v_mfma_f32_16x16x32_bf16 v[56:59], v[136:139], v[156:159], 0
	v_mfma_f32_16x16x32_bf16 v[44:47], v[128:131], v[164:167], 0
	v_mfma_f32_16x16x32_bf16 v[40:43], v[136:139], v[164:167], 0
	v_mfma_f32_16x16x32_bf16 v[28:31], v[128:131], v[192:195], 0
	v_mfma_f32_16x16x32_bf16 v[24:27], v[136:139], v[192:195], 0
	v_mfma_f32_16x16x32_bf16 v[12:15], v[128:131], v[200:203], 0
	v_mfma_f32_16x16x32_bf16 v[8:11], v[136:139], v[200:203], 0
	v_mfma_f32_16x16x32_bf16 v[60:63], v[132:135], v[160:163], v[60:63]
	v_mfma_f32_16x16x32_bf16 v[56:59], v[140:143], v[160:163], v[56:59]
	v_mfma_f32_16x16x32_bf16 v[44:47], v[132:135], v[188:191], v[44:47]
	v_mfma_f32_16x16x32_bf16 v[40:43], v[140:143], v[188:191], v[40:43]
	v_mfma_f32_16x16x32_bf16 v[28:31], v[132:135], v[196:199], v[28:31]
	v_mfma_f32_16x16x32_bf16 v[24:27], v[140:143], v[196:199], v[24:27]
	v_mfma_f32_16x16x32_bf16 v[12:15], v[132:135], v[204:207], v[12:15]
	v_mfma_f32_16x16x32_bf16 v[8:11], v[140:143], v[204:207], v[8:11]
	s_barrier
	s_add_u32 s36, s72, 0x40000
	s_addc_u32 s37, s73, 0
	s_add_i32 s27, s27, s81
	s_mov_b32 m0, s27
	s_nop 0
	global_load_lds_dwordx4 v148, s[36:37]
	s_add_i32 m0, s27, 0x2000
	s_nop 0
	global_load_lds_dwordx4 v146, s[36:37]
	s_waitcnt vmcnt(6)
	s_barrier
	v_mfma_f32_16x16x32_bf16 v[52:55], v[220:223], v[156:159], 0
	v_mfma_f32_16x16x32_bf16 v[48:51], v[232:235], v[156:159], 0
	v_mfma_f32_16x16x32_bf16 v[36:39], v[220:223], v[164:167], 0
	v_mfma_f32_16x16x32_bf16 v[32:35], v[232:235], v[164:167], 0
	v_mfma_f32_16x16x32_bf16 v[20:23], v[220:223], v[192:195], 0
	v_mfma_f32_16x16x32_bf16 v[16:19], v[232:235], v[192:195], 0
	v_mfma_f32_16x16x32_bf16 v[4:7], v[220:223], v[200:203], 0
	v_mfma_f32_16x16x32_bf16 v[0:3], v[232:235], v[200:203], 0
	v_mfma_f32_16x16x32_bf16 v[52:55], v[228:231], v[160:163], v[52:55]
	v_mfma_f32_16x16x32_bf16 v[48:51], v[236:239], v[160:163], v[48:51]
	v_mfma_f32_16x16x32_bf16 v[36:39], v[228:231], v[188:191], v[36:39]
	v_mfma_f32_16x16x32_bf16 v[32:35], v[236:239], v[188:191], v[32:35]
	v_mfma_f32_16x16x32_bf16 v[20:23], v[228:231], v[196:199], v[20:23]
	v_mfma_f32_16x16x32_bf16 v[16:19], v[236:239], v[196:199], v[16:19]
	v_mfma_f32_16x16x32_bf16 v[4:7], v[228:231], v[204:207], v[4:7]
	v_mfma_f32_16x16x32_bf16 v[0:3], v[236:239], v[204:207], v[0:3]
	s_barrier
	s_add_i32 s27, 0, 0x18000
	v_add_u32_e32 v140, s27, v216
	ds_read_b128 v[128:131], v140
	ds_read_b128 v[132:135], v140 offset:1024
	ds_read_b128 v[136:139], v140 offset:2048
	ds_read_b128 v[140:143], v140 offset:3072
	s_add_u32 s36, s74, 0x40000
	s_addc_u32 s37, s75, 0
	s_mov_b32 m0, s85
	ds_read_b128 v[156:159], v217 offset:32768
	ds_read_b128 v[160:163], v217 offset:33792
	ds_read_b128 v[164:167], v217 offset:34816
	ds_read_b128 v[188:191], v217 offset:35840
	ds_read_b128 v[192:195], v217 offset:36864
	ds_read_b128 v[196:199], v217 offset:37888
	ds_read_b128 v[200:203], v217 offset:38912
	ds_read_b128 v[204:207], v217 offset:39936
	global_load_lds_dwordx4 v148, s[36:37]
	s_mov_b32 m0, s86
	s_nop 0
	global_load_lds_dwordx4 v146, s[36:37]
	s_waitcnt lgkmcnt(8)
	s_barrier
	s_waitcnt lgkmcnt(0)
	v_mfma_f32_16x16x32_bf16 v[124:127], v[128:131], v[156:159], v[124:127]
	v_mfma_f32_16x16x32_bf16 v[120:123], v[136:139], v[156:159], v[120:123]
	v_mfma_f32_16x16x32_bf16 v[108:111], v[128:131], v[164:167], v[108:111]
	v_mfma_f32_16x16x32_bf16 v[104:107], v[136:139], v[164:167], v[104:107]
	v_mfma_f32_16x16x32_bf16 v[92:95], v[128:131], v[192:195], v[92:95]
	v_mfma_f32_16x16x32_bf16 v[88:91], v[136:139], v[192:195], v[88:91]
	v_mfma_f32_16x16x32_bf16 v[76:79], v[128:131], v[200:203], v[76:79]
	v_mfma_f32_16x16x32_bf16 v[72:75], v[136:139], v[200:203], v[72:75]
	v_mfma_f32_16x16x32_bf16 v[124:127], v[132:135], v[160:163], v[124:127]
	v_mfma_f32_16x16x32_bf16 v[120:123], v[140:143], v[160:163], v[120:123]
	v_mfma_f32_16x16x32_bf16 v[108:111], v[132:135], v[188:191], v[108:111]
	v_mfma_f32_16x16x32_bf16 v[104:107], v[140:143], v[188:191], v[104:107]
	v_mfma_f32_16x16x32_bf16 v[92:95], v[132:135], v[196:199], v[92:95]
	v_mfma_f32_16x16x32_bf16 v[88:91], v[140:143], v[196:199], v[88:91]
	v_mfma_f32_16x16x32_bf16 v[76:79], v[132:135], v[204:207], v[76:79]
	v_mfma_f32_16x16x32_bf16 v[72:75], v[140:143], v[204:207], v[72:75]
	s_barrier
	s_add_i32 s35, 0, 0x1c000
	s_add_i32 s27, s27, s81
	v_add_u32_e32 v144, s35, v216
	v_lshl_add_u64 v[168:169], v[168:169], 0, s[18:19]
	s_mov_b32 m0, s27
	ds_read_b128 v[220:223], v144
	ds_read_b128 v[228:231], v144 offset:1024
	ds_read_b128 v[232:235], v144 offset:2048
	ds_read_b128 v[236:239], v144 offset:3072
	global_load_lds_dwordx4 v[168:169], off
	v_lshl_add_u64 v[168:169], v[176:177], 0, s[18:19]
	s_add_i32 m0, s27, 0x2000
	s_nop 0
	global_load_lds_dwordx4 v[168:169], off
	s_barrier
	s_waitcnt lgkmcnt(0)
	v_mfma_f32_16x16x32_bf16 v[116:119], v[220:223], v[156:159], v[116:119]
	v_mfma_f32_16x16x32_bf16 v[112:115], v[232:235], v[156:159], v[112:115]
	v_mfma_f32_16x16x32_bf16 v[100:103], v[220:223], v[164:167], v[100:103]
	v_mfma_f32_16x16x32_bf16 v[96:99], v[232:235], v[164:167], v[96:99]
	v_mfma_f32_16x16x32_bf16 v[84:87], v[220:223], v[192:195], v[84:87]
	v_mfma_f32_16x16x32_bf16 v[80:83], v[232:235], v[192:195], v[80:83]
	v_mfma_f32_16x16x32_bf16 v[68:71], v[220:223], v[200:203], v[68:71]
	v_mfma_f32_16x16x32_bf16 v[64:67], v[232:235], v[200:203], v[64:67]
	v_mfma_f32_16x16x32_bf16 v[116:119], v[228:231], v[160:163], v[116:119]
	v_mfma_f32_16x16x32_bf16 v[112:115], v[236:239], v[160:163], v[112:115]
	v_mfma_f32_16x16x32_bf16 v[100:103], v[228:231], v[188:191], v[100:103]
	v_mfma_f32_16x16x32_bf16 v[96:99], v[236:239], v[188:191], v[96:99]
	v_mfma_f32_16x16x32_bf16 v[84:87], v[228:231], v[196:199], v[84:87]
	v_mfma_f32_16x16x32_bf16 v[80:83], v[236:239], v[196:199], v[80:83]
	v_mfma_f32_16x16x32_bf16 v[68:71], v[228:231], v[204:207], v[68:71]
	v_mfma_f32_16x16x32_bf16 v[64:67], v[236:239], v[204:207], v[64:67]
	s_barrier
	s_mov_b32 m0, s87
	v_lshl_add_u64 v[168:169], v[224:225], 0, s[18:19]
	ds_read_b128 v[156:159], v217 offset:49152
	ds_read_b128 v[160:163], v217 offset:50176
	ds_read_b128 v[164:167], v217 offset:51200
	ds_read_b128 v[188:191], v217 offset:52224
	ds_read_b128 v[192:195], v217 offset:53248
	ds_read_b128 v[196:199], v217 offset:54272
	ds_read_b128 v[200:203], v217 offset:55296
	ds_read_b128 v[204:207], v217 offset:56320
	global_load_lds_dwordx4 v[168:169], off
	v_lshl_add_u64 v[168:169], v[240:241], 0, s[18:19]
	s_mov_b32 m0, s79
	s_nop 0
	global_load_lds_dwordx4 v[168:169], off
	s_barrier
	s_waitcnt lgkmcnt(0)
	v_mfma_f32_16x16x32_bf16 v[60:63], v[128:131], v[156:159], v[60:63]
	v_mfma_f32_16x16x32_bf16 v[56:59], v[136:139], v[156:159], v[56:59]
	v_mfma_f32_16x16x32_bf16 v[44:47], v[128:131], v[164:167], v[44:47]
	v_mfma_f32_16x16x32_bf16 v[40:43], v[136:139], v[164:167], v[40:43]
	v_mfma_f32_16x16x32_bf16 v[28:31], v[128:131], v[192:195], v[28:31]
	v_mfma_f32_16x16x32_bf16 v[24:27], v[136:139], v[192:195], v[24:27]
	v_mfma_f32_16x16x32_bf16 v[12:15], v[128:131], v[200:203], v[12:15]
	v_mfma_f32_16x16x32_bf16 v[8:11], v[136:139], v[200:203], v[8:11]
	v_mfma_f32_16x16x32_bf16 v[60:63], v[132:135], v[160:163], v[60:63]
	v_mfma_f32_16x16x32_bf16 v[56:59], v[140:143], v[160:163], v[56:59]
	v_mfma_f32_16x16x32_bf16 v[44:47], v[132:135], v[188:191], v[44:47]
	v_mfma_f32_16x16x32_bf16 v[40:43], v[140:143], v[188:191], v[40:43]
	v_mfma_f32_16x16x32_bf16 v[28:31], v[132:135], v[196:199], v[28:31]
	v_mfma_f32_16x16x32_bf16 v[24:27], v[140:143], v[196:199], v[24:27]
	v_mfma_f32_16x16x32_bf16 v[12:15], v[132:135], v[204:207], v[12:15]
	v_mfma_f32_16x16x32_bf16 v[8:11], v[140:143], v[204:207], v[8:11]
	s_barrier
	s_add_u32 s36, s72, 0x40080
	s_addc_u32 s37, s73, 0
	s_add_i32 s27, s35, s81
	s_mov_b32 m0, s27
	s_nop 0
	global_load_lds_dwordx4 v148, s[36:37]
	s_add_i32 m0, s27, 0x2000
	s_nop 0
	global_load_lds_dwordx4 v146, s[36:37]
	s_waitcnt vmcnt(6)
	s_barrier
	v_mfma_f32_16x16x32_bf16 v[52:55], v[220:223], v[156:159], v[52:55]
	v_mfma_f32_16x16x32_bf16 v[48:51], v[232:235], v[156:159], v[48:51]
	v_mfma_f32_16x16x32_bf16 v[36:39], v[220:223], v[164:167], v[36:39]
	v_mfma_f32_16x16x32_bf16 v[32:35], v[232:235], v[164:167], v[32:35]
	v_mfma_f32_16x16x32_bf16 v[20:23], v[220:223], v[192:195], v[20:23]
	v_mfma_f32_16x16x32_bf16 v[16:19], v[232:235], v[192:195], v[16:19]
	v_mfma_f32_16x16x32_bf16 v[4:7], v[220:223], v[200:203], v[4:7]
	v_mfma_f32_16x16x32_bf16 v[0:3], v[232:235], v[200:203], v[0:3]
	v_mfma_f32_16x16x32_bf16 v[52:55], v[228:231], v[160:163], v[52:55]
	v_mfma_f32_16x16x32_bf16 v[48:51], v[236:239], v[160:163], v[48:51]
	v_mfma_f32_16x16x32_bf16 v[36:39], v[228:231], v[188:191], v[36:39]
	v_mfma_f32_16x16x32_bf16 v[32:35], v[236:239], v[188:191], v[32:35]
	v_mfma_f32_16x16x32_bf16 v[20:23], v[228:231], v[196:199], v[20:23]
	v_mfma_f32_16x16x32_bf16 v[16:19], v[236:239], v[196:199], v[16:19]
	v_mfma_f32_16x16x32_bf16 v[4:7], v[228:231], v[204:207], v[4:7]
	v_mfma_f32_16x16x32_bf16 v[0:3], v[236:239], v[204:207], v[0:3]
	s_barrier
	s_add_i32 s34, s34, 2
	s_add_u32 s52, s52, 0x100
	s_addc_u32 s53, s53, 0
	s_add_u32 s31, s31, 0x100
	s_addc_u32 s33, s33, 0
	s_cmp_gt_u32 s34, 13
.LBB0_326:
	s_add_u32 s27, s52, 0xfffc0080
	s_addc_u32 s35, s53, -1
	s_add_i32 s36, 0, 0x10000
	v_add_u32_e32 v140, s36, v216
	ds_read_b128 v[128:131], v140
	ds_read_b128 v[132:135], v140 offset:1024
	ds_read_b128 v[136:139], v140 offset:2048
	ds_read_b128 v[140:143], v140 offset:3072
	s_cmp_eq_u32 s34, 12
	s_cselect_b32 s75, s1, s35
	s_cselect_b32 s74, s11, s27
	s_cselect_b32 s73, s25, s33
	s_cselect_b32 s72, s30, s31
	s_add_i32 m0, s83, 0xc000
	ds_read_b128 v[156:159], v217
	ds_read_b128 v[160:163], v217 offset:1024
	ds_read_b128 v[164:167], v217 offset:2048
	ds_read_b128 v[188:191], v217 offset:3072
	ds_read_b128 v[192:195], v217 offset:4096
	ds_read_b128 v[196:199], v217 offset:5120
	ds_read_b128 v[200:203], v217 offset:6144
	ds_read_b128 v[204:207], v217 offset:7168
	global_load_lds_dwordx4 v152, s[52:53]
	s_add_i32 m0, s83, 0xe000
	s_nop 0
	global_load_lds_dwordx4 v154, s[52:53]
	s_waitcnt lgkmcnt(8)
	s_barrier
	s_waitcnt lgkmcnt(0)
	v_mfma_f32_16x16x32_bf16 v[124:127], v[128:131], v[156:159], v[124:127]
	v_mfma_f32_16x16x32_bf16 v[120:123], v[136:139], v[156:159], v[120:123]
	v_mfma_f32_16x16x32_bf16 v[108:111], v[128:131], v[164:167], v[108:111]
	v_mfma_f32_16x16x32_bf16 v[104:107], v[136:139], v[164:167], v[104:107]
	v_mfma_f32_16x16x32_bf16 v[92:95], v[128:131], v[192:195], v[92:95]
	v_mfma_f32_16x16x32_bf16 v[88:91], v[136:139], v[192:195], v[88:91]
	v_mfma_f32_16x16x32_bf16 v[76:79], v[128:131], v[200:203], v[76:79]
	v_mfma_f32_16x16x32_bf16 v[72:75], v[136:139], v[200:203], v[72:75]
	v_mfma_f32_16x16x32_bf16 v[124:127], v[132:135], v[160:163], v[124:127]
	v_mfma_f32_16x16x32_bf16 v[120:123], v[140:143], v[160:163], v[120:123]
	v_mfma_f32_16x16x32_bf16 v[108:111], v[132:135], v[188:191], v[108:111]
	v_mfma_f32_16x16x32_bf16 v[104:107], v[140:143], v[188:191], v[104:107]
	v_mfma_f32_16x16x32_bf16 v[92:95], v[132:135], v[196:199], v[92:95]
	v_mfma_f32_16x16x32_bf16 v[88:91], v[140:143], v[196:199], v[88:91]
	v_mfma_f32_16x16x32_bf16 v[76:79], v[132:135], v[204:207], v[76:79]
	v_mfma_f32_16x16x32_bf16 v[72:75], v[140:143], v[204:207], v[72:75]
	s_barrier
	s_add_i32 s27, 0, 0x14000
	s_add_i32 s35, s36, s81
	v_add_u32_e32 v144, s27, v216
	v_lshl_add_u64 v[168:169], s[72:73], 0, v[148:149]
	s_mov_b32 m0, s35
	ds_read_b128 v[220:223], v144
	ds_read_b128 v[228:231], v144 offset:1024
	ds_read_b128 v[232:235], v144 offset:2048
	ds_read_b128 v[236:239], v144 offset:3072
	global_load_lds_dwordx4 v[168:169], off
	v_lshl_add_u64 v[176:177], s[72:73], 0, v[146:147]
	s_add_i32 m0, s35, 0x2000
	s_nop 0
	global_load_lds_dwordx4 v[176:177], off
	s_barrier
	s_waitcnt lgkmcnt(0)
	v_mfma_f32_16x16x32_bf16 v[116:119], v[220:223], v[156:159], v[116:119]
	v_mfma_f32_16x16x32_bf16 v[112:115], v[232:235], v[156:159], v[112:115]
	v_mfma_f32_16x16x32_bf16 v[100:103], v[220:223], v[164:167], v[100:103]
	v_mfma_f32_16x16x32_bf16 v[96:99], v[232:235], v[164:167], v[96:99]
	v_mfma_f32_16x16x32_bf16 v[84:87], v[220:223], v[192:195], v[84:87]
	v_mfma_f32_16x16x32_bf16 v[80:83], v[232:235], v[192:195], v[80:83]
	v_mfma_f32_16x16x32_bf16 v[68:71], v[220:223], v[200:203], v[68:71]
	v_mfma_f32_16x16x32_bf16 v[64:67], v[232:235], v[200:203], v[64:67]
	v_mfma_f32_16x16x32_bf16 v[116:119], v[228:231], v[160:163], v[116:119]
	v_mfma_f32_16x16x32_bf16 v[112:115], v[236:239], v[160:163], v[112:115]
	v_mfma_f32_16x16x32_bf16 v[100:103], v[228:231], v[188:191], v[100:103]
	v_mfma_f32_16x16x32_bf16 v[96:99], v[236:239], v[188:191], v[96:99]
	v_mfma_f32_16x16x32_bf16 v[84:87], v[228:231], v[196:199], v[84:87]
	v_mfma_f32_16x16x32_bf16 v[80:83], v[236:239], v[196:199], v[80:83]
	v_mfma_f32_16x16x32_bf16 v[68:71], v[228:231], v[204:207], v[68:71]
	v_mfma_f32_16x16x32_bf16 v[64:67], v[236:239], v[204:207], v[64:67]
	s_barrier
	s_mov_b32 m0, s83
	v_lshl_add_u64 v[224:225], s[74:75], 0, v[148:149]
	ds_read_b128 v[156:159], v217 offset:16384
	ds_read_b128 v[160:163], v217 offset:17408
	ds_read_b128 v[164:167], v217 offset:18432
	ds_read_b128 v[188:191], v217 offset:19456
	ds_read_b128 v[192:195], v217 offset:20480
	ds_read_b128 v[196:199], v217 offset:21504
	ds_read_b128 v[200:203], v217 offset:22528
	ds_read_b128 v[204:207], v217 offset:23552
	global_load_lds_dwordx4 v[224:225], off
	v_lshl_add_u64 v[240:241], s[74:75], 0, v[146:147]
	s_mov_b32 m0, s84
	s_nop 0
	global_load_lds_dwordx4 v[240:241], off
	s_barrier
	s_waitcnt lgkmcnt(0)
	v_mfma_f32_16x16x32_bf16 v[60:63], v[128:131], v[156:159], v[60:63]
	v_mfma_f32_16x16x32_bf16 v[56:59], v[136:139], v[156:159], v[56:59]
	v_mfma_f32_16x16x32_bf16 v[44:47], v[128:131], v[164:167], v[44:47]
	v_mfma_f32_16x16x32_bf16 v[40:43], v[136:139], v[164:167], v[40:43]
	v_mfma_f32_16x16x32_bf16 v[28:31], v[128:131], v[192:195], v[28:31]
	v_mfma_f32_16x16x32_bf16 v[24:27], v[136:139], v[192:195], v[24:27]
	v_mfma_f32_16x16x32_bf16 v[12:15], v[128:131], v[200:203], v[12:15]
	v_mfma_f32_16x16x32_bf16 v[8:11], v[136:139], v[200:203], v[8:11]
	v_mfma_f32_16x16x32_bf16 v[60:63], v[132:135], v[160:163], v[60:63]
	v_mfma_f32_16x16x32_bf16 v[56:59], v[140:143], v[160:163], v[56:59]
	v_mfma_f32_16x16x32_bf16 v[44:47], v[132:135], v[188:191], v[44:47]
	v_mfma_f32_16x16x32_bf16 v[40:43], v[140:143], v[188:191], v[40:43]
	v_mfma_f32_16x16x32_bf16 v[28:31], v[132:135], v[196:199], v[28:31]
	v_mfma_f32_16x16x32_bf16 v[24:27], v[140:143], v[196:199], v[24:27]
	v_mfma_f32_16x16x32_bf16 v[12:15], v[132:135], v[204:207], v[12:15]
	v_mfma_f32_16x16x32_bf16 v[8:11], v[140:143], v[204:207], v[8:11]
	s_barrier
	s_add_u32 s36, s72, 0x40000
	s_addc_u32 s37, s73, 0
	s_add_i32 s27, s27, s81
	s_mov_b32 m0, s27
	s_nop 0
	global_load_lds_dwordx4 v148, s[36:37]
	s_add_i32 m0, s27, 0x2000
	s_nop 0
	global_load_lds_dwordx4 v146, s[36:37]
	s_waitcnt vmcnt(6)
	s_barrier
	v_mfma_f32_16x16x32_bf16 v[52:55], v[220:223], v[156:159], v[52:55]
	v_mfma_f32_16x16x32_bf16 v[48:51], v[232:235], v[156:159], v[48:51]
	v_mfma_f32_16x16x32_bf16 v[36:39], v[220:223], v[164:167], v[36:39]
	v_mfma_f32_16x16x32_bf16 v[32:35], v[232:235], v[164:167], v[32:35]
	v_mfma_f32_16x16x32_bf16 v[20:23], v[220:223], v[192:195], v[20:23]
	v_mfma_f32_16x16x32_bf16 v[16:19], v[232:235], v[192:195], v[16:19]
	v_mfma_f32_16x16x32_bf16 v[4:7], v[220:223], v[200:203], v[4:7]
	v_mfma_f32_16x16x32_bf16 v[0:3], v[232:235], v[200:203], v[0:3]
	v_mfma_f32_16x16x32_bf16 v[52:55], v[228:231], v[160:163], v[52:55]
	v_mfma_f32_16x16x32_bf16 v[48:51], v[236:239], v[160:163], v[48:51]
	v_mfma_f32_16x16x32_bf16 v[36:39], v[228:231], v[188:191], v[36:39]
	v_mfma_f32_16x16x32_bf16 v[32:35], v[236:239], v[188:191], v[32:35]
	v_mfma_f32_16x16x32_bf16 v[20:23], v[228:231], v[196:199], v[20:23]
	v_mfma_f32_16x16x32_bf16 v[16:19], v[236:239], v[196:199], v[16:19]
	v_mfma_f32_16x16x32_bf16 v[4:7], v[228:231], v[204:207], v[4:7]
	v_mfma_f32_16x16x32_bf16 v[0:3], v[236:239], v[204:207], v[0:3]
	s_barrier
	s_add_i32 s27, 0, 0x18000
	v_add_u32_e32 v140, s27, v216
	ds_read_b128 v[128:131], v140
	ds_read_b128 v[132:135], v140 offset:1024
	ds_read_b128 v[136:139], v140 offset:2048
	ds_read_b128 v[140:143], v140 offset:3072
	s_add_u32 s36, s74, 0x40000
	s_addc_u32 s37, s75, 0
	s_mov_b32 m0, s85
	ds_read_b128 v[156:159], v217 offset:32768
	ds_read_b128 v[160:163], v217 offset:33792
	ds_read_b128 v[164:167], v217 offset:34816
	ds_read_b128 v[188:191], v217 offset:35840
	ds_read_b128 v[192:195], v217 offset:36864
	ds_read_b128 v[196:199], v217 offset:37888
	ds_read_b128 v[200:203], v217 offset:38912
	ds_read_b128 v[204:207], v217 offset:39936
	global_load_lds_dwordx4 v148, s[36:37]
	s_mov_b32 m0, s86
	s_nop 0
	global_load_lds_dwordx4 v146, s[36:37]
	s_waitcnt lgkmcnt(8)
	s_barrier
	s_waitcnt lgkmcnt(0)
	v_mfma_f32_16x16x32_bf16 v[124:127], v[128:131], v[156:159], v[124:127]
	v_mfma_f32_16x16x32_bf16 v[120:123], v[136:139], v[156:159], v[120:123]
	v_mfma_f32_16x16x32_bf16 v[108:111], v[128:131], v[164:167], v[108:111]
	v_mfma_f32_16x16x32_bf16 v[104:107], v[136:139], v[164:167], v[104:107]
	v_mfma_f32_16x16x32_bf16 v[92:95], v[128:131], v[192:195], v[92:95]
	v_mfma_f32_16x16x32_bf16 v[88:91], v[136:139], v[192:195], v[88:91]
	v_mfma_f32_16x16x32_bf16 v[76:79], v[128:131], v[200:203], v[76:79]
	v_mfma_f32_16x16x32_bf16 v[72:75], v[136:139], v[200:203], v[72:75]
	v_mfma_f32_16x16x32_bf16 v[124:127], v[132:135], v[160:163], v[124:127]
	v_mfma_f32_16x16x32_bf16 v[120:123], v[140:143], v[160:163], v[120:123]
	v_mfma_f32_16x16x32_bf16 v[108:111], v[132:135], v[188:191], v[108:111]
	v_mfma_f32_16x16x32_bf16 v[104:107], v[140:143], v[188:191], v[104:107]
	v_mfma_f32_16x16x32_bf16 v[92:95], v[132:135], v[196:199], v[92:95]
	v_mfma_f32_16x16x32_bf16 v[88:91], v[140:143], v[196:199], v[88:91]
	v_mfma_f32_16x16x32_bf16 v[76:79], v[132:135], v[204:207], v[76:79]
	v_mfma_f32_16x16x32_bf16 v[72:75], v[140:143], v[204:207], v[72:75]
	s_barrier
	s_add_i32 s35, 0, 0x1c000
	s_add_i32 s27, s27, s81
	v_add_u32_e32 v144, s35, v216
	v_lshl_add_u64 v[168:169], v[168:169], 0, s[18:19]
	s_mov_b32 m0, s27
	ds_read_b128 v[220:223], v144
	ds_read_b128 v[228:231], v144 offset:1024
	ds_read_b128 v[232:235], v144 offset:2048
	ds_read_b128 v[236:239], v144 offset:3072
	global_load_lds_dwordx4 v[168:169], off
	v_lshl_add_u64 v[168:169], v[176:177], 0, s[18:19]
	s_add_i32 m0, s27, 0x2000
	s_nop 0
	global_load_lds_dwordx4 v[168:169], off
	s_barrier
	s_waitcnt lgkmcnt(0)
	v_mfma_f32_16x16x32_bf16 v[116:119], v[220:223], v[156:159], v[116:119]
	v_mfma_f32_16x16x32_bf16 v[112:115], v[232:235], v[156:159], v[112:115]
	v_mfma_f32_16x16x32_bf16 v[100:103], v[220:223], v[164:167], v[100:103]
	v_mfma_f32_16x16x32_bf16 v[96:99], v[232:235], v[164:167], v[96:99]
	v_mfma_f32_16x16x32_bf16 v[84:87], v[220:223], v[192:195], v[84:87]
	v_mfma_f32_16x16x32_bf16 v[80:83], v[232:235], v[192:195], v[80:83]
	v_mfma_f32_16x16x32_bf16 v[68:71], v[220:223], v[200:203], v[68:71]
	v_mfma_f32_16x16x32_bf16 v[64:67], v[232:235], v[200:203], v[64:67]
	v_mfma_f32_16x16x32_bf16 v[116:119], v[228:231], v[160:163], v[116:119]
	v_mfma_f32_16x16x32_bf16 v[112:115], v[236:239], v[160:163], v[112:115]
	v_mfma_f32_16x16x32_bf16 v[100:103], v[228:231], v[188:191], v[100:103]
	v_mfma_f32_16x16x32_bf16 v[96:99], v[236:239], v[188:191], v[96:99]
	v_mfma_f32_16x16x32_bf16 v[84:87], v[228:231], v[196:199], v[84:87]
	v_mfma_f32_16x16x32_bf16 v[80:83], v[236:239], v[196:199], v[80:83]
	v_mfma_f32_16x16x32_bf16 v[68:71], v[228:231], v[204:207], v[68:71]
	v_mfma_f32_16x16x32_bf16 v[64:67], v[236:239], v[204:207], v[64:67]
	s_barrier
	s_mov_b32 m0, s87
	v_lshl_add_u64 v[168:169], v[224:225], 0, s[18:19]
	ds_read_b128 v[156:159], v217 offset:49152
	ds_read_b128 v[160:163], v217 offset:50176
	ds_read_b128 v[164:167], v217 offset:51200
	ds_read_b128 v[188:191], v217 offset:52224
	ds_read_b128 v[192:195], v217 offset:53248
	ds_read_b128 v[196:199], v217 offset:54272
	ds_read_b128 v[200:203], v217 offset:55296
	ds_read_b128 v[204:207], v217 offset:56320
	global_load_lds_dwordx4 v[168:169], off
	v_lshl_add_u64 v[168:169], v[240:241], 0, s[18:19]
	s_mov_b32 m0, s79
	s_nop 0
	global_load_lds_dwordx4 v[168:169], off
	s_barrier
	s_waitcnt lgkmcnt(0)
	v_mfma_f32_16x16x32_bf16 v[60:63], v[128:131], v[156:159], v[60:63]
	v_mfma_f32_16x16x32_bf16 v[56:59], v[136:139], v[156:159], v[56:59]
	v_mfma_f32_16x16x32_bf16 v[44:47], v[128:131], v[164:167], v[44:47]
	v_mfma_f32_16x16x32_bf16 v[40:43], v[136:139], v[164:167], v[40:43]
	v_mfma_f32_16x16x32_bf16 v[28:31], v[128:131], v[192:195], v[28:31]
	v_mfma_f32_16x16x32_bf16 v[24:27], v[136:139], v[192:195], v[24:27]
	v_mfma_f32_16x16x32_bf16 v[12:15], v[128:131], v[200:203], v[12:15]
	v_mfma_f32_16x16x32_bf16 v[8:11], v[136:139], v[200:203], v[8:11]
	v_mfma_f32_16x16x32_bf16 v[60:63], v[132:135], v[160:163], v[60:63]
	v_mfma_f32_16x16x32_bf16 v[56:59], v[140:143], v[160:163], v[56:59]
	v_mfma_f32_16x16x32_bf16 v[44:47], v[132:135], v[188:191], v[44:47]
	v_mfma_f32_16x16x32_bf16 v[40:43], v[140:143], v[188:191], v[40:43]
	v_mfma_f32_16x16x32_bf16 v[28:31], v[132:135], v[196:199], v[28:31]
	v_mfma_f32_16x16x32_bf16 v[24:27], v[140:143], v[196:199], v[24:27]
	v_mfma_f32_16x16x32_bf16 v[12:15], v[132:135], v[204:207], v[12:15]
	v_mfma_f32_16x16x32_bf16 v[8:11], v[140:143], v[204:207], v[8:11]
	s_barrier
	s_add_u32 s36, s72, 0x40080
	s_addc_u32 s37, s73, 0
	s_add_i32 s27, s35, s81
	s_mov_b32 m0, s27
	s_nop 0
	global_load_lds_dwordx4 v148, s[36:37]
	s_add_i32 m0, s27, 0x2000
	s_nop 0
	global_load_lds_dwordx4 v146, s[36:37]
	s_waitcnt vmcnt(6)
	s_barrier
	v_mfma_f32_16x16x32_bf16 v[52:55], v[220:223], v[156:159], v[52:55]
	v_mfma_f32_16x16x32_bf16 v[48:51], v[232:235], v[156:159], v[48:51]
	v_mfma_f32_16x16x32_bf16 v[36:39], v[220:223], v[164:167], v[36:39]
	v_mfma_f32_16x16x32_bf16 v[32:35], v[232:235], v[164:167], v[32:35]
	v_mfma_f32_16x16x32_bf16 v[20:23], v[220:223], v[192:195], v[20:23]
	v_mfma_f32_16x16x32_bf16 v[16:19], v[232:235], v[192:195], v[16:19]
	v_mfma_f32_16x16x32_bf16 v[4:7], v[220:223], v[200:203], v[4:7]
	v_mfma_f32_16x16x32_bf16 v[0:3], v[232:235], v[200:203], v[0:3]
	v_mfma_f32_16x16x32_bf16 v[52:55], v[228:231], v[160:163], v[52:55]
	v_mfma_f32_16x16x32_bf16 v[48:51], v[236:239], v[160:163], v[48:51]
	v_mfma_f32_16x16x32_bf16 v[36:39], v[228:231], v[188:191], v[36:39]
	v_mfma_f32_16x16x32_bf16 v[32:35], v[236:239], v[188:191], v[32:35]
	v_mfma_f32_16x16x32_bf16 v[20:23], v[228:231], v[196:199], v[20:23]
	v_mfma_f32_16x16x32_bf16 v[16:19], v[236:239], v[196:199], v[16:19]
	v_mfma_f32_16x16x32_bf16 v[4:7], v[228:231], v[204:207], v[4:7]
	v_mfma_f32_16x16x32_bf16 v[0:3], v[236:239], v[204:207], v[0:3]
	s_barrier
	s_add_i32 s34, s34, 2
	s_add_u32 s52, s52, 0x100
	s_addc_u32 s53, s53, 0
	s_add_u32 s31, s31, 0x100
	s_addc_u32 s33, s33, 0
	s_cmp_gt_u32 s34, 13
	s_cbranch_scc0 .LBB0_326
	v_lshl_add_u32 v128, s0, 8, v151
	v_readlane_b32 s0, v252, 36
	v_ashrrev_i32_e32 v129, 31, v128
	v_readlane_b32 s1, v252, 37
	v_or_b32_e32 v132, 16, v128
	v_or_b32_e32 v136, 32, v128
	v_lshl_add_u64 v[130:131], v[128:129], 3, s[0:1]
	v_ashrrev_i32_e32 v133, 31, v132
	v_ashrrev_i32_e32 v137, 31, v136
	v_or_b32_e32 v140, 48, v128
	v_lshl_add_u64 v[134:135], v[132:133], 3, s[0:1]
	v_lshl_add_u64 v[138:139], v[136:137], 3, s[0:1]
	v_ashrrev_i32_e32 v141, 31, v140
	global_load_dwordx2 v[202:203], v[130:131], off
	global_load_dwordx2 v[200:201], v[134:135], off
	global_load_dwordx2 v[192:193], v[138:139], off
	global_load_dwordx2 v[166:167], v[130:131], off offset:1024
	v_add_u32_e32 v164, 0x90, v128
	v_add_u32_e32 v158, 0xa0, v128
	v_add_u32_e32 v156, 0xb0, v128
	v_lshl_add_u64 v[142:143], v[140:141], 3, s[0:1]
	v_ashrrev_i32_e32 v165, 31, v164
	v_ashrrev_i32_e32 v159, 31, v158
	v_ashrrev_i32_e32 v157, 31, v156
	v_lshl_add_u64 v[130:131], v[164:165], 3, s[0:1]
	v_lshl_add_u64 v[134:135], v[158:159], 3, s[0:1]
	v_lshl_add_u64 v[138:139], v[156:157], 3, s[0:1]
	global_load_dwordx2 v[196:197], v[142:143], off
	global_load_dwordx2 v[188:189], v[130:131], off
	global_load_dwordx2 v[162:163], v[134:135], off
	global_load_dwordx2 v[160:161], v[138:139], off
	v_add_u32_e32 v168, 0x80, v128
	s_mov_b64 s[0:1], -1
	s_cmp_gt_u32 s10, 1
	v_lshlrev_b32_e32 v144, 1, v150
	v_ashrrev_i32_e32 v169, 31, v168
	v_lshlrev_b64 v[204:205], 10, v[128:129]
	v_lshlrev_b64 v[198:199], 10, v[132:133]
	v_lshlrev_b64 v[194:195], 10, v[136:137]
	v_lshlrev_b64 v[190:191], 10, v[140:141]
	s_waitcnt vmcnt(0)
	v_ffbh_u32_e32 v222, v203
	v_ffbh_u32_e32 v221, v201
	v_ffbh_u32_e32 v220, v193
	v_ffbh_u32_e32 v219, v197
	s_cbranch_scc0 .LBB0_329
	s_cmp_lt_u32 s10, 4
	s_cselect_b64 vcc, -1, 0
	v_readlane_b32 s56, v254, 23
	s_and_b64 s[0:1], vcc, exec
	v_readlane_b32 s70, v254, 37
	v_readlane_b32 s36, v252, 15
	v_readlane_b32 s71, v254, 38
	v_readlane_b32 s37, v252, 16
	s_cselect_b32 s0, s70, s36
	s_mov_b32 s11, 0x4400000
	v_readlane_b32 s30, v254, 62
	s_cselect_b32 s1, s71, s37
	s_cselect_b32 s11, s11, 0x4800000
	v_readlane_b32 s31, v254, 63
	s_add_u32 s0, s0, s30
	s_addc_u32 s1, s1, s31
	global_load_dwordx4 v[136:139], v218, s[0:1] offset:16
	global_load_dwordx4 v[140:143], v218, s[0:1]
	global_load_dwordx4 v[128:131], v218, s[0:1] offset:144
	global_load_dwordx4 v[132:135], v218, s[0:1] offset:128
	v_and_b32_e32 v177, 64, v214
	v_xor_b32_e32 v176, 16, v214
	v_add_u32_e32 v177, 64, v177
	v_cndmask_b32_e32 v223, 1.0, v215, vcc
	v_cmp_lt_i32_e32 vcc, v176, v177
	v_readlane_b32 s9, v254, 52
	s_add_u32 s11, s9, s11
	v_cndmask_b32_e32 v176, v214, v176, vcc
	v_lshlrev_b32_e32 v225, 2, v176
	v_xor_b32_e32 v176, 32, v214
	v_cmp_lt_i32_e32 vcc, v176, v177
	v_readlane_b32 s9, v254, 61
	s_addc_u32 s25, s9, 0
	v_cndmask_b32_e32 v176, v214, v176, vcc
	v_lshlrev_b32_e32 v224, 2, v176
	v_min_u32_e32 v176, 32, v222
	v_lshlrev_b64 v[228:229], v176, v[202:203]
	v_min_u32_e32 v177, 1, v228
	v_or_b32_e32 v177, v229, v177
	v_cvt_f32_u32_e32 v177, v177
	v_sub_u32_e32 v176, 32, v176
	s_lshl_b32 s0, s10, 9
	s_and_b32 s0, s0, 0x200
	v_ldexp_f32 v176, v177, v176
	v_mul_f32_e32 v176, 0x35800000, v176
	v_fmamk_f32 v176, v176, 0x3a800000, v210
	s_add_u32 s0, s11, s0
	v_rsq_f32_e32 v176, v176
	s_addc_u32 s1, s25, 0
	v_lshl_add_u64 v[206:207], s[0:1], 0, v[144:145]
	v_readlane_b32 s48, v252, 27
	v_mov_b32_e32 v228, v176
	v_pk_mul_f32 v[230:231], v[124:125], v[228:229] op_sel_hi:[1,0]
	v_pk_mul_f32 v[232:233], v[126:127], v[228:229] op_sel_hi:[1,0]
	v_pk_mul_f32 v[236:237], v[230:231], v[230:231]
	v_pk_mul_f32 v[234:235], v[232:233], v[232:233]
	v_pk_mul_f32 v[250:251], v[114:115], v[228:229] op_sel_hi:[1,0]
	v_pk_mov_b32 v[238:239], v[236:237], v[234:235] op_sel:[1,0]
	v_mov_b32_e32 v237, v235
	v_pk_add_f32 v[234:235], v[238:239], v[236:237]
	v_pk_mul_f32 v[236:237], v[120:121], v[228:229] op_sel_hi:[1,0]
	v_pk_mul_f32 v[238:239], v[122:123], v[228:229] op_sel_hi:[1,0]
	v_pk_mul_f32 v[242:243], v[236:237], v[236:237]
	v_pk_mul_f32 v[240:241], v[238:239], v[238:239]
	v_pk_add_f32 v[234:235], v[234:235], v[234:235] op_sel_hi:[0,1]
	v_pk_mov_b32 v[244:245], v[242:243], v[240:241] op_sel:[1,0]
	v_mov_b32_e32 v243, v241
	v_pk_add_f32 v[240:241], v[244:245], v[242:243]
	v_pk_mul_f32 v[244:245], v[116:117], v[228:229] op_sel_hi:[1,0]
	v_pk_mul_f32 v[242:243], v[118:119], v[228:229] op_sel_hi:[1,0]
	v_mul_f32_e32 v234, v244, v244
	v_pk_fma_f32 v[246:247], v[244:245], v[244:245], v[234:235] op_sel_hi:[1,1,0]
	v_mul_f32_e32 v234, v242, v242
	v_pk_add_f32 v[240:241], v[240:241], v[240:241] op_sel_hi:[0,1]
	v_pk_fma_f32 v[248:249], v[242:243], v[242:243], v[234:235] op_sel_hi:[1,1,0]
	v_pk_mul_f32 v[176:177], v[112:113], v[228:229] op_sel_hi:[1,0]
	v_mul_f32_e32 v234, v250, v250
	v_mul_f32_e32 v246, v176, v176
	v_mul_f32_e32 v248, v177, v177
	v_mul_f32_e32 v240, v251, v251
	v_pk_add_f32 v[228:229], v[246:247], v[248:249]
	v_pk_add_f32 v[234:235], v[234:235], v[240:241]
	v_lshl_add_u64 v[240:241], v[206:207], 0, v[204:205]
	v_pk_add_f32 v[228:229], v[228:229], v[234:235]
	v_readlane_b32 s57, v254, 24
	v_add_f32_e32 v228, v228, v229
	ds_bpermute_b32 v229, v225, v228
	v_readlane_b32 s58, v254, 25
	v_readlane_b32 s59, v254, 26
	v_readlane_b32 s60, v254, 27
	v_readlane_b32 s61, v254, 28
	s_waitcnt lgkmcnt(0)
	v_add_f32_e32 v228, v228, v229
	ds_bpermute_b32 v229, v224, v228
	v_readlane_b32 s62, v254, 29
	v_readlane_b32 s63, v254, 30
	v_readlane_b32 s64, v254, 31
	v_readlane_b32 s65, v254, 32
	s_waitcnt lgkmcnt(0)
	v_add_f32_e32 v228, v228, v229
	v_fmamk_f32 v228, v228, 0x3c800000, v210
	v_readlane_b32 s66, v254, 33
	v_rsq_f32_e32 v228, v228
	v_readlane_b32 s67, v254, 34
	v_readlane_b32 s68, v254, 35
	v_readlane_b32 s69, v254, 36
	v_mul_f32_e32 v234, v223, v228
	v_pk_mul_f32 v[228:229], v[230:231], v[234:235] op_sel_hi:[1,0]
	v_pk_mul_f32 v[230:231], v[232:233], v[234:235] op_sel_hi:[1,0]
	s_waitcnt vmcnt(2)
	v_pk_mul_f32 v[228:229], v[140:141], v[228:229]
	v_pk_mul_f32 v[230:231], v[142:143], v[230:231]
	v_pk_mul_f32 v[232:233], v[236:237], v[234:235] op_sel_hi:[1,0]
	v_pk_mul_f32 v[236:237], v[238:239], v[234:235] op_sel_hi:[1,0]
	v_cvt_pk_bf16_f32 v228, v228, v229
	v_cvt_pk_bf16_f32 v229, v230, v231
	v_pk_mul_f32 v[232:233], v[136:137], v[232:233]
	v_pk_mul_f32 v[236:237], v[138:139], v[236:237]
	v_cvt_pk_bf16_f32 v230, v232, v233
	v_pk_mul_f32 v[176:177], v[176:177], v[234:235] op_sel_hi:[1,0]
	v_cvt_pk_bf16_f32 v231, v236, v237
	global_store_dwordx4 v[240:241], v[228:231], off
	v_pk_mul_f32 v[232:233], v[250:251], v[234:235] op_sel_hi:[1,0]
	s_waitcnt vmcnt(2)
	v_pk_mul_f32 v[176:177], v[128:129], v[176:177]
	v_pk_mul_f32 v[228:229], v[244:245], v[234:235] op_sel_hi:[1,0]
	v_pk_mul_f32 v[230:231], v[242:243], v[234:235] op_sel_hi:[1,0]
	s_waitcnt vmcnt(1)
	v_pk_mul_f32 v[228:229], v[132:133], v[228:229]
	v_pk_mul_f32 v[230:231], v[134:135], v[230:231]
	v_cvt_pk_bf16_f32 v228, v228, v229
	v_pk_mul_f32 v[232:233], v[130:131], v[232:233]
	v_cvt_pk_bf16_f32 v229, v230, v231
	v_cvt_pk_bf16_f32 v230, v176, v177
	s_nop 1
	v_readlane_b32 s38, v252, 17
	v_cvt_pk_bf16_f32 v231, v232, v233
	s_nop 1
	global_store_dwordx4 v[240:241], v[228:231], off offset:64
	v_readlane_b32 s39, v252, 18
	v_readlane_b32 s40, v252, 19
	v_min_u32_e32 v228, 32, v221
	v_lshlrev_b64 v[176:177], v228, v[200:201]
	v_min_u32_e32 v176, 1, v176
	v_or_b32_e32 v176, v177, v176
	v_cvt_f32_u32_e32 v176, v176
	v_sub_u32_e32 v177, 32, v228
	v_readlane_b32 s41, v252, 20
	v_readlane_b32 s42, v252, 21
	v_ldexp_f32 v176, v176, v177
	v_mul_f32_e32 v176, 0x35800000, v176
	v_fmamk_f32 v176, v176, 0x3a800000, v210
	v_readlane_b32 s43, v252, 22
	v_rsq_f32_e32 v176, v176
	v_readlane_b32 s44, v252, 23
	v_readlane_b32 s45, v252, 24
	v_readlane_b32 s46, v252, 25
	v_pk_mul_f32 v[228:229], v[108:109], v[176:177] op_sel_hi:[1,0]
	v_pk_mul_f32 v[230:231], v[110:111], v[176:177] op_sel_hi:[1,0]
	v_pk_mul_f32 v[234:235], v[228:229], v[228:229]
	v_pk_mul_f32 v[232:233], v[230:231], v[230:231]
	v_pk_mul_f32 v[248:249], v[98:99], v[176:177] op_sel_hi:[1,0]
	v_pk_mov_b32 v[236:237], v[234:235], v[232:233] op_sel:[1,0]
	v_mov_b32_e32 v235, v233
	v_pk_add_f32 v[232:233], v[236:237], v[234:235]
	v_pk_mul_f32 v[234:235], v[104:105], v[176:177] op_sel_hi:[1,0]
	v_pk_mul_f32 v[236:237], v[106:107], v[176:177] op_sel_hi:[1,0]
	v_pk_mul_f32 v[240:241], v[234:235], v[234:235]
	v_pk_mul_f32 v[238:239], v[236:237], v[236:237]
	v_pk_add_f32 v[232:233], v[232:233], v[232:233] op_sel_hi:[0,1]
	v_pk_mov_b32 v[242:243], v[240:241], v[238:239] op_sel:[1,0]
	v_mov_b32_e32 v241, v239
	v_pk_add_f32 v[238:239], v[242:243], v[240:241]
	v_pk_mul_f32 v[242:243], v[100:101], v[176:177] op_sel_hi:[1,0]
	v_pk_mul_f32 v[240:241], v[102:103], v[176:177] op_sel_hi:[1,0]
	v_mul_f32_e32 v232, v242, v242
	v_pk_fma_f32 v[244:245], v[242:243], v[242:243], v[232:233] op_sel_hi:[1,1,0]
	v_mul_f32_e32 v232, v240, v240
	v_pk_add_f32 v[238:239], v[238:239], v[238:239] op_sel_hi:[0,1]
	v_pk_fma_f32 v[246:247], v[240:241], v[240:241], v[232:233] op_sel_hi:[1,1,0]
	v_pk_mul_f32 v[176:177], v[96:97], v[176:177] op_sel_hi:[1,0]
	v_mul_f32_e32 v232, v248, v248
	v_mul_f32_e32 v244, v176, v176
	v_mul_f32_e32 v246, v177, v177
	v_mul_f32_e32 v238, v249, v249
	v_pk_add_f32 v[244:245], v[244:245], v[246:247]
	v_pk_add_f32 v[232:233], v[232:233], v[238:239]
	v_lshl_add_u64 v[238:239], v[206:207], 0, v[198:199]
	v_pk_add_f32 v[232:233], v[244:245], v[232:233]
	v_readlane_b32 s47, v252, 26
	v_add_f32_e32 v232, v232, v233
	ds_bpermute_b32 v233, v225, v232
	v_readlane_b32 s49, v252, 28
	v_readlane_b32 s50, v252, 29
	v_readlane_b32 s51, v252, 30
	v_readlane_b32 s48, v252, 40
	s_waitcnt lgkmcnt(0)
	v_add_f32_e32 v232, v232, v233
	ds_bpermute_b32 v233, v224, v232
	s_mov_b64 s[0:1], 0
	s_waitcnt lgkmcnt(0)
	v_add_f32_e32 v232, v232, v233
	v_fmamk_f32 v232, v232, 0x3c800000, v210
	s_nop 0
	v_rsq_f32_e32 v232, v232
	s_nop 0
	v_mul_f32_e32 v232, v223, v232
	v_pk_mul_f32 v[228:229], v[228:229], v[232:233] op_sel_hi:[1,0]
	v_pk_mul_f32 v[230:231], v[230:231], v[232:233] op_sel_hi:[1,0]
	v_pk_mul_f32 v[228:229], v[140:141], v[228:229]
	v_pk_mul_f32 v[230:231], v[142:143], v[230:231]
	v_pk_mul_f32 v[234:235], v[234:235], v[232:233] op_sel_hi:[1,0]
	v_pk_mul_f32 v[236:237], v[236:237], v[232:233] op_sel_hi:[1,0]
	v_cvt_pk_bf16_f32 v228, v228, v229
	v_cvt_pk_bf16_f32 v229, v230, v231
	v_pk_mul_f32 v[234:235], v[136:137], v[234:235]
	v_pk_mul_f32 v[236:237], v[138:139], v[236:237]
	v_cvt_pk_bf16_f32 v230, v234, v235
	v_pk_mul_f32 v[176:177], v[176:177], v[232:233] op_sel_hi:[1,0]
	v_cvt_pk_bf16_f32 v231, v236, v237
	global_store_dwordx4 v[238:239], v[228:231], off
	v_pk_mul_f32 v[176:177], v[128:129], v[176:177]
	s_nop 0
	v_pk_mul_f32 v[228:229], v[242:243], v[232:233] op_sel_hi:[1,0]
	v_pk_mul_f32 v[230:231], v[240:241], v[232:233] op_sel_hi:[1,0]
	v_pk_mul_f32 v[228:229], v[132:133], v[228:229]
	v_pk_mul_f32 v[230:231], v[134:135], v[230:231]
	v_pk_mul_f32 v[232:233], v[248:249], v[232:233] op_sel_hi:[1,0]
	v_cvt_pk_bf16_f32 v228, v228, v229
	v_cvt_pk_bf16_f32 v229, v230, v231
	v_cvt_pk_bf16_f32 v230, v176, v177
	s_nop 0
	v_pk_mul_f32 v[232:233], v[130:131], v[232:233]
	s_nop 0
	v_cvt_pk_bf16_f32 v231, v232, v233
	global_store_dwordx4 v[238:239], v[228:231], off offset:64
	s_nop 1
	v_min_u32_e32 v228, 32, v220
	v_lshlrev_b64 v[176:177], v228, v[192:193]
	v_min_u32_e32 v176, 1, v176
	v_or_b32_e32 v176, v177, v176
	v_cvt_f32_u32_e32 v176, v176
	v_sub_u32_e32 v177, 32, v228
	v_ldexp_f32 v176, v176, v177
	v_mul_f32_e32 v176, 0x35800000, v176
	v_fmamk_f32 v176, v176, 0x3a800000, v210
	s_nop 0
	v_rsq_f32_e32 v176, v176
	s_nop 0
	v_pk_mul_f32 v[228:229], v[92:93], v[176:177] op_sel_hi:[1,0]
	v_pk_mul_f32 v[230:231], v[94:95], v[176:177] op_sel_hi:[1,0]
	v_pk_mul_f32 v[234:235], v[228:229], v[228:229]
	v_pk_mul_f32 v[232:233], v[230:231], v[230:231]
	v_pk_mul_f32 v[248:249], v[82:83], v[176:177] op_sel_hi:[1,0]
	v_pk_mov_b32 v[236:237], v[234:235], v[232:233] op_sel:[1,0]
	v_mov_b32_e32 v235, v233
	v_pk_add_f32 v[232:233], v[236:237], v[234:235]
	v_pk_mul_f32 v[234:235], v[88:89], v[176:177] op_sel_hi:[1,0]
	v_pk_mul_f32 v[236:237], v[90:91], v[176:177] op_sel_hi:[1,0]
	v_pk_mul_f32 v[240:241], v[234:235], v[234:235]
	v_pk_mul_f32 v[238:239], v[236:237], v[236:237]
	v_pk_add_f32 v[232:233], v[232:233], v[232:233] op_sel_hi:[0,1]
	v_pk_mov_b32 v[242:243], v[240:241], v[238:239] op_sel:[1,0]
	v_mov_b32_e32 v241, v239
	v_pk_add_f32 v[238:239], v[242:243], v[240:241]
	v_pk_mul_f32 v[242:243], v[84:85], v[176:177] op_sel_hi:[1,0]
	v_pk_mul_f32 v[240:241], v[86:87], v[176:177] op_sel_hi:[1,0]
	v_mul_f32_e32 v232, v242, v242
	v_pk_fma_f32 v[244:245], v[242:243], v[242:243], v[232:233] op_sel_hi:[1,1,0]
	v_mul_f32_e32 v232, v240, v240
	v_pk_add_f32 v[238:239], v[238:239], v[238:239] op_sel_hi:[0,1]
	v_pk_fma_f32 v[246:247], v[240:241], v[240:241], v[232:233] op_sel_hi:[1,1,0]
	v_pk_mul_f32 v[176:177], v[80:81], v[176:177] op_sel_hi:[1,0]
	v_mul_f32_e32 v232, v248, v248
	v_mul_f32_e32 v244, v176, v176
	v_mul_f32_e32 v246, v177, v177
	v_mul_f32_e32 v238, v249, v249
	v_pk_add_f32 v[244:245], v[244:245], v[246:247]
	v_pk_add_f32 v[232:233], v[232:233], v[238:239]
	v_lshl_add_u64 v[238:239], v[206:207], 0, v[194:195]
	v_pk_add_f32 v[232:233], v[244:245], v[232:233]
	s_nop 0
	v_add_f32_e32 v232, v232, v233
	ds_bpermute_b32 v233, v225, v232
	s_waitcnt lgkmcnt(0)
	v_add_f32_e32 v232, v232, v233
	ds_bpermute_b32 v233, v224, v232
	s_waitcnt lgkmcnt(0)
	v_add_f32_e32 v232, v232, v233
	v_fmamk_f32 v232, v232, 0x3c800000, v210
	s_nop 0
	v_rsq_f32_e32 v232, v232
	s_nop 0
	v_mul_f32_e32 v232, v223, v232
	v_pk_mul_f32 v[228:229], v[228:229], v[232:233] op_sel_hi:[1,0]
	v_pk_mul_f32 v[230:231], v[230:231], v[232:233] op_sel_hi:[1,0]
	v_pk_mul_f32 v[228:229], v[140:141], v[228:229]
	v_pk_mul_f32 v[230:231], v[142:143], v[230:231]
	v_pk_mul_f32 v[234:235], v[234:235], v[232:233] op_sel_hi:[1,0]
	v_pk_mul_f32 v[236:237], v[236:237], v[232:233] op_sel_hi:[1,0]
	v_cvt_pk_bf16_f32 v228, v228, v229
	v_cvt_pk_bf16_f32 v229, v230, v231
	v_pk_mul_f32 v[234:235], v[136:137], v[234:235]
	v_pk_mul_f32 v[236:237], v[138:139], v[236:237]
	v_cvt_pk_bf16_f32 v230, v234, v235
	v_pk_mul_f32 v[176:177], v[176:177], v[232:233] op_sel_hi:[1,0]
	v_cvt_pk_bf16_f32 v231, v236, v237
	global_store_dwordx4 v[238:239], v[228:231], off
	v_pk_mul_f32 v[176:177], v[128:129], v[176:177]
	s_nop 0
	v_pk_mul_f32 v[228:229], v[242:243], v[232:233] op_sel_hi:[1,0]
	v_pk_mul_f32 v[230:231], v[240:241], v[232:233] op_sel_hi:[1,0]
	v_pk_mul_f32 v[228:229], v[132:133], v[228:229]
	v_pk_mul_f32 v[230:231], v[134:135], v[230:231]
	v_pk_mul_f32 v[232:233], v[248:249], v[232:233] op_sel_hi:[1,0]
	v_cvt_pk_bf16_f32 v228, v228, v229
	v_cvt_pk_bf16_f32 v229, v230, v231
	v_cvt_pk_bf16_f32 v230, v176, v177
	s_nop 0
	v_pk_mul_f32 v[232:233], v[130:131], v[232:233]
	s_nop 0
	v_cvt_pk_bf16_f32 v231, v232, v233
	global_store_dwordx4 v[238:239], v[228:231], off offset:64
	s_nop 1
	v_min_u32_e32 v228, 32, v219
	v_lshlrev_b64 v[176:177], v228, v[196:197]
	v_min_u32_e32 v176, 1, v176
	v_or_b32_e32 v176, v177, v176
	v_cvt_f32_u32_e32 v176, v176
	v_sub_u32_e32 v177, 32, v228
	v_ldexp_f32 v176, v176, v177
	v_mul_f32_e32 v176, 0x35800000, v176
	v_fmamk_f32 v176, v176, 0x3a800000, v210
	s_nop 0
	v_rsq_f32_e32 v176, v176
	s_nop 0
	v_pk_mul_f32 v[228:229], v[76:77], v[176:177] op_sel_hi:[1,0]
	v_pk_mul_f32 v[230:231], v[78:79], v[176:177] op_sel_hi:[1,0]
	v_pk_mul_f32 v[234:235], v[228:229], v[228:229]
	v_pk_mul_f32 v[232:233], v[230:231], v[230:231]
	v_pk_mul_f32 v[248:249], v[66:67], v[176:177] op_sel_hi:[1,0]
	v_pk_mov_b32 v[236:237], v[234:235], v[232:233] op_sel:[1,0]
	v_mov_b32_e32 v235, v233
	v_pk_add_f32 v[232:233], v[236:237], v[234:235]
	v_pk_mul_f32 v[234:235], v[72:73], v[176:177] op_sel_hi:[1,0]
	v_pk_mul_f32 v[236:237], v[74:75], v[176:177] op_sel_hi:[1,0]
	v_pk_mul_f32 v[240:241], v[234:235], v[234:235]
	v_pk_mul_f32 v[238:239], v[236:237], v[236:237]
	v_pk_add_f32 v[232:233], v[232:233], v[232:233] op_sel_hi:[0,1]
	v_pk_mov_b32 v[242:243], v[240:241], v[238:239] op_sel:[1,0]
	v_mov_b32_e32 v241, v239
	v_pk_add_f32 v[238:239], v[242:243], v[240:241]
	v_pk_mul_f32 v[242:243], v[68:69], v[176:177] op_sel_hi:[1,0]
	v_pk_mul_f32 v[240:241], v[70:71], v[176:177] op_sel_hi:[1,0]
	v_mul_f32_e32 v232, v242, v242
	v_pk_fma_f32 v[244:245], v[242:243], v[242:243], v[232:233] op_sel_hi:[1,1,0]
	v_mul_f32_e32 v232, v240, v240
	v_pk_add_f32 v[238:239], v[238:239], v[238:239] op_sel_hi:[0,1]
	v_pk_fma_f32 v[246:247], v[240:241], v[240:241], v[232:233] op_sel_hi:[1,1,0]
	v_pk_mul_f32 v[176:177], v[64:65], v[176:177] op_sel_hi:[1,0]
	v_mul_f32_e32 v232, v248, v248
	v_mul_f32_e32 v244, v176, v176
	v_mul_f32_e32 v246, v177, v177
	v_mul_f32_e32 v238, v249, v249
	v_pk_add_f32 v[244:245], v[244:245], v[246:247]
	v_pk_add_f32 v[232:233], v[232:233], v[238:239]
	v_lshl_add_u64 v[238:239], v[206:207], 0, v[190:191]
	v_pk_add_f32 v[232:233], v[244:245], v[232:233]
	s_nop 0
	v_add_f32_e32 v232, v232, v233
	ds_bpermute_b32 v233, v225, v232
	s_waitcnt lgkmcnt(0)
	v_add_f32_e32 v232, v232, v233
	ds_bpermute_b32 v233, v224, v232
	s_waitcnt lgkmcnt(0)
	v_add_f32_e32 v232, v232, v233
	v_fmamk_f32 v232, v232, 0x3c800000, v210
	s_nop 0
	v_rsq_f32_e32 v232, v232
	s_nop 0
	v_mul_f32_e32 v232, v223, v232
	v_pk_mul_f32 v[228:229], v[228:229], v[232:233] op_sel_hi:[1,0]
	v_pk_mul_f32 v[230:231], v[230:231], v[232:233] op_sel_hi:[1,0]
	v_pk_mul_f32 v[228:229], v[140:141], v[228:229]
	v_pk_mul_f32 v[230:231], v[142:143], v[230:231]
	v_pk_mul_f32 v[234:235], v[234:235], v[232:233] op_sel_hi:[1,0]
	v_pk_mul_f32 v[236:237], v[236:237], v[232:233] op_sel_hi:[1,0]
	v_pk_mul_f32 v[234:235], v[136:137], v[234:235]
	v_pk_mul_f32 v[236:237], v[138:139], v[236:237]
	v_cvt_pk_bf16_f32 v228, v228, v229
	v_cvt_pk_bf16_f32 v229, v230, v231
	v_cvt_pk_bf16_f32 v230, v234, v235
	v_pk_mul_f32 v[176:177], v[176:177], v[232:233] op_sel_hi:[1,0]
	v_cvt_pk_bf16_f32 v231, v236, v237
	global_store_dwordx4 v[238:239], v[228:231], off
	v_pk_mul_f32 v[176:177], v[128:129], v[176:177]
	s_nop 0
	v_pk_mul_f32 v[228:229], v[242:243], v[232:233] op_sel_hi:[1,0]
	v_pk_mul_f32 v[230:231], v[240:241], v[232:233] op_sel_hi:[1,0]
	v_pk_mul_f32 v[228:229], v[132:133], v[228:229]
	v_pk_mul_f32 v[230:231], v[134:135], v[230:231]
	v_pk_mul_f32 v[232:233], v[248:249], v[232:233] op_sel_hi:[1,0]
	v_cvt_pk_bf16_f32 v228, v228, v229
	v_cvt_pk_bf16_f32 v229, v230, v231
	v_cvt_pk_bf16_f32 v230, v176, v177
	v_ffbh_u32_e32 v176, v167
	v_pk_mul_f32 v[232:233], v[130:131], v[232:233]
	s_nop 0
	v_cvt_pk_bf16_f32 v231, v232, v233
	global_store_dwordx4 v[238:239], v[228:231], off offset:64
	s_nop 1
	v_min_u32_e32 v228, 32, v176
	v_lshlrev_b64 v[176:177], v228, v[166:167]
	v_min_u32_e32 v176, 1, v176
	v_or_b32_e32 v176, v177, v176
	v_cvt_f32_u32_e32 v176, v176
	v_sub_u32_e32 v177, 32, v228
	v_ldexp_f32 v176, v176, v177
	v_mul_f32_e32 v176, 0x35800000, v176
	v_fmamk_f32 v176, v176, 0x3a800000, v210
	s_nop 0
	v_rsq_f32_e32 v176, v176
	s_nop 0
	v_pk_mul_f32 v[228:229], v[60:61], v[176:177] op_sel_hi:[1,0]
	v_pk_mul_f32 v[230:231], v[62:63], v[176:177] op_sel_hi:[1,0]
	v_pk_mul_f32 v[234:235], v[228:229], v[228:229]
	v_pk_mul_f32 v[232:233], v[230:231], v[230:231]
	v_pk_mul_f32 v[248:249], v[50:51], v[176:177] op_sel_hi:[1,0]
	v_pk_mov_b32 v[236:237], v[234:235], v[232:233] op_sel:[1,0]
	v_mov_b32_e32 v235, v233
	v_pk_add_f32 v[232:233], v[236:237], v[234:235]
	v_pk_mul_f32 v[234:235], v[56:57], v[176:177] op_sel_hi:[1,0]
	v_pk_mul_f32 v[236:237], v[58:59], v[176:177] op_sel_hi:[1,0]
	v_pk_mul_f32 v[240:241], v[234:235], v[234:235]
	v_pk_mul_f32 v[238:239], v[236:237], v[236:237]
	v_pk_add_f32 v[232:233], v[232:233], v[232:233] op_sel_hi:[0,1]
	v_pk_mov_b32 v[242:243], v[240:241], v[238:239] op_sel:[1,0]
	v_mov_b32_e32 v241, v239
	v_pk_add_f32 v[238:239], v[242:243], v[240:241]
	v_pk_mul_f32 v[242:243], v[52:53], v[176:177] op_sel_hi:[1,0]
	v_pk_mul_f32 v[240:241], v[54:55], v[176:177] op_sel_hi:[1,0]
	v_mul_f32_e32 v232, v242, v242
	v_pk_fma_f32 v[244:245], v[242:243], v[242:243], v[232:233] op_sel_hi:[1,1,0]
	v_mul_f32_e32 v232, v240, v240
	v_pk_add_f32 v[238:239], v[238:239], v[238:239] op_sel_hi:[0,1]
	v_pk_fma_f32 v[246:247], v[240:241], v[240:241], v[232:233] op_sel_hi:[1,1,0]
	v_pk_mul_f32 v[176:177], v[48:49], v[176:177] op_sel_hi:[1,0]
	v_mul_f32_e32 v232, v248, v248
	v_mul_f32_e32 v244, v176, v176
	v_mul_f32_e32 v246, v177, v177
	v_mul_f32_e32 v238, v249, v249
	v_pk_add_f32 v[244:245], v[244:245], v[246:247]
	v_pk_add_f32 v[232:233], v[232:233], v[238:239]
	v_lshlrev_b64 v[238:239], 10, v[168:169]
	v_pk_add_f32 v[232:233], v[244:245], v[232:233]
	v_lshl_add_u64 v[238:239], v[206:207], 0, v[238:239]
	v_add_f32_e32 v232, v232, v233
	ds_bpermute_b32 v233, v225, v232
	s_waitcnt lgkmcnt(0)
	v_add_f32_e32 v232, v232, v233
	ds_bpermute_b32 v233, v224, v232
	s_waitcnt lgkmcnt(0)
	v_add_f32_e32 v232, v232, v233
	v_fmamk_f32 v232, v232, 0x3c800000, v210
	s_nop 0
	v_rsq_f32_e32 v232, v232
	s_nop 0
	v_mul_f32_e32 v232, v223, v232
	v_pk_mul_f32 v[228:229], v[228:229], v[232:233] op_sel_hi:[1,0]
	v_pk_mul_f32 v[230:231], v[230:231], v[232:233] op_sel_hi:[1,0]
	v_pk_mul_f32 v[228:229], v[140:141], v[228:229]
	v_pk_mul_f32 v[230:231], v[142:143], v[230:231]
	v_pk_mul_f32 v[234:235], v[234:235], v[232:233] op_sel_hi:[1,0]
	v_pk_mul_f32 v[236:237], v[236:237], v[232:233] op_sel_hi:[1,0]
	v_pk_mul_f32 v[234:235], v[136:137], v[234:235]
	v_pk_mul_f32 v[236:237], v[138:139], v[236:237]
	v_cvt_pk_bf16_f32 v228, v228, v229
	v_cvt_pk_bf16_f32 v229, v230, v231
	v_cvt_pk_bf16_f32 v230, v234, v235
	v_pk_mul_f32 v[176:177], v[176:177], v[232:233] op_sel_hi:[1,0]
	v_cvt_pk_bf16_f32 v231, v236, v237
	global_store_dwordx4 v[238:239], v[228:231], off
	v_pk_mul_f32 v[176:177], v[128:129], v[176:177]
	s_nop 0
	v_pk_mul_f32 v[228:229], v[242:243], v[232:233] op_sel_hi:[1,0]
	v_pk_mul_f32 v[230:231], v[240:241], v[232:233] op_sel_hi:[1,0]
	v_pk_mul_f32 v[228:229], v[132:133], v[228:229]
	v_pk_mul_f32 v[230:231], v[134:135], v[230:231]
	v_pk_mul_f32 v[232:233], v[248:249], v[232:233] op_sel_hi:[1,0]
	v_cvt_pk_bf16_f32 v228, v228, v229
	v_cvt_pk_bf16_f32 v229, v230, v231
	v_cvt_pk_bf16_f32 v230, v176, v177
	v_ffbh_u32_e32 v176, v189
	v_pk_mul_f32 v[232:233], v[130:131], v[232:233]
	s_nop 0
	v_cvt_pk_bf16_f32 v231, v232, v233
	global_store_dwordx4 v[238:239], v[228:231], off offset:64
	s_nop 1
	v_min_u32_e32 v228, 32, v176
	v_lshlrev_b64 v[176:177], v228, v[188:189]
	v_min_u32_e32 v176, 1, v176
	v_or_b32_e32 v176, v177, v176
	v_cvt_f32_u32_e32 v176, v176
	v_sub_u32_e32 v177, 32, v228
	v_ldexp_f32 v176, v176, v177
	v_mul_f32_e32 v176, 0x35800000, v176
	v_fmamk_f32 v176, v176, 0x3a800000, v210
	s_nop 0
	v_rsq_f32_e32 v176, v176
	s_nop 0
	v_pk_mul_f32 v[228:229], v[44:45], v[176:177] op_sel_hi:[1,0]
	v_pk_mul_f32 v[230:231], v[46:47], v[176:177] op_sel_hi:[1,0]
	v_pk_mul_f32 v[234:235], v[228:229], v[228:229]
	v_pk_mul_f32 v[232:233], v[230:231], v[230:231]
	v_pk_mul_f32 v[248:249], v[34:35], v[176:177] op_sel_hi:[1,0]
	v_pk_mov_b32 v[236:237], v[234:235], v[232:233] op_sel:[1,0]
	v_mov_b32_e32 v235, v233
	v_pk_add_f32 v[232:233], v[236:237], v[234:235]
	v_pk_mul_f32 v[234:235], v[40:41], v[176:177] op_sel_hi:[1,0]
	v_pk_mul_f32 v[236:237], v[42:43], v[176:177] op_sel_hi:[1,0]
	v_pk_mul_f32 v[240:241], v[234:235], v[234:235]
	v_pk_mul_f32 v[238:239], v[236:237], v[236:237]
	v_pk_add_f32 v[232:233], v[232:233], v[232:233] op_sel_hi:[0,1]
	v_pk_mov_b32 v[242:243], v[240:241], v[238:239] op_sel:[1,0]
	v_mov_b32_e32 v241, v239
	v_pk_add_f32 v[238:239], v[242:243], v[240:241]
	v_pk_mul_f32 v[242:243], v[36:37], v[176:177] op_sel_hi:[1,0]
	v_pk_mul_f32 v[240:241], v[38:39], v[176:177] op_sel_hi:[1,0]
	v_mul_f32_e32 v232, v242, v242
	v_pk_fma_f32 v[244:245], v[242:243], v[242:243], v[232:233] op_sel_hi:[1,1,0]
	v_mul_f32_e32 v232, v240, v240
	v_pk_add_f32 v[238:239], v[238:239], v[238:239] op_sel_hi:[0,1]
	v_pk_fma_f32 v[246:247], v[240:241], v[240:241], v[232:233] op_sel_hi:[1,1,0]
	v_pk_mul_f32 v[176:177], v[32:33], v[176:177] op_sel_hi:[1,0]
	v_mul_f32_e32 v232, v248, v248
	v_mul_f32_e32 v244, v176, v176
	v_mul_f32_e32 v246, v177, v177
	v_mul_f32_e32 v238, v249, v249
	v_pk_add_f32 v[244:245], v[244:245], v[246:247]
	v_pk_add_f32 v[232:233], v[232:233], v[238:239]
	v_lshlrev_b64 v[238:239], 10, v[164:165]
	v_pk_add_f32 v[232:233], v[244:245], v[232:233]
	v_lshl_add_u64 v[238:239], v[206:207], 0, v[238:239]
	v_add_f32_e32 v232, v232, v233
	ds_bpermute_b32 v233, v225, v232
	s_waitcnt lgkmcnt(0)
	v_add_f32_e32 v232, v232, v233
	ds_bpermute_b32 v233, v224, v232
	s_waitcnt lgkmcnt(0)
	v_add_f32_e32 v232, v232, v233
	v_fmamk_f32 v232, v232, 0x3c800000, v210
	s_nop 0
	v_rsq_f32_e32 v232, v232
	s_nop 0
	v_mul_f32_e32 v232, v223, v232
	v_pk_mul_f32 v[228:229], v[228:229], v[232:233] op_sel_hi:[1,0]
	v_pk_mul_f32 v[230:231], v[230:231], v[232:233] op_sel_hi:[1,0]
	v_pk_mul_f32 v[228:229], v[140:141], v[228:229]
	v_pk_mul_f32 v[230:231], v[142:143], v[230:231]
	v_pk_mul_f32 v[234:235], v[234:235], v[232:233] op_sel_hi:[1,0]
	v_pk_mul_f32 v[236:237], v[236:237], v[232:233] op_sel_hi:[1,0]
	v_pk_mul_f32 v[234:235], v[136:137], v[234:235]
	v_pk_mul_f32 v[236:237], v[138:139], v[236:237]
	v_cvt_pk_bf16_f32 v228, v228, v229
	v_cvt_pk_bf16_f32 v229, v230, v231
	v_cvt_pk_bf16_f32 v230, v234, v235
	v_pk_mul_f32 v[176:177], v[176:177], v[232:233] op_sel_hi:[1,0]
	v_cvt_pk_bf16_f32 v231, v236, v237
	global_store_dwordx4 v[238:239], v[228:231], off
	v_pk_mul_f32 v[176:177], v[128:129], v[176:177]
	s_nop 0
	v_pk_mul_f32 v[228:229], v[242:243], v[232:233] op_sel_hi:[1,0]
	v_pk_mul_f32 v[230:231], v[240:241], v[232:233] op_sel_hi:[1,0]
	v_pk_mul_f32 v[228:229], v[132:133], v[228:229]
	v_pk_mul_f32 v[230:231], v[134:135], v[230:231]
	v_pk_mul_f32 v[232:233], v[248:249], v[232:233] op_sel_hi:[1,0]
	v_cvt_pk_bf16_f32 v228, v228, v229
	v_cvt_pk_bf16_f32 v229, v230, v231
	v_cvt_pk_bf16_f32 v230, v176, v177
	v_ffbh_u32_e32 v176, v163
	v_pk_mul_f32 v[232:233], v[130:131], v[232:233]
	s_nop 0
	v_cvt_pk_bf16_f32 v231, v232, v233
	global_store_dwordx4 v[238:239], v[228:231], off offset:64
	s_nop 1
	v_min_u32_e32 v228, 32, v176
	v_lshlrev_b64 v[176:177], v228, v[162:163]
	v_min_u32_e32 v176, 1, v176
	v_or_b32_e32 v176, v177, v176
	v_cvt_f32_u32_e32 v176, v176
	v_sub_u32_e32 v177, 32, v228
	v_ldexp_f32 v176, v176, v177
	v_mul_f32_e32 v176, 0x35800000, v176
	v_fmamk_f32 v176, v176, 0x3a800000, v210
	s_nop 0
	v_rsq_f32_e32 v176, v176
	s_nop 0
	v_pk_mul_f32 v[228:229], v[28:29], v[176:177] op_sel_hi:[1,0]
	v_pk_mul_f32 v[230:231], v[30:31], v[176:177] op_sel_hi:[1,0]
	v_pk_mul_f32 v[234:235], v[228:229], v[228:229]
	v_pk_mul_f32 v[232:233], v[230:231], v[230:231]
	v_pk_mul_f32 v[248:249], v[18:19], v[176:177] op_sel_hi:[1,0]
	v_pk_mov_b32 v[236:237], v[234:235], v[232:233] op_sel:[1,0]
	v_mov_b32_e32 v235, v233
	v_pk_add_f32 v[232:233], v[236:237], v[234:235]
	v_pk_mul_f32 v[234:235], v[24:25], v[176:177] op_sel_hi:[1,0]
	v_pk_mul_f32 v[236:237], v[26:27], v[176:177] op_sel_hi:[1,0]
	v_pk_mul_f32 v[240:241], v[234:235], v[234:235]
	v_pk_mul_f32 v[238:239], v[236:237], v[236:237]
	v_pk_add_f32 v[232:233], v[232:233], v[232:233] op_sel_hi:[0,1]
	v_pk_mov_b32 v[242:243], v[240:241], v[238:239] op_sel:[1,0]
	v_mov_b32_e32 v241, v239
	v_pk_add_f32 v[238:239], v[242:243], v[240:241]
	v_pk_mul_f32 v[242:243], v[20:21], v[176:177] op_sel_hi:[1,0]
	v_pk_mul_f32 v[240:241], v[22:23], v[176:177] op_sel_hi:[1,0]
	v_mul_f32_e32 v232, v242, v242
	v_pk_fma_f32 v[244:245], v[242:243], v[242:243], v[232:233] op_sel_hi:[1,1,0]
	v_mul_f32_e32 v232, v240, v240
	v_pk_add_f32 v[238:239], v[238:239], v[238:239] op_sel_hi:[0,1]
	v_pk_fma_f32 v[246:247], v[240:241], v[240:241], v[232:233] op_sel_hi:[1,1,0]
	v_pk_mul_f32 v[176:177], v[16:17], v[176:177] op_sel_hi:[1,0]
	v_mul_f32_e32 v232, v248, v248
	v_mul_f32_e32 v244, v176, v176
	v_mul_f32_e32 v246, v177, v177
	v_mul_f32_e32 v238, v249, v249
	v_pk_add_f32 v[244:245], v[244:245], v[246:247]
	v_pk_add_f32 v[232:233], v[232:233], v[238:239]
	v_lshlrev_b64 v[238:239], 10, v[158:159]
	v_pk_add_f32 v[232:233], v[244:245], v[232:233]
	v_lshl_add_u64 v[238:239], v[206:207], 0, v[238:239]
	v_add_f32_e32 v232, v232, v233
	ds_bpermute_b32 v233, v225, v232
	s_waitcnt lgkmcnt(0)
	v_add_f32_e32 v232, v232, v233
	ds_bpermute_b32 v233, v224, v232
	s_waitcnt lgkmcnt(0)
	v_add_f32_e32 v232, v232, v233
	v_fmamk_f32 v232, v232, 0x3c800000, v210
	s_nop 0
	v_rsq_f32_e32 v232, v232
	s_nop 0
	v_mul_f32_e32 v232, v223, v232
	v_pk_mul_f32 v[228:229], v[228:229], v[232:233] op_sel_hi:[1,0]
	v_pk_mul_f32 v[230:231], v[230:231], v[232:233] op_sel_hi:[1,0]
	v_pk_mul_f32 v[228:229], v[140:141], v[228:229]
	v_pk_mul_f32 v[230:231], v[142:143], v[230:231]
	v_pk_mul_f32 v[234:235], v[234:235], v[232:233] op_sel_hi:[1,0]
	v_pk_mul_f32 v[236:237], v[236:237], v[232:233] op_sel_hi:[1,0]
	v_pk_mul_f32 v[234:235], v[136:137], v[234:235]
	v_pk_mul_f32 v[236:237], v[138:139], v[236:237]
	v_cvt_pk_bf16_f32 v228, v228, v229
	v_cvt_pk_bf16_f32 v229, v230, v231
	v_cvt_pk_bf16_f32 v230, v234, v235
	v_pk_mul_f32 v[176:177], v[176:177], v[232:233] op_sel_hi:[1,0]
	v_cvt_pk_bf16_f32 v231, v236, v237
	global_store_dwordx4 v[238:239], v[228:231], off
	v_pk_mul_f32 v[176:177], v[128:129], v[176:177]
	s_nop 0
	v_pk_mul_f32 v[228:229], v[242:243], v[232:233] op_sel_hi:[1,0]
	v_pk_mul_f32 v[230:231], v[240:241], v[232:233] op_sel_hi:[1,0]
	v_pk_mul_f32 v[228:229], v[132:133], v[228:229]
	v_pk_mul_f32 v[230:231], v[134:135], v[230:231]
	v_pk_mul_f32 v[232:233], v[248:249], v[232:233] op_sel_hi:[1,0]
	v_cvt_pk_bf16_f32 v228, v228, v229
	v_cvt_pk_bf16_f32 v229, v230, v231
	v_cvt_pk_bf16_f32 v230, v176, v177
	v_ffbh_u32_e32 v176, v161
	v_pk_mul_f32 v[232:233], v[130:131], v[232:233]
	s_nop 0
	v_cvt_pk_bf16_f32 v231, v232, v233
	global_store_dwordx4 v[238:239], v[228:231], off offset:64
	s_nop 1
	v_min_u32_e32 v228, 32, v176
	v_lshlrev_b64 v[176:177], v228, v[160:161]
	v_min_u32_e32 v176, 1, v176
	v_or_b32_e32 v176, v177, v176
	v_cvt_f32_u32_e32 v176, v176
	v_sub_u32_e32 v177, 32, v228
	v_ldexp_f32 v176, v176, v177
	v_mul_f32_e32 v176, 0x35800000, v176
	v_fmamk_f32 v176, v176, 0x3a800000, v210
	s_nop 0
	v_rsq_f32_e32 v176, v176
	s_nop 0
	v_pk_mul_f32 v[228:229], v[12:13], v[176:177] op_sel_hi:[1,0]
	v_pk_mul_f32 v[230:231], v[14:15], v[176:177] op_sel_hi:[1,0]
	v_pk_mul_f32 v[234:235], v[228:229], v[228:229]
	v_pk_mul_f32 v[232:233], v[230:231], v[230:231]
	v_pk_mul_f32 v[248:249], v[2:3], v[176:177] op_sel_hi:[1,0]
	v_pk_mov_b32 v[236:237], v[234:235], v[232:233] op_sel:[1,0]
	v_mov_b32_e32 v235, v233
	v_pk_add_f32 v[232:233], v[236:237], v[234:235]
	v_pk_mul_f32 v[234:235], v[8:9], v[176:177] op_sel_hi:[1,0]
	v_pk_mul_f32 v[236:237], v[10:11], v[176:177] op_sel_hi:[1,0]
	v_pk_mul_f32 v[240:241], v[234:235], v[234:235]
	v_pk_mul_f32 v[238:239], v[236:237], v[236:237]
	v_pk_add_f32 v[232:233], v[232:233], v[232:233] op_sel_hi:[0,1]
	v_pk_mov_b32 v[242:243], v[240:241], v[238:239] op_sel:[1,0]
	v_mov_b32_e32 v241, v239
	v_pk_add_f32 v[238:239], v[242:243], v[240:241]
	v_pk_mul_f32 v[242:243], v[4:5], v[176:177] op_sel_hi:[1,0]
	v_pk_mul_f32 v[240:241], v[6:7], v[176:177] op_sel_hi:[1,0]
	v_mul_f32_e32 v232, v242, v242
	v_pk_fma_f32 v[244:245], v[242:243], v[242:243], v[232:233] op_sel_hi:[1,1,0]
	v_mul_f32_e32 v232, v240, v240
	v_pk_add_f32 v[238:239], v[238:239], v[238:239] op_sel_hi:[0,1]
	v_pk_fma_f32 v[246:247], v[240:241], v[240:241], v[232:233] op_sel_hi:[1,1,0]
	v_pk_mul_f32 v[176:177], v[0:1], v[176:177] op_sel_hi:[1,0]
	v_mul_f32_e32 v232, v248, v248
	v_mul_f32_e32 v244, v176, v176
	v_mul_f32_e32 v246, v177, v177
	v_mul_f32_e32 v238, v249, v249
	v_pk_add_f32 v[244:245], v[244:245], v[246:247]
	v_pk_add_f32 v[232:233], v[232:233], v[238:239]
	s_nop 0
	v_pk_add_f32 v[232:233], v[244:245], v[232:233]
	s_nop 0
	v_add_f32_e32 v232, v232, v233
	ds_bpermute_b32 v225, v225, v232
	s_waitcnt lgkmcnt(0)
	v_add_f32_e32 v225, v232, v225
	ds_bpermute_b32 v224, v224, v225
	v_lshlrev_b64 v[232:233], 10, v[156:157]
	v_lshl_add_u64 v[206:207], v[206:207], 0, v[232:233]
	s_waitcnt lgkmcnt(0)
	v_add_f32_e32 v224, v225, v224
	v_fmamk_f32 v224, v224, 0x3c800000, v210
	s_nop 0
	v_rsq_f32_e32 v224, v224
	s_nop 0
	v_mul_f32_e32 v224, v223, v224
	v_pk_mul_f32 v[228:229], v[228:229], v[224:225] op_sel_hi:[1,0]
	v_pk_mul_f32 v[230:231], v[230:231], v[224:225] op_sel_hi:[1,0]
	v_pk_mul_f32 v[140:141], v[140:141], v[228:229]
	v_pk_mul_f32 v[142:143], v[142:143], v[230:231]
	v_pk_mul_f32 v[228:229], v[234:235], v[224:225] op_sel_hi:[1,0]
	v_pk_mul_f32 v[230:231], v[236:237], v[224:225] op_sel_hi:[1,0]
	s_nop 0
	v_pk_mul_f32 v[230:231], v[138:139], v[230:231]
	v_pk_mul_f32 v[138:139], v[136:137], v[228:229]
	v_cvt_pk_bf16_f32 v136, v140, v141
	v_cvt_pk_bf16_f32 v137, v142, v143
	s_nop 0
	v_cvt_pk_bf16_f32 v138, v138, v139
	v_cvt_pk_bf16_f32 v139, v230, v231
	global_store_dwordx4 v[206:207], v[136:139], off
	s_nop 1
	v_pk_mul_f32 v[136:137], v[242:243], v[224:225] op_sel_hi:[1,0]
	v_pk_mul_f32 v[138:139], v[240:241], v[224:225] op_sel_hi:[1,0]
	v_pk_mul_f32 v[132:133], v[132:133], v[136:137]
	v_pk_mul_f32 v[134:135], v[134:135], v[138:139]
	v_pk_mul_f32 v[136:137], v[176:177], v[224:225] op_sel_hi:[1,0]
	v_pk_mul_f32 v[138:139], v[248:249], v[224:225] op_sel_hi:[1,0]
	s_nop 0
	v_pk_mul_f32 v[138:139], v[130:131], v[138:139]
	v_pk_mul_f32 v[130:131], v[128:129], v[136:137]
	v_cvt_pk_bf16_f32 v128, v132, v133
	v_cvt_pk_bf16_f32 v129, v134, v135
	s_nop 0
	v_cvt_pk_bf16_f32 v130, v130, v131
	v_cvt_pk_bf16_f32 v131, v138, v139
	s_nop 1

.LBB0_350:
	s_lshl_b32 s25, s84, 1
	s_add_i32 s25, s85, s25
	s_and_b32 s85, s25, 3
	s_lshl_b32 s25, s85, 19
	s_add_u32 s92, s74, s25
	v_cmp_lt_i64_e32 vcc, s[52:53], v[180:181]
	s_addc_u32 s93, s75, 0
	s_and_b64 s[30:31], vcc, exec
	s_cselect_b32 s25, s93, s1
	s_cselect_b32 s30, s92, s0
	s_ashr_i32 s47, s46, 31
	s_lshl_b64 s[34:35], s[46:47], 19
	s_add_u32 s94, s54, s34
	s_addc_u32 s95, s55, s35
	s_and_b64 s[34:35], vcc, exec
	s_cselect_b32 s31, s95, s51
	s_cselect_b32 s33, s94, s50
	s_add_u32 s0, s0, 0x40080
	s_addc_u32 s1, s1, 0
	s_add_u32 s34, s50, 0x100
	s_addc_u32 s35, s51, 0
	s_mov_b32 s36, -2
	s_add_u32 s27, s0, 0xfffc0080
	s_addc_u32 s37, s1, -1
	s_add_i32 s47, 0, 0x10000
	v_add_u32_e32 v140, s47, v192
	ds_read_b128 v[128:131], v140
	ds_read_b128 v[132:135], v140 offset:1024
	ds_read_b128 v[136:139], v140 offset:2048
	ds_read_b128 v[140:143], v140 offset:3072
	s_cmp_eq_u32 s36, 12
	s_cselect_b32 s53, s25, s37
	s_cselect_b32 s52, s30, s27
	s_cselect_b32 s51, s31, s35
	s_cselect_b32 s50, s33, s34
	s_add_i32 m0, s77, 0xc000
	ds_read_b128 v[162:165], v194
	ds_read_b128 v[166:169], v194 offset:1024
	ds_read_b128 v[196:199], v194 offset:2048
	ds_read_b128 v[200:203], v194 offset:3072
	ds_read_b128 v[204:207], v194 offset:4096
	ds_read_b128 v[216:219], v194 offset:5120
	ds_read_b128 v[220:223], v194 offset:6144
	ds_read_b128 v[228:231], v194 offset:7168
	global_load_lds_dwordx4 v156, s[0:1]
	s_add_i32 m0, s77, 0xe000
	s_nop 0
	global_load_lds_dwordx4 v158, s[0:1]
	s_waitcnt lgkmcnt(8)
	s_barrier
	s_waitcnt lgkmcnt(0)
	v_mfma_f32_16x16x32_bf16 v[124:127], v[128:131], v[162:165], 0
	v_mfma_f32_16x16x32_bf16 v[120:123], v[136:139], v[162:165], 0
	v_mfma_f32_16x16x32_bf16 v[116:119], v[128:131], v[196:199], 0
	v_mfma_f32_16x16x32_bf16 v[112:115], v[136:139], v[196:199], 0
	v_mfma_f32_16x16x32_bf16 v[108:111], v[128:131], v[204:207], 0
	v_mfma_f32_16x16x32_bf16 v[104:107], v[136:139], v[204:207], 0
	v_mfma_f32_16x16x32_bf16 v[100:103], v[128:131], v[220:223], 0
	v_mfma_f32_16x16x32_bf16 v[96:99], v[136:139], v[220:223], 0
	v_mfma_f32_16x16x32_bf16 v[124:127], v[132:135], v[166:169], v[124:127]
	v_mfma_f32_16x16x32_bf16 v[120:123], v[140:143], v[166:169], v[120:123]
	v_mfma_f32_16x16x32_bf16 v[116:119], v[132:135], v[200:203], v[116:119]
	v_mfma_f32_16x16x32_bf16 v[112:115], v[140:143], v[200:203], v[112:115]
	v_mfma_f32_16x16x32_bf16 v[108:111], v[132:135], v[216:219], v[108:111]
	v_mfma_f32_16x16x32_bf16 v[104:107], v[140:143], v[216:219], v[104:107]
	v_mfma_f32_16x16x32_bf16 v[100:103], v[132:135], v[228:231], v[100:103]
	v_mfma_f32_16x16x32_bf16 v[96:99], v[140:143], v[228:231], v[96:99]
	s_barrier
	s_add_i32 s27, 0, 0x14000
	s_add_i32 s37, s47, s76
	v_add_u32_e32 v161, s27, v192
	v_lshl_add_u64 v[176:177], s[50:51], 0, v[148:149]
	s_mov_b32 m0, s37
	ds_read_b128 v[232:235], v161
	ds_read_b128 v[236:239], v161 offset:1024
	ds_read_b128 v[240:243], v161 offset:2048
	ds_read_b128 v[244:247], v161 offset:3072
	global_load_lds_dwordx4 v[176:177], off
	v_lshl_add_u64 v[188:189], s[50:51], 0, v[152:153]
	s_add_i32 m0, s37, 0x2000
	s_nop 0
	global_load_lds_dwordx4 v[188:189], off
	s_barrier
	s_waitcnt lgkmcnt(0)
	v_mfma_f32_16x16x32_bf16 v[92:95], v[232:235], v[162:165], 0
	v_mfma_f32_16x16x32_bf16 v[88:91], v[240:243], v[162:165], 0
	v_mfma_f32_16x16x32_bf16 v[84:87], v[232:235], v[196:199], 0
	v_mfma_f32_16x16x32_bf16 v[80:83], v[240:243], v[196:199], 0
	v_mfma_f32_16x16x32_bf16 v[76:79], v[232:235], v[204:207], 0
	v_mfma_f32_16x16x32_bf16 v[72:75], v[240:243], v[204:207], 0
	v_mfma_f32_16x16x32_bf16 v[68:71], v[232:235], v[220:223], 0
	v_mfma_f32_16x16x32_bf16 v[64:67], v[240:243], v[220:223], 0
	v_mfma_f32_16x16x32_bf16 v[92:95], v[236:239], v[166:169], v[92:95]
	v_mfma_f32_16x16x32_bf16 v[88:91], v[244:247], v[166:169], v[88:91]
	v_mfma_f32_16x16x32_bf16 v[84:87], v[236:239], v[200:203], v[84:87]
	v_mfma_f32_16x16x32_bf16 v[80:83], v[244:247], v[200:203], v[80:83]
	v_mfma_f32_16x16x32_bf16 v[76:79], v[236:239], v[216:219], v[76:79]
	v_mfma_f32_16x16x32_bf16 v[72:75], v[244:247], v[216:219], v[72:75]
	v_mfma_f32_16x16x32_bf16 v[68:71], v[236:239], v[228:231], v[68:71]
	v_mfma_f32_16x16x32_bf16 v[64:67], v[244:247], v[228:231], v[64:67]
	s_barrier
	s_mov_b32 m0, s77
	v_lshl_add_u64 v[224:225], s[52:53], 0, v[146:147]
	ds_read_b128 v[162:165], v194 offset:16384
	ds_read_b128 v[166:169], v194 offset:17408
	ds_read_b128 v[196:199], v194 offset:18432
	ds_read_b128 v[200:203], v194 offset:19456
	ds_read_b128 v[204:207], v194 offset:20480
	ds_read_b128 v[216:219], v194 offset:21504
	ds_read_b128 v[220:223], v194 offset:22528
	ds_read_b128 v[228:231], v194 offset:23552
	global_load_lds_dwordx4 v[224:225], off
	v_lshl_add_u64 v[248:249], s[52:53], 0, v[150:151]
	s_mov_b32 m0, s78
	s_nop 0
	global_load_lds_dwordx4 v[248:249], off
	s_barrier
	s_waitcnt lgkmcnt(0)
	v_mfma_f32_16x16x32_bf16 v[60:63], v[128:131], v[162:165], 0
	v_mfma_f32_16x16x32_bf16 v[56:59], v[136:139], v[162:165], 0
	v_mfma_f32_16x16x32_bf16 v[52:55], v[128:131], v[196:199], 0
	v_mfma_f32_16x16x32_bf16 v[48:51], v[136:139], v[196:199], 0
	v_mfma_f32_16x16x32_bf16 v[44:47], v[128:131], v[204:207], 0
	v_mfma_f32_16x16x32_bf16 v[40:43], v[136:139], v[204:207], 0
	v_mfma_f32_16x16x32_bf16 v[36:39], v[128:131], v[220:223], 0
	v_mfma_f32_16x16x32_bf16 v[32:35], v[136:139], v[220:223], 0
	v_mfma_f32_16x16x32_bf16 v[60:63], v[132:135], v[166:169], v[60:63]
	v_mfma_f32_16x16x32_bf16 v[56:59], v[140:143], v[166:169], v[56:59]
	v_mfma_f32_16x16x32_bf16 v[52:55], v[132:135], v[200:203], v[52:55]
	v_mfma_f32_16x16x32_bf16 v[48:51], v[140:143], v[200:203], v[48:51]
	v_mfma_f32_16x16x32_bf16 v[44:47], v[132:135], v[216:219], v[44:47]
	v_mfma_f32_16x16x32_bf16 v[40:43], v[140:143], v[216:219], v[40:43]
	v_mfma_f32_16x16x32_bf16 v[36:39], v[132:135], v[228:231], v[36:39]
	v_mfma_f32_16x16x32_bf16 v[32:35], v[140:143], v[228:231], v[32:35]
	s_barrier
	s_add_u32 s56, s50, 0x40000
	s_addc_u32 s57, s51, 0
	s_add_i32 s27, s27, s76
	s_mov_b32 m0, s27
	s_nop 0
	global_load_lds_dwordx4 v148, s[56:57]
	s_add_i32 m0, s27, 0x2000
	s_nop 0
	global_load_lds_dwordx4 v152, s[56:57]
	s_waitcnt vmcnt(6)
	s_barrier
	v_mfma_f32_16x16x32_bf16 v[28:31], v[232:235], v[162:165], 0
	v_mfma_f32_16x16x32_bf16 v[24:27], v[240:243], v[162:165], 0
	v_mfma_f32_16x16x32_bf16 v[20:23], v[232:235], v[196:199], 0
	v_mfma_f32_16x16x32_bf16 v[16:19], v[240:243], v[196:199], 0
	v_mfma_f32_16x16x32_bf16 v[12:15], v[232:235], v[204:207], 0
	v_mfma_f32_16x16x32_bf16 v[8:11], v[240:243], v[204:207], 0
	v_mfma_f32_16x16x32_bf16 v[4:7], v[232:235], v[220:223], 0
	v_mfma_f32_16x16x32_bf16 v[0:3], v[240:243], v[220:223], 0
	v_mfma_f32_16x16x32_bf16 v[28:31], v[236:239], v[166:169], v[28:31]
	v_mfma_f32_16x16x32_bf16 v[24:27], v[244:247], v[166:169], v[24:27]
	v_mfma_f32_16x16x32_bf16 v[20:23], v[236:239], v[200:203], v[20:23]
	v_mfma_f32_16x16x32_bf16 v[16:19], v[244:247], v[200:203], v[16:19]
	v_mfma_f32_16x16x32_bf16 v[12:15], v[236:239], v[216:219], v[12:15]
	v_mfma_f32_16x16x32_bf16 v[8:11], v[244:247], v[216:219], v[8:11]
	v_mfma_f32_16x16x32_bf16 v[4:7], v[236:239], v[228:231], v[4:7]
	v_mfma_f32_16x16x32_bf16 v[0:3], v[244:247], v[228:231], v[0:3]
	s_barrier
	s_add_i32 s27, 0, 0x18000
	v_add_u32_e32 v140, s27, v192
	ds_read_b128 v[128:131], v140
	ds_read_b128 v[132:135], v140 offset:1024
	ds_read_b128 v[136:139], v140 offset:2048
	ds_read_b128 v[140:143], v140 offset:3072
	s_add_u32 s52, s52, 0x40000
	s_addc_u32 s53, s53, 0
	s_mov_b32 m0, s81
	ds_read_b128 v[162:165], v194 offset:32768
	ds_read_b128 v[166:169], v194 offset:33792
	ds_read_b128 v[196:199], v194 offset:34816
	ds_read_b128 v[200:203], v194 offset:35840
	ds_read_b128 v[204:207], v194 offset:36864
	ds_read_b128 v[216:219], v194 offset:37888
	ds_read_b128 v[220:223], v194 offset:38912
	ds_read_b128 v[228:231], v194 offset:39936
	global_load_lds_dwordx4 v146, s[52:53]
	s_mov_b32 m0, s82
	s_nop 0
	global_load_lds_dwordx4 v150, s[52:53]
	s_waitcnt lgkmcnt(8)
	s_barrier
	s_waitcnt lgkmcnt(0)
	v_mfma_f32_16x16x32_bf16 v[124:127], v[128:131], v[162:165], v[124:127]
	v_mfma_f32_16x16x32_bf16 v[120:123], v[136:139], v[162:165], v[120:123]
	v_mfma_f32_16x16x32_bf16 v[116:119], v[128:131], v[196:199], v[116:119]
	v_mfma_f32_16x16x32_bf16 v[112:115], v[136:139], v[196:199], v[112:115]
	v_mfma_f32_16x16x32_bf16 v[108:111], v[128:131], v[204:207], v[108:111]
	v_mfma_f32_16x16x32_bf16 v[104:107], v[136:139], v[204:207], v[104:107]
	v_mfma_f32_16x16x32_bf16 v[100:103], v[128:131], v[220:223], v[100:103]
	v_mfma_f32_16x16x32_bf16 v[96:99], v[136:139], v[220:223], v[96:99]
	v_mfma_f32_16x16x32_bf16 v[124:127], v[132:135], v[166:169], v[124:127]
	v_mfma_f32_16x16x32_bf16 v[120:123], v[140:143], v[166:169], v[120:123]
	v_mfma_f32_16x16x32_bf16 v[116:119], v[132:135], v[200:203], v[116:119]
	v_mfma_f32_16x16x32_bf16 v[112:115], v[140:143], v[200:203], v[112:115]
	v_mfma_f32_16x16x32_bf16 v[108:111], v[132:135], v[216:219], v[108:111]
	v_mfma_f32_16x16x32_bf16 v[104:107], v[140:143], v[216:219], v[104:107]
	v_mfma_f32_16x16x32_bf16 v[100:103], v[132:135], v[228:231], v[100:103]
	v_mfma_f32_16x16x32_bf16 v[96:99], v[140:143], v[228:231], v[96:99]
	s_barrier
	s_add_i32 s37, 0, 0x1c000
	s_add_i32 s27, s27, s76
	v_add_u32_e32 v161, s37, v192
	v_lshl_add_u64 v[176:177], v[176:177], 0, s[18:19]
	s_mov_b32 m0, s27
	ds_read_b128 v[232:235], v161
	ds_read_b128 v[236:239], v161 offset:1024
	ds_read_b128 v[240:243], v161 offset:2048
	ds_read_b128 v[244:247], v161 offset:3072
	global_load_lds_dwordx4 v[176:177], off
	v_lshl_add_u64 v[176:177], v[188:189], 0, s[18:19]
	s_add_i32 m0, s27, 0x2000
	s_nop 0
	global_load_lds_dwordx4 v[176:177], off
	s_barrier
	s_waitcnt lgkmcnt(0)
	v_mfma_f32_16x16x32_bf16 v[92:95], v[232:235], v[162:165], v[92:95]
	v_mfma_f32_16x16x32_bf16 v[88:91], v[240:243], v[162:165], v[88:91]
	v_mfma_f32_16x16x32_bf16 v[84:87], v[232:235], v[196:199], v[84:87]
	v_mfma_f32_16x16x32_bf16 v[80:83], v[240:243], v[196:199], v[80:83]
	v_mfma_f32_16x16x32_bf16 v[76:79], v[232:235], v[204:207], v[76:79]
	v_mfma_f32_16x16x32_bf16 v[72:75], v[240:243], v[204:207], v[72:75]
	v_mfma_f32_16x16x32_bf16 v[68:71], v[232:235], v[220:223], v[68:71]
	v_mfma_f32_16x16x32_bf16 v[64:67], v[240:243], v[220:223], v[64:67]
	v_mfma_f32_16x16x32_bf16 v[92:95], v[236:239], v[166:169], v[92:95]
	v_mfma_f32_16x16x32_bf16 v[88:91], v[244:247], v[166:169], v[88:91]
	v_mfma_f32_16x16x32_bf16 v[84:87], v[236:239], v[200:203], v[84:87]
	v_mfma_f32_16x16x32_bf16 v[80:83], v[244:247], v[200:203], v[80:83]
	v_mfma_f32_16x16x32_bf16 v[76:79], v[236:239], v[216:219], v[76:79]
	v_mfma_f32_16x16x32_bf16 v[72:75], v[244:247], v[216:219], v[72:75]
	v_mfma_f32_16x16x32_bf16 v[68:71], v[236:239], v[228:231], v[68:71]
	v_mfma_f32_16x16x32_bf16 v[64:67], v[244:247], v[228:231], v[64:67]
	s_barrier
	s_mov_b32 m0, s80
	v_lshl_add_u64 v[176:177], v[224:225], 0, s[18:19]
	ds_read_b128 v[162:165], v194 offset:49152
	ds_read_b128 v[166:169], v194 offset:50176
	ds_read_b128 v[196:199], v194 offset:51200
	ds_read_b128 v[200:203], v194 offset:52224
	ds_read_b128 v[204:207], v194 offset:53248
	ds_read_b128 v[216:219], v194 offset:54272
	ds_read_b128 v[220:223], v194 offset:55296
	ds_read_b128 v[228:231], v194 offset:56320
	global_load_lds_dwordx4 v[176:177], off
	v_lshl_add_u64 v[176:177], v[248:249], 0, s[18:19]
	s_mov_b32 m0, s83
	s_nop 0
	global_load_lds_dwordx4 v[176:177], off
	s_barrier
	s_waitcnt lgkmcnt(0)
	v_mfma_f32_16x16x32_bf16 v[60:63], v[128:131], v[162:165], v[60:63]
	v_mfma_f32_16x16x32_bf16 v[56:59], v[136:139], v[162:165], v[56:59]
	v_mfma_f32_16x16x32_bf16 v[52:55], v[128:131], v[196:199], v[52:55]
	v_mfma_f32_16x16x32_bf16 v[48:51], v[136:139], v[196:199], v[48:51]
	v_mfma_f32_16x16x32_bf16 v[44:47], v[128:131], v[204:207], v[44:47]
	v_mfma_f32_16x16x32_bf16 v[40:43], v[136:139], v[204:207], v[40:43]
	v_mfma_f32_16x16x32_bf16 v[36:39], v[128:131], v[220:223], v[36:39]
	v_mfma_f32_16x16x32_bf16 v[32:35], v[136:139], v[220:223], v[32:35]
	v_mfma_f32_16x16x32_bf16 v[60:63], v[132:135], v[166:169], v[60:63]
	v_mfma_f32_16x16x32_bf16 v[56:59], v[140:143], v[166:169], v[56:59]
	v_mfma_f32_16x16x32_bf16 v[52:55], v[132:135], v[200:203], v[52:55]
	v_mfma_f32_16x16x32_bf16 v[48:51], v[140:143], v[200:203], v[48:51]
	v_mfma_f32_16x16x32_bf16 v[44:47], v[132:135], v[216:219], v[44:47]
	v_mfma_f32_16x16x32_bf16 v[40:43], v[140:143], v[216:219], v[40:43]
	v_mfma_f32_16x16x32_bf16 v[36:39], v[132:135], v[228:231], v[36:39]
	v_mfma_f32_16x16x32_bf16 v[32:35], v[140:143], v[228:231], v[32:35]
	s_barrier
	s_add_u32 s50, s50, 0x40080
	s_addc_u32 s51, s51, 0
	s_add_i32 s27, s37, s76
	s_mov_b32 m0, s27
	s_nop 0
	global_load_lds_dwordx4 v148, s[50:51]
	s_add_i32 m0, s27, 0x2000
	s_nop 0
	global_load_lds_dwordx4 v152, s[50:51]
	s_waitcnt vmcnt(6)
	s_barrier
	v_mfma_f32_16x16x32_bf16 v[28:31], v[232:235], v[162:165], v[28:31]
	v_mfma_f32_16x16x32_bf16 v[24:27], v[240:243], v[162:165], v[24:27]
	v_mfma_f32_16x16x32_bf16 v[20:23], v[232:235], v[196:199], v[20:23]
	v_mfma_f32_16x16x32_bf16 v[16:19], v[240:243], v[196:199], v[16:19]
	v_mfma_f32_16x16x32_bf16 v[12:15], v[232:235], v[204:207], v[12:15]
	v_mfma_f32_16x16x32_bf16 v[8:11], v[240:243], v[204:207], v[8:11]
	v_mfma_f32_16x16x32_bf16 v[4:7], v[232:235], v[220:223], v[4:7]
	v_mfma_f32_16x16x32_bf16 v[0:3], v[240:243], v[220:223], v[0:3]
	v_mfma_f32_16x16x32_bf16 v[28:31], v[236:239], v[166:169], v[28:31]
	v_mfma_f32_16x16x32_bf16 v[24:27], v[244:247], v[166:169], v[24:27]
	v_mfma_f32_16x16x32_bf16 v[20:23], v[236:239], v[200:203], v[20:23]
	v_mfma_f32_16x16x32_bf16 v[16:19], v[244:247], v[200:203], v[16:19]
	v_mfma_f32_16x16x32_bf16 v[12:15], v[236:239], v[216:219], v[12:15]
	v_mfma_f32_16x16x32_bf16 v[8:11], v[244:247], v[216:219], v[8:11]
	v_mfma_f32_16x16x32_bf16 v[4:7], v[236:239], v[228:231], v[4:7]
	v_mfma_f32_16x16x32_bf16 v[0:3], v[244:247], v[228:231], v[0:3]
	s_barrier
	s_add_i32 s36, s36, 2
	s_add_u32 s0, s0, 0x100
	s_addc_u32 s1, s1, 0
	s_add_u32 s34, s34, 0x100
	s_addc_u32 s35, s35, 0
	s_cmp_gt_u32 s36, 13
.LBB0_351:
	s_add_u32 s27, s0, 0xfffc0080
	s_addc_u32 s37, s1, -1
	s_add_i32 s47, 0, 0x10000
	v_add_u32_e32 v140, s47, v192
	ds_read_b128 v[128:131], v140
	ds_read_b128 v[132:135], v140 offset:1024
	ds_read_b128 v[136:139], v140 offset:2048
	ds_read_b128 v[140:143], v140 offset:3072
	s_cmp_eq_u32 s36, 12
	s_cselect_b32 s53, s25, s37
	s_cselect_b32 s52, s30, s27
	s_cselect_b32 s51, s31, s35
	s_cselect_b32 s50, s33, s34
	s_add_i32 m0, s77, 0xc000
	ds_read_b128 v[162:165], v194
	ds_read_b128 v[166:169], v194 offset:1024
	ds_read_b128 v[196:199], v194 offset:2048
	ds_read_b128 v[200:203], v194 offset:3072
	ds_read_b128 v[204:207], v194 offset:4096
	ds_read_b128 v[216:219], v194 offset:5120
	ds_read_b128 v[220:223], v194 offset:6144
	ds_read_b128 v[228:231], v194 offset:7168
	global_load_lds_dwordx4 v156, s[0:1]
	s_add_i32 m0, s77, 0xe000
	s_nop 0
	global_load_lds_dwordx4 v158, s[0:1]
	s_waitcnt lgkmcnt(8)
	s_barrier
	s_waitcnt lgkmcnt(0)
	v_mfma_f32_16x16x32_bf16 v[124:127], v[128:131], v[162:165], v[124:127]
	v_mfma_f32_16x16x32_bf16 v[120:123], v[136:139], v[162:165], v[120:123]
	v_mfma_f32_16x16x32_bf16 v[116:119], v[128:131], v[196:199], v[116:119]
	v_mfma_f32_16x16x32_bf16 v[112:115], v[136:139], v[196:199], v[112:115]
	v_mfma_f32_16x16x32_bf16 v[108:111], v[128:131], v[204:207], v[108:111]
	v_mfma_f32_16x16x32_bf16 v[104:107], v[136:139], v[204:207], v[104:107]
	v_mfma_f32_16x16x32_bf16 v[100:103], v[128:131], v[220:223], v[100:103]
	v_mfma_f32_16x16x32_bf16 v[96:99], v[136:139], v[220:223], v[96:99]
	v_mfma_f32_16x16x32_bf16 v[124:127], v[132:135], v[166:169], v[124:127]
	v_mfma_f32_16x16x32_bf16 v[120:123], v[140:143], v[166:169], v[120:123]
	v_mfma_f32_16x16x32_bf16 v[116:119], v[132:135], v[200:203], v[116:119]
	v_mfma_f32_16x16x32_bf16 v[112:115], v[140:143], v[200:203], v[112:115]
	v_mfma_f32_16x16x32_bf16 v[108:111], v[132:135], v[216:219], v[108:111]
	v_mfma_f32_16x16x32_bf16 v[104:107], v[140:143], v[216:219], v[104:107]
	v_mfma_f32_16x16x32_bf16 v[100:103], v[132:135], v[228:231], v[100:103]
	v_mfma_f32_16x16x32_bf16 v[96:99], v[140:143], v[228:231], v[96:99]
	s_barrier
	s_add_i32 s27, 0, 0x14000
	s_add_i32 s37, s47, s76
	v_add_u32_e32 v161, s27, v192
	v_lshl_add_u64 v[176:177], s[50:51], 0, v[148:149]
	s_mov_b32 m0, s37
	ds_read_b128 v[232:235], v161
	ds_read_b128 v[236:239], v161 offset:1024
	ds_read_b128 v[240:243], v161 offset:2048
	ds_read_b128 v[244:247], v161 offset:3072
	global_load_lds_dwordx4 v[176:177], off
	v_lshl_add_u64 v[188:189], s[50:51], 0, v[152:153]
	s_add_i32 m0, s37, 0x2000
	s_nop 0
	global_load_lds_dwordx4 v[188:189], off
	s_barrier
	s_waitcnt lgkmcnt(0)
	v_mfma_f32_16x16x32_bf16 v[92:95], v[232:235], v[162:165], v[92:95]
	v_mfma_f32_16x16x32_bf16 v[88:91], v[240:243], v[162:165], v[88:91]
	v_mfma_f32_16x16x32_bf16 v[84:87], v[232:235], v[196:199], v[84:87]
	v_mfma_f32_16x16x32_bf16 v[80:83], v[240:243], v[196:199], v[80:83]
	v_mfma_f32_16x16x32_bf16 v[76:79], v[232:235], v[204:207], v[76:79]
	v_mfma_f32_16x16x32_bf16 v[72:75], v[240:243], v[204:207], v[72:75]
	v_mfma_f32_16x16x32_bf16 v[68:71], v[232:235], v[220:223], v[68:71]
	v_mfma_f32_16x16x32_bf16 v[64:67], v[240:243], v[220:223], v[64:67]
	v_mfma_f32_16x16x32_bf16 v[92:95], v[236:239], v[166:169], v[92:95]
	v_mfma_f32_16x16x32_bf16 v[88:91], v[244:247], v[166:169], v[88:91]
	v_mfma_f32_16x16x32_bf16 v[84:87], v[236:239], v[200:203], v[84:87]
	v_mfma_f32_16x16x32_bf16 v[80:83], v[244:247], v[200:203], v[80:83]
	v_mfma_f32_16x16x32_bf16 v[76:79], v[236:239], v[216:219], v[76:79]
	v_mfma_f32_16x16x32_bf16 v[72:75], v[244:247], v[216:219], v[72:75]
	v_mfma_f32_16x16x32_bf16 v[68:71], v[236:239], v[228:231], v[68:71]
	v_mfma_f32_16x16x32_bf16 v[64:67], v[244:247], v[228:231], v[64:67]
	s_barrier
	s_mov_b32 m0, s77
	v_lshl_add_u64 v[224:225], s[52:53], 0, v[146:147]
	ds_read_b128 v[162:165], v194 offset:16384
	ds_read_b128 v[166:169], v194 offset:17408
	ds_read_b128 v[196:199], v194 offset:18432
	ds_read_b128 v[200:203], v194 offset:19456
	ds_read_b128 v[204:207], v194 offset:20480
	ds_read_b128 v[216:219], v194 offset:21504
	ds_read_b128 v[220:223], v194 offset:22528
	ds_read_b128 v[228:231], v194 offset:23552
	global_load_lds_dwordx4 v[224:225], off
	v_lshl_add_u64 v[248:249], s[52:53], 0, v[150:151]
	s_mov_b32 m0, s78
	s_nop 0
	global_load_lds_dwordx4 v[248:249], off
	s_barrier
	s_waitcnt lgkmcnt(0)
	v_mfma_f32_16x16x32_bf16 v[60:63], v[128:131], v[162:165], v[60:63]
	v_mfma_f32_16x16x32_bf16 v[56:59], v[136:139], v[162:165], v[56:59]
	v_mfma_f32_16x16x32_bf16 v[52:55], v[128:131], v[196:199], v[52:55]
	v_mfma_f32_16x16x32_bf16 v[48:51], v[136:139], v[196:199], v[48:51]
	v_mfma_f32_16x16x32_bf16 v[44:47], v[128:131], v[204:207], v[44:47]
	v_mfma_f32_16x16x32_bf16 v[40:43], v[136:139], v[204:207], v[40:43]
	v_mfma_f32_16x16x32_bf16 v[36:39], v[128:131], v[220:223], v[36:39]
	v_mfma_f32_16x16x32_bf16 v[32:35], v[136:139], v[220:223], v[32:35]
	v_mfma_f32_16x16x32_bf16 v[60:63], v[132:135], v[166:169], v[60:63]
	v_mfma_f32_16x16x32_bf16 v[56:59], v[140:143], v[166:169], v[56:59]
	v_mfma_f32_16x16x32_bf16 v[52:55], v[132:135], v[200:203], v[52:55]
	v_mfma_f32_16x16x32_bf16 v[48:51], v[140:143], v[200:203], v[48:51]
	v_mfma_f32_16x16x32_bf16 v[44:47], v[132:135], v[216:219], v[44:47]
	v_mfma_f32_16x16x32_bf16 v[40:43], v[140:143], v[216:219], v[40:43]
	v_mfma_f32_16x16x32_bf16 v[36:39], v[132:135], v[228:231], v[36:39]
	v_mfma_f32_16x16x32_bf16 v[32:35], v[140:143], v[228:231], v[32:35]
	s_barrier
	s_add_u32 s56, s50, 0x40000
	s_addc_u32 s57, s51, 0
	s_add_i32 s27, s27, s76
	s_mov_b32 m0, s27
	s_nop 0
	global_load_lds_dwordx4 v148, s[56:57]
	s_add_i32 m0, s27, 0x2000
	s_nop 0
	global_load_lds_dwordx4 v152, s[56:57]
	s_waitcnt vmcnt(6)
	s_barrier
	v_mfma_f32_16x16x32_bf16 v[28:31], v[232:235], v[162:165], v[28:31]
	v_mfma_f32_16x16x32_bf16 v[24:27], v[240:243], v[162:165], v[24:27]
	v_mfma_f32_16x16x32_bf16 v[20:23], v[232:235], v[196:199], v[20:23]
	v_mfma_f32_16x16x32_bf16 v[16:19], v[240:243], v[196:199], v[16:19]
	v_mfma_f32_16x16x32_bf16 v[12:15], v[232:235], v[204:207], v[12:15]
	v_mfma_f32_16x16x32_bf16 v[8:11], v[240:243], v[204:207], v[8:11]
	v_mfma_f32_16x16x32_bf16 v[4:7], v[232:235], v[220:223], v[4:7]
	v_mfma_f32_16x16x32_bf16 v[0:3], v[240:243], v[220:223], v[0:3]
	v_mfma_f32_16x16x32_bf16 v[28:31], v[236:239], v[166:169], v[28:31]
	v_mfma_f32_16x16x32_bf16 v[24:27], v[244:247], v[166:169], v[24:27]
	v_mfma_f32_16x16x32_bf16 v[20:23], v[236:239], v[200:203], v[20:23]
	v_mfma_f32_16x16x32_bf16 v[16:19], v[244:247], v[200:203], v[16:19]
	v_mfma_f32_16x16x32_bf16 v[12:15], v[236:239], v[216:219], v[12:15]
	v_mfma_f32_16x16x32_bf16 v[8:11], v[244:247], v[216:219], v[8:11]
	v_mfma_f32_16x16x32_bf16 v[4:7], v[236:239], v[228:231], v[4:7]
	v_mfma_f32_16x16x32_bf16 v[0:3], v[244:247], v[228:231], v[0:3]
	s_barrier
	s_add_i32 s27, 0, 0x18000
	v_add_u32_e32 v140, s27, v192
	ds_read_b128 v[128:131], v140
	ds_read_b128 v[132:135], v140 offset:1024
	ds_read_b128 v[136:139], v140 offset:2048
	ds_read_b128 v[140:143], v140 offset:3072
	s_add_u32 s52, s52, 0x40000
	s_addc_u32 s53, s53, 0
	s_mov_b32 m0, s81
	ds_read_b128 v[162:165], v194 offset:32768
	ds_read_b128 v[166:169], v194 offset:33792
	ds_read_b128 v[196:199], v194 offset:34816
	ds_read_b128 v[200:203], v194 offset:35840
	ds_read_b128 v[204:207], v194 offset:36864
	ds_read_b128 v[216:219], v194 offset:37888
	ds_read_b128 v[220:223], v194 offset:38912
	ds_read_b128 v[228:231], v194 offset:39936
	global_load_lds_dwordx4 v146, s[52:53]
	s_mov_b32 m0, s82
	s_nop 0
	global_load_lds_dwordx4 v150, s[52:53]
	s_waitcnt lgkmcnt(8)
	s_barrier
	s_waitcnt lgkmcnt(0)
	v_mfma_f32_16x16x32_bf16 v[124:127], v[128:131], v[162:165], v[124:127]
	v_mfma_f32_16x16x32_bf16 v[120:123], v[136:139], v[162:165], v[120:123]
	v_mfma_f32_16x16x32_bf16 v[116:119], v[128:131], v[196:199], v[116:119]
	v_mfma_f32_16x16x32_bf16 v[112:115], v[136:139], v[196:199], v[112:115]
	v_mfma_f32_16x16x32_bf16 v[108:111], v[128:131], v[204:207], v[108:111]
	v_mfma_f32_16x16x32_bf16 v[104:107], v[136:139], v[204:207], v[104:107]
	v_mfma_f32_16x16x32_bf16 v[100:103], v[128:131], v[220:223], v[100:103]
	v_mfma_f32_16x16x32_bf16 v[96:99], v[136:139], v[220:223], v[96:99]
	v_mfma_f32_16x16x32_bf16 v[124:127], v[132:135], v[166:169], v[124:127]
	v_mfma_f32_16x16x32_bf16 v[120:123], v[140:143], v[166:169], v[120:123]
	v_mfma_f32_16x16x32_bf16 v[116:119], v[132:135], v[200:203], v[116:119]
	v_mfma_f32_16x16x32_bf16 v[112:115], v[140:143], v[200:203], v[112:115]
	v_mfma_f32_16x16x32_bf16 v[108:111], v[132:135], v[216:219], v[108:111]
	v_mfma_f32_16x16x32_bf16 v[104:107], v[140:143], v[216:219], v[104:107]
	v_mfma_f32_16x16x32_bf16 v[100:103], v[132:135], v[228:231], v[100:103]
	v_mfma_f32_16x16x32_bf16 v[96:99], v[140:143], v[228:231], v[96:99]
	s_barrier
	s_add_i32 s37, 0, 0x1c000
	s_add_i32 s27, s27, s76
	v_add_u32_e32 v161, s37, v192
	v_lshl_add_u64 v[176:177], v[176:177], 0, s[18:19]
	s_mov_b32 m0, s27
	ds_read_b128 v[232:235], v161
	ds_read_b128 v[236:239], v161 offset:1024
	ds_read_b128 v[240:243], v161 offset:2048
	ds_read_b128 v[244:247], v161 offset:3072
	global_load_lds_dwordx4 v[176:177], off
	v_lshl_add_u64 v[176:177], v[188:189], 0, s[18:19]
	s_add_i32 m0, s27, 0x2000
	s_nop 0
	global_load_lds_dwordx4 v[176:177], off
	s_barrier
	s_waitcnt lgkmcnt(0)
	v_mfma_f32_16x16x32_bf16 v[92:95], v[232:235], v[162:165], v[92:95]
	v_mfma_f32_16x16x32_bf16 v[88:91], v[240:243], v[162:165], v[88:91]
	v_mfma_f32_16x16x32_bf16 v[84:87], v[232:235], v[196:199], v[84:87]
	v_mfma_f32_16x16x32_bf16 v[80:83], v[240:243], v[196:199], v[80:83]
	v_mfma_f32_16x16x32_bf16 v[76:79], v[232:235], v[204:207], v[76:79]
	v_mfma_f32_16x16x32_bf16 v[72:75], v[240:243], v[204:207], v[72:75]
	v_mfma_f32_16x16x32_bf16 v[68:71], v[232:235], v[220:223], v[68:71]
	v_mfma_f32_16x16x32_bf16 v[64:67], v[240:243], v[220:223], v[64:67]
	v_mfma_f32_16x16x32_bf16 v[92:95], v[236:239], v[166:169], v[92:95]
	v_mfma_f32_16x16x32_bf16 v[88:91], v[244:247], v[166:169], v[88:91]
	v_mfma_f32_16x16x32_bf16 v[84:87], v[236:239], v[200:203], v[84:87]
	v_mfma_f32_16x16x32_bf16 v[80:83], v[244:247], v[200:203], v[80:83]
	v_mfma_f32_16x16x32_bf16 v[76:79], v[236:239], v[216:219], v[76:79]
	v_mfma_f32_16x16x32_bf16 v[72:75], v[244:247], v[216:219], v[72:75]
	v_mfma_f32_16x16x32_bf16 v[68:71], v[236:239], v[228:231], v[68:71]
	v_mfma_f32_16x16x32_bf16 v[64:67], v[244:247], v[228:231], v[64:67]
	s_barrier
	s_mov_b32 m0, s80
	v_lshl_add_u64 v[176:177], v[224:225], 0, s[18:19]
	ds_read_b128 v[162:165], v194 offset:49152
	ds_read_b128 v[166:169], v194 offset:50176
	ds_read_b128 v[196:199], v194 offset:51200
	ds_read_b128 v[200:203], v194 offset:52224
	ds_read_b128 v[204:207], v194 offset:53248
	ds_read_b128 v[216:219], v194 offset:54272
	ds_read_b128 v[220:223], v194 offset:55296
	ds_read_b128 v[228:231], v194 offset:56320
	global_load_lds_dwordx4 v[176:177], off
	v_lshl_add_u64 v[176:177], v[248:249], 0, s[18:19]
	s_mov_b32 m0, s83
	s_nop 0
	global_load_lds_dwordx4 v[176:177], off
	s_barrier
	s_waitcnt lgkmcnt(0)
	v_mfma_f32_16x16x32_bf16 v[60:63], v[128:131], v[162:165], v[60:63]
	v_mfma_f32_16x16x32_bf16 v[56:59], v[136:139], v[162:165], v[56:59]
	v_mfma_f32_16x16x32_bf16 v[52:55], v[128:131], v[196:199], v[52:55]
	v_mfma_f32_16x16x32_bf16 v[48:51], v[136:139], v[196:199], v[48:51]
	v_mfma_f32_16x16x32_bf16 v[44:47], v[128:131], v[204:207], v[44:47]
	v_mfma_f32_16x16x32_bf16 v[40:43], v[136:139], v[204:207], v[40:43]
	v_mfma_f32_16x16x32_bf16 v[36:39], v[128:131], v[220:223], v[36:39]
	v_mfma_f32_16x16x32_bf16 v[32:35], v[136:139], v[220:223], v[32:35]
	v_mfma_f32_16x16x32_bf16 v[60:63], v[132:135], v[166:169], v[60:63]
	v_mfma_f32_16x16x32_bf16 v[56:59], v[140:143], v[166:169], v[56:59]
	v_mfma_f32_16x16x32_bf16 v[52:55], v[132:135], v[200:203], v[52:55]
	v_mfma_f32_16x16x32_bf16 v[48:51], v[140:143], v[200:203], v[48:51]
	v_mfma_f32_16x16x32_bf16 v[44:47], v[132:135], v[216:219], v[44:47]
	v_mfma_f32_16x16x32_bf16 v[40:43], v[140:143], v[216:219], v[40:43]
	v_mfma_f32_16x16x32_bf16 v[36:39], v[132:135], v[228:231], v[36:39]
	v_mfma_f32_16x16x32_bf16 v[32:35], v[140:143], v[228:231], v[32:35]
	s_barrier
	s_add_u32 s50, s50, 0x40080
	s_addc_u32 s51, s51, 0
	s_add_i32 s27, s37, s76
	s_mov_b32 m0, s27
	s_nop 0
	global_load_lds_dwordx4 v148, s[50:51]
	s_add_i32 m0, s27, 0x2000
	s_nop 0
	global_load_lds_dwordx4 v152, s[50:51]
	s_waitcnt vmcnt(6)
	s_barrier
	v_mfma_f32_16x16x32_bf16 v[28:31], v[232:235], v[162:165], v[28:31]
	v_mfma_f32_16x16x32_bf16 v[24:27], v[240:243], v[162:165], v[24:27]
	v_mfma_f32_16x16x32_bf16 v[20:23], v[232:235], v[196:199], v[20:23]
	v_mfma_f32_16x16x32_bf16 v[16:19], v[240:243], v[196:199], v[16:19]
	v_mfma_f32_16x16x32_bf16 v[12:15], v[232:235], v[204:207], v[12:15]
	v_mfma_f32_16x16x32_bf16 v[8:11], v[240:243], v[204:207], v[8:11]
	v_mfma_f32_16x16x32_bf16 v[4:7], v[232:235], v[220:223], v[4:7]
	v_mfma_f32_16x16x32_bf16 v[0:3], v[240:243], v[220:223], v[0:3]
	v_mfma_f32_16x16x32_bf16 v[28:31], v[236:239], v[166:169], v[28:31]
	v_mfma_f32_16x16x32_bf16 v[24:27], v[244:247], v[166:169], v[24:27]
	v_mfma_f32_16x16x32_bf16 v[20:23], v[236:239], v[200:203], v[20:23]
	v_mfma_f32_16x16x32_bf16 v[16:19], v[244:247], v[200:203], v[16:19]
	v_mfma_f32_16x16x32_bf16 v[12:15], v[236:239], v[216:219], v[12:15]
	v_mfma_f32_16x16x32_bf16 v[8:11], v[244:247], v[216:219], v[8:11]
	v_mfma_f32_16x16x32_bf16 v[4:7], v[236:239], v[228:231], v[4:7]
	v_mfma_f32_16x16x32_bf16 v[0:3], v[244:247], v[228:231], v[0:3]
	s_barrier
	s_add_i32 s36, s36, 2
	s_add_u32 s0, s0, 0x100
	s_addc_u32 s1, s1, 0
	s_add_u32 s34, s34, 0x100
	s_addc_u32 s35, s35, 0
	s_cmp_gt_u32 s36, 13
	s_cbranch_scc0 .LBB0_351
	s_lshl_b32 s0, s11, 8
	s_or_b32 s50, s0, s79
	s_ashr_i32 s51, s50, 31
	v_lshl_add_u64 v[140:141], s[50:51], 3, v[154:155]
	global_load_dwordx4 v[128:131], v[140:141], off offset:48
	global_load_dwordx4 v[132:135], v[140:141], off offset:32
	global_load_dwordx4 v[136:139], v[140:141], off offset:16
	global_load_dwordx4 v[162:165], v[140:141], off
	s_mov_b32 s34, 0x35800000
	s_mov_b32 s0, 0x358637bd
	v_mov_b64_e32 v[168:169], s[0:1]
	s_mov_b32 s30, 0x45800000
	s_cmp_lt_u32 s10, 2
	s_waitcnt vmcnt(0)
	v_ffbh_u32_e32 v142, v165
	v_min_u32_e32 v161, 32, v142
	v_lshlrev_b64 v[142:143], v161, v[164:165]
	v_min_u32_e32 v142, 1, v142
	v_or_b32_e32 v142, v143, v142
	v_cvt_f32_u32_e32 v142, v142
	v_sub_u32_e32 v143, 32, v161
	v_ldexp_f32 v143, v142, v143
	v_ffbh_u32_e32 v142, v163
	v_min_u32_e32 v142, 32, v142
	v_lshlrev_b64 v[162:163], v142, v[162:163]
	v_min_u32_e32 v161, 1, v162
	v_or_b32_e32 v161, v163, v161
	v_cvt_f32_u32_e32 v161, v161
	v_sub_u32_e32 v142, 32, v142
	v_ldexp_f32 v142, v161, v142
	v_pk_mul_f32 v[142:143], v[142:143], s[34:35] op_sel_hi:[1,0]
	s_nop 0
	v_pk_fma_f32 v[142:143], v[142:143], s[2:3], v[168:169] op_sel_hi:[1,0,0]
	s_nop 0
	v_mul_f32_e32 v161, 0x4b800000, v142
	v_cmp_gt_f32_e64 s[0:1], s89, v142
	v_cmp_gt_f32_e32 vcc, s89, v143
	s_nop 0
	v_cndmask_b32_e64 v142, v142, v161, s[0:1]
	v_mul_f32_e32 v161, 0x4b800000, v143
	v_cndmask_b32_e32 v143, v143, v161, vcc
	v_rsq_f32_e32 v142, v142
	v_rsq_f32_e32 v143, v143
	s_nop 0
	v_pk_mul_f32 v[162:163], v[142:143], s[30:31] op_sel_hi:[1,0]
	s_nop 0
	v_cndmask_b32_e64 v166, v142, v162, s[0:1]
	v_ffbh_u32_e32 v142, v139
	v_min_u32_e32 v142, 32, v142
	v_lshlrev_b64 v[138:139], v142, v[138:139]
	v_min_u32_e32 v138, 1, v138
	v_or_b32_e32 v138, v139, v138
	v_cvt_f32_u32_e32 v138, v138
	v_sub_u32_e32 v139, 32, v142
	v_cndmask_b32_e32 v167, v143, v163, vcc
	v_pk_mul_f32 v[60:61], v[60:61], v[166:167]
	v_ldexp_f32 v139, v138, v139
	v_ffbh_u32_e32 v138, v137
	v_min_u32_e32 v138, 32, v138
	v_lshlrev_b64 v[136:137], v138, v[136:137]
	v_min_u32_e32 v136, 1, v136
	v_or_b32_e32 v136, v137, v136
	v_cvt_f32_u32_e32 v136, v136
	v_sub_u32_e32 v137, 32, v138
	v_pk_mul_f32 v[52:53], v[52:53], v[166:167]
	v_pk_mul_f32 v[44:45], v[44:45], v[166:167]
	v_ldexp_f32 v138, v136, v137
	v_pk_mul_f32 v[136:137], v[138:139], s[34:35] op_sel_hi:[1,0]
	v_pk_mul_f32 v[36:37], v[36:37], v[166:167]
	v_pk_fma_f32 v[136:137], v[136:137], s[2:3], v[168:169] op_sel_hi:[1,0,0]
	s_nop 0
	v_mul_f32_e32 v138, 0x4b800000, v136
	v_cmp_gt_f32_e64 s[0:1], s89, v136
	v_cmp_gt_f32_e32 vcc, s89, v137
	s_nop 0
	v_cndmask_b32_e64 v136, v136, v138, s[0:1]
	v_mul_f32_e32 v138, 0x4b800000, v137
	v_cndmask_b32_e32 v137, v137, v138, vcc
	v_rsq_f32_e32 v136, v136
	v_rsq_f32_e32 v137, v137
	s_nop 0
	v_pk_mul_f32 v[138:139], v[136:137], s[30:31] op_sel_hi:[1,0]
	s_nop 0
	v_cndmask_b32_e64 v162, v136, v138, s[0:1]
	v_ffbh_u32_e32 v136, v135
	v_min_u32_e32 v136, 32, v136
	v_lshlrev_b64 v[134:135], v136, v[134:135]
	v_min_u32_e32 v134, 1, v134
	v_or_b32_e32 v134, v135, v134
	v_cvt_f32_u32_e32 v134, v134
	v_sub_u32_e32 v135, 32, v136
	v_cndmask_b32_e32 v163, v137, v139, vcc
	v_ldexp_f32 v135, v134, v135
	v_ffbh_u32_e32 v134, v133
	v_min_u32_e32 v134, 32, v134
	v_lshlrev_b64 v[132:133], v134, v[132:133]
	v_min_u32_e32 v132, 1, v132
	v_or_b32_e32 v132, v133, v132
	v_cvt_f32_u32_e32 v132, v132
	v_sub_u32_e32 v133, 32, v134
	v_ldexp_f32 v134, v132, v133
	v_pk_mul_f32 v[132:133], v[134:135], s[34:35] op_sel_hi:[1,0]
	s_nop 0
	v_pk_fma_f32 v[132:133], v[132:133], s[2:3], v[168:169] op_sel_hi:[1,0,0]
	s_nop 0
	v_mul_f32_e32 v134, 0x4b800000, v132
	v_cmp_gt_f32_e64 s[0:1], s89, v132
	v_cmp_gt_f32_e32 vcc, s89, v133
	s_nop 0
	v_cndmask_b32_e64 v132, v132, v134, s[0:1]
	v_mul_f32_e32 v134, 0x4b800000, v133
	v_cndmask_b32_e32 v133, v133, v134, vcc
	v_rsq_f32_e32 v132, v132
	v_rsq_f32_e32 v133, v133
	s_nop 0
	v_pk_mul_f32 v[134:135], v[132:133], s[30:31] op_sel_hi:[1,0]
	s_nop 0
	v_cndmask_b32_e64 v188, v132, v134, s[0:1]
	v_ffbh_u32_e32 v132, v131
	v_min_u32_e32 v132, 32, v132
	v_lshlrev_b64 v[130:131], v132, v[130:131]
	v_min_u32_e32 v130, 1, v130
	v_or_b32_e32 v130, v131, v130
	v_cvt_f32_u32_e32 v130, v130
	v_sub_u32_e32 v131, 32, v132
	v_cndmask_b32_e32 v189, v133, v135, vcc
	v_pk_mul_f32 v[56:57], v[56:57], v[188:189]
	v_ldexp_f32 v131, v130, v131
	v_ffbh_u32_e32 v130, v129
	v_min_u32_e32 v130, 32, v130
	v_lshlrev_b64 v[128:129], v130, v[128:129]
	v_min_u32_e32 v128, 1, v128
	v_or_b32_e32 v128, v129, v128
	v_cvt_f32_u32_e32 v128, v128
	v_sub_u32_e32 v129, 32, v130
	v_pk_mul_f32 v[48:49], v[48:49], v[188:189]
	v_pk_mul_f32 v[40:41], v[40:41], v[188:189]
	v_ldexp_f32 v130, v128, v129
	v_pk_mul_f32 v[128:129], v[130:131], s[34:35] op_sel_hi:[1,0]
	v_pk_mul_f32 v[32:33], v[32:33], v[188:189]
	v_pk_fma_f32 v[128:129], v[128:129], s[2:3], v[168:169] op_sel_hi:[1,0,0]
	s_nop 0
	v_mul_f32_e32 v130, 0x4b800000, v128
	v_cmp_gt_f32_e64 s[0:1], s89, v128
	v_cmp_gt_f32_e32 vcc, s89, v129
	s_nop 0
	v_cndmask_b32_e64 v128, v128, v130, s[0:1]
	v_mul_f32_e32 v130, 0x4b800000, v129
	v_cndmask_b32_e32 v129, v129, v130, vcc
	v_rsq_f32_e32 v128, v128
	v_rsq_f32_e32 v129, v129
	s_nop 0
	v_pk_mul_f32 v[130:131], v[128:129], s[30:31] op_sel_hi:[1,0]
	s_nop 0
	v_cndmask_b32_e32 v165, v129, v131, vcc
	v_cndmask_b32_e64 v164, v128, v130, s[0:1]
	global_load_dwordx4 v[128:131], v[140:141], off offset:1072
	global_load_dwordx4 v[132:135], v[140:141], off offset:1056
	global_load_dwordx4 v[136:139], v[140:141], off offset:1040
	s_nop 0
	global_load_dwordx4 v[140:143], v[140:141], off offset:1024
	s_waitcnt vmcnt(0)
	v_ffbh_u32_e32 v161, v143
	v_min_u32_e32 v161, 32, v161
	v_lshlrev_b64 v[142:143], v161, v[142:143]
	v_min_u32_e32 v142, 1, v142
	v_or_b32_e32 v142, v143, v142
	v_cvt_f32_u32_e32 v142, v142
	v_sub_u32_e32 v143, 32, v161
	v_ldexp_f32 v143, v142, v143
	v_ffbh_u32_e32 v142, v141
	v_min_u32_e32 v142, 32, v142
	v_lshlrev_b64 v[140:141], v142, v[140:141]
	v_min_u32_e32 v140, 1, v140
	v_or_b32_e32 v140, v141, v140
	v_cvt_f32_u32_e32 v140, v140
	v_sub_u32_e32 v141, 32, v142
	v_ldexp_f32 v142, v140, v141
	v_pk_mul_f32 v[140:141], v[142:143], s[34:35] op_sel_hi:[1,0]
	s_nop 0
	v_pk_fma_f32 v[140:141], v[140:141], s[2:3], v[168:169] op_sel_hi:[1,0,0]
	s_nop 0
	v_mul_f32_e32 v142, 0x4b800000, v140
	v_cmp_gt_f32_e64 s[0:1], s89, v140
	v_cmp_gt_f32_e32 vcc, s89, v141
	s_nop 0
	v_cndmask_b32_e64 v140, v140, v142, s[0:1]
	v_mul_f32_e32 v142, 0x4b800000, v141
	v_cndmask_b32_e32 v141, v141, v142, vcc
	v_rsq_f32_e32 v140, v140
	v_rsq_f32_e32 v141, v141
	s_nop 0
	v_pk_mul_f32 v[142:143], v[140:141], s[30:31] op_sel_hi:[1,0]
	s_nop 0
	v_cndmask_b32_e64 v142, v140, v142, s[0:1]
	v_ffbh_u32_e32 v140, v139
	v_min_u32_e32 v140, 32, v140
	v_lshlrev_b64 v[138:139], v140, v[138:139]
	v_min_u32_e32 v138, 1, v138
	v_or_b32_e32 v138, v139, v138
	v_cvt_f32_u32_e32 v138, v138
	v_sub_u32_e32 v139, 32, v140
	v_cndmask_b32_e32 v143, v141, v143, vcc
	v_pk_mul_f32 v[140:141], v[124:125], v[166:167]
	v_ldexp_f32 v139, v138, v139
	v_ffbh_u32_e32 v138, v137
	v_min_u32_e32 v138, 32, v138
	v_lshlrev_b64 v[136:137], v138, v[136:137]
	v_min_u32_e32 v136, 1, v136
	v_or_b32_e32 v136, v137, v136
	v_cvt_f32_u32_e32 v136, v136
	v_sub_u32_e32 v137, 32, v138
	v_pk_mul_f32 v[28:29], v[28:29], v[142:143]
	v_pk_mul_f32 v[20:21], v[20:21], v[142:143]
	v_ldexp_f32 v138, v136, v137
	v_pk_mul_f32 v[136:137], v[138:139], s[34:35] op_sel_hi:[1,0]
	v_pk_mul_f32 v[12:13], v[12:13], v[142:143]
	v_pk_fma_f32 v[136:137], v[136:137], s[2:3], v[168:169] op_sel_hi:[1,0,0]
	v_pk_mul_f32 v[4:5], v[4:5], v[142:143]
	v_mul_f32_e32 v138, 0x4b800000, v136
	v_cmp_gt_f32_e64 s[0:1], s89, v136
	v_cmp_gt_f32_e32 vcc, s89, v137
	s_nop 0
	v_cndmask_b32_e64 v136, v136, v138, s[0:1]
	v_mul_f32_e32 v138, 0x4b800000, v137
	v_cndmask_b32_e32 v137, v137, v138, vcc
	v_rsq_f32_e32 v136, v136
	v_rsq_f32_e32 v137, v137
	s_nop 0
	v_pk_mul_f32 v[138:139], v[136:137], s[30:31] op_sel_hi:[1,0]
	s_nop 0
	v_cndmask_b32_e64 v136, v136, v138, s[0:1]
	v_ffbh_u32_e32 v138, v135
	v_min_u32_e32 v138, 32, v138
	v_lshlrev_b64 v[134:135], v138, v[134:135]
	v_min_u32_e32 v134, 1, v134
	v_or_b32_e32 v134, v135, v134
	v_cvt_f32_u32_e32 v134, v134
	v_sub_u32_e32 v135, 32, v138
	v_cndmask_b32_e32 v137, v137, v139, vcc
	v_pk_mul_f32 v[138:139], v[120:121], v[188:189]
	v_ldexp_f32 v135, v134, v135
	v_ffbh_u32_e32 v134, v133
	v_min_u32_e32 v134, 32, v134
	v_lshlrev_b64 v[132:133], v134, v[132:133]
	v_min_u32_e32 v132, 1, v132
	v_or_b32_e32 v132, v133, v132
	v_cvt_f32_u32_e32 v132, v132
	v_sub_u32_e32 v133, 32, v134
	v_pk_mul_f32 v[120:121], v[84:85], v[142:143]
	v_ldexp_f32 v134, v132, v133
	v_pk_mul_f32 v[132:133], v[134:135], s[34:35] op_sel_hi:[1,0]
	s_nop 0
	v_pk_fma_f32 v[132:133], v[132:133], s[2:3], v[168:169] op_sel_hi:[1,0,0]
	s_nop 0
	v_mul_f32_e32 v134, 0x4b800000, v132
	v_cmp_gt_f32_e64 s[0:1], s89, v132
	v_cmp_gt_f32_e32 vcc, s89, v133
	s_nop 0
	v_cndmask_b32_e64 v132, v132, v134, s[0:1]
	v_mul_f32_e32 v134, 0x4b800000, v133
	v_cndmask_b32_e32 v133, v133, v134, vcc
	v_rsq_f32_e32 v132, v132
	v_rsq_f32_e32 v133, v133
	s_nop 0
	v_pk_mul_f32 v[134:135], v[132:133], s[30:31] op_sel_hi:[1,0]
	s_nop 0
	v_cndmask_b32_e64 v176, v132, v134, s[0:1]
	v_ffbh_u32_e32 v132, v131
	v_min_u32_e32 v132, 32, v132
	v_lshlrev_b64 v[130:131], v132, v[130:131]
	v_min_u32_e32 v130, 1, v130
	v_or_b32_e32 v130, v131, v130
	v_cvt_f32_u32_e32 v130, v130
	v_sub_u32_e32 v131, 32, v132
	v_cndmask_b32_e32 v177, v133, v135, vcc
	v_pk_mul_f32 v[124:125], v[88:89], v[176:177]
	v_ldexp_f32 v131, v130, v131
	v_ffbh_u32_e32 v130, v129
	v_min_u32_e32 v130, 32, v130
	v_lshlrev_b64 v[128:129], v130, v[128:129]
	v_min_u32_e32 v128, 1, v128
	v_or_b32_e32 v128, v129, v128
	v_cvt_f32_u32_e32 v128, v128
	v_sub_u32_e32 v129, 32, v130
	v_pk_mul_f32 v[134:135], v[116:117], v[166:167]
	v_pk_mul_f32 v[132:133], v[112:113], v[188:189]
	v_ldexp_f32 v130, v128, v129
	v_pk_mul_f32 v[128:129], v[130:131], s[34:35] op_sel_hi:[1,0]
	v_pk_mul_f32 v[116:117], v[80:81], v[176:177]
	v_pk_fma_f32 v[128:129], v[128:129], s[2:3], v[168:169] op_sel_hi:[1,0,0]
	v_pk_mul_f32 v[88:89], v[104:105], v[188:189]
	v_mul_f32_e32 v130, 0x4b800000, v128
	v_cmp_gt_f32_e64 s[0:1], s89, v128
	v_cmp_gt_f32_e32 vcc, s89, v129
	v_pk_mul_f32 v[112:113], v[76:77], v[142:143]
	v_cndmask_b32_e64 v128, v128, v130, s[0:1]
	v_mul_f32_e32 v130, 0x4b800000, v129
	v_cndmask_b32_e32 v129, v129, v130, vcc
	v_rsq_f32_e32 v128, v128
	v_rsq_f32_e32 v129, v129
	v_pk_mul_f32 v[76:77], v[100:101], v[166:167]
	v_pk_mul_f32 v[104:105], v[68:69], v[142:143]
	v_pk_mul_f32 v[24:25], v[24:25], v[176:177]
	v_pk_mul_f32 v[130:131], v[128:129], s[30:31] op_sel_hi:[1,0]
	v_pk_mul_f32 v[16:17], v[16:17], v[176:177]
	v_cndmask_b32_e32 v129, v129, v131, vcc
	v_cndmask_b32_e64 v128, v128, v130, s[0:1]
	s_mov_b64 s[0:1], -1
	v_pk_mul_f32 v[130:131], v[92:93], v[142:143]
	v_pk_mul_f32 v[92:93], v[108:109], v[166:167]
	v_pk_mul_f32 v[108:109], v[72:73], v[176:177]
	v_pk_mul_f32 v[72:73], v[96:97], v[188:189]
	v_pk_mul_f32 v[96:97], v[64:65], v[176:177]
	v_pk_mul_f32 v[8:9], v[8:9], v[176:177]
	v_pk_mul_f32 v[0:1], v[0:1], v[176:177]
	s_cbranch_scc1 .LBB0_354
	v_lshl_add_u32 v68, s10, 8, v193
	v_ashrrev_i32_e32 v69, 31, v68
	v_pk_mul_f32 v[64:65], v[126:127], v[162:163]
	v_cvt_pk_bf16_f32 v80, v140, v141
	s_lshl_b64 s[0:1], s[50:51], 1
	v_cvt_pk_bf16_f32 v81, v64, v65
	v_lshlrev_b64 v[64:65], 13, v[68:69]
	v_lshl_add_u64 v[64:65], s[44:45], 0, v[64:65]
	v_lshl_add_u64 v[64:65], v[64:65], 0, s[0:1]
	v_lshl_add_u64 v[64:65], v[64:65], 0, v[144:145]
	v_mov_b32_e32 v161, v145
	v_lshl_add_u64 v[64:65], v[64:65], 0, v[160:161]
	global_store_dwordx2 v[64:65], v[80:81], off
	v_pk_mul_f32 v[80:81], v[122:123], v[164:165]
	v_cvt_pk_bf16_f32 v84, v138, v139
	s_nop 0
	v_cvt_pk_bf16_f32 v85, v80, v81
	v_pk_mul_f32 v[80:81], v[94:95], v[136:137]
	global_store_dwordx2 v[64:65], v[84:85], off offset:16
	v_cvt_pk_bf16_f32 v84, v130, v131
	v_cvt_pk_bf16_f32 v85, v80, v81
	v_pk_mul_f32 v[80:81], v[90:91], v[128:129]
	global_store_dwordx2 v[64:65], v[84:85], off offset:256
	v_cvt_pk_bf16_f32 v84, v124, v125
	v_cvt_pk_bf16_f32 v85, v80, v81
	v_or_b32_e32 v80, 16, v68
	v_ashrrev_i32_e32 v81, 31, v80
	v_lshlrev_b64 v[80:81], 13, v[80:81]
	v_lshl_add_u64 v[80:81], s[44:45], 0, v[80:81]
	v_lshl_add_u64 v[80:81], v[80:81], 0, s[0:1]
	v_lshl_add_u64 v[80:81], v[80:81], 0, v[144:145]
	global_store_dwordx2 v[64:65], v[84:85], off offset:272
	v_pk_mul_f32 v[84:85], v[118:119], v[162:163]
	v_cvt_pk_bf16_f32 v100, v134, v135
	v_lshl_add_u64 v[80:81], v[80:81], 0, v[160:161]
	v_cvt_pk_bf16_f32 v101, v84, v85
	global_store_dwordx2 v[80:81], v[100:101], off
	v_pk_mul_f32 v[84:85], v[114:115], v[164:165]
	v_cvt_pk_bf16_f32 v100, v132, v133
	s_nop 0
	v_cvt_pk_bf16_f32 v101, v84, v85
	global_store_dwordx2 v[80:81], v[100:101], off offset:16
	v_pk_mul_f32 v[84:85], v[86:87], v[136:137]
	v_cvt_pk_bf16_f32 v100, v120, v121
	s_nop 0
	v_cvt_pk_bf16_f32 v101, v84, v85
	global_store_dwordx2 v[80:81], v[100:101], off offset:256
	v_pk_mul_f32 v[84:85], v[82:83], v[128:129]
	v_cvt_pk_bf16_f32 v100, v116, v117
	s_nop 0
	v_cvt_pk_bf16_f32 v101, v84, v85
	global_store_dwordx2 v[80:81], v[100:101], off offset:272
	v_or_b32_e32 v80, 32, v68
	v_ashrrev_i32_e32 v81, 31, v80
	v_lshlrev_b64 v[80:81], 13, v[80:81]
	v_lshl_add_u64 v[80:81], s[44:45], 0, v[80:81]
	v_or_b32_e32 v68, 48, v68
	v_lshl_add_u64 v[80:81], v[80:81], 0, s[0:1]
	v_ashrrev_i32_e32 v69, 31, v68
	v_pk_mul_f32 v[84:85], v[110:111], v[162:163]
	v_lshl_add_u64 v[80:81], v[80:81], 0, v[144:145]
	v_lshlrev_b64 v[68:69], 13, v[68:69]
	v_cvt_pk_bf16_f32 v100, v92, v93
	v_cvt_pk_bf16_f32 v101, v84, v85
	v_lshl_add_u64 v[80:81], v[80:81], 0, v[160:161]
	v_pk_mul_f32 v[84:85], v[106:107], v[164:165]
	v_lshl_add_u64 v[68:69], s[44:45], 0, v[68:69]
	global_store_dwordx2 v[80:81], v[100:101], off
	v_cvt_pk_bf16_f32 v100, v88, v89
	v_cvt_pk_bf16_f32 v101, v84, v85
	v_pk_mul_f32 v[84:85], v[78:79], v[136:137]
	v_lshl_add_u64 v[68:69], v[68:69], 0, s[0:1]
	global_store_dwordx2 v[80:81], v[100:101], off offset:16
	v_cvt_pk_bf16_f32 v100, v112, v113
	v_cvt_pk_bf16_f32 v101, v84, v85
	v_pk_mul_f32 v[84:85], v[74:75], v[128:129]
	v_lshl_add_u64 v[68:69], v[68:69], 0, v[144:145]
	global_store_dwordx2 v[80:81], v[100:101], off offset:256
	v_cvt_pk_bf16_f32 v100, v108, v109
	v_cvt_pk_bf16_f32 v101, v84, v85
	global_store_dwordx2 v[80:81], v[100:101], off offset:272
	v_cvt_pk_bf16_f32 v84, v76, v77
	v_lshl_add_u64 v[68:69], v[68:69], 0, v[160:161]
	v_pk_mul_f32 v[80:81], v[102:103], v[162:163]
	s_mov_b64 s[0:1], 0x100000
	v_cvt_pk_bf16_f32 v85, v80, v81
	global_store_dwordx2 v[68:69], v[84:85], off
	v_cvt_pk_bf16_f32 v84, v72, v73
	v_pk_mul_f32 v[80:81], v[98:99], v[164:165]
	s_nop 0
	v_cvt_pk_bf16_f32 v85, v80, v81
	global_store_dwordx2 v[68:69], v[84:85], off offset:16
	v_cvt_pk_bf16_f32 v84, v104, v105
	v_pk_mul_f32 v[80:81], v[70:71], v[136:137]
	s_nop 0
	v_cvt_pk_bf16_f32 v85, v80, v81
	global_store_dwordx2 v[68:69], v[84:85], off offset:256
	v_cvt_pk_bf16_f32 v84, v96, v97
	v_pk_mul_f32 v[80:81], v[66:67], v[128:129]
	s_nop 0
	v_cvt_pk_bf16_f32 v85, v80, v81
	global_store_dwordx2 v[68:69], v[84:85], off offset:272
	v_add_co_u32_e32 v84, vcc, s29, v64
	v_pk_mul_f32 v[68:69], v[62:63], v[162:163]
	s_nop 0
	v_addc_co_u32_e32 v85, vcc, 0, v65, vcc
	v_cvt_pk_bf16_f32 v80, v60, v61
	v_cvt_pk_bf16_f32 v81, v68, v69
	v_lshl_add_u64 v[68:69], v[64:65], 0, s[0:1]
	global_store_dwordx2 v[84:85], v[80:81], off
	v_cvt_pk_bf16_f32 v84, v56, v57
	v_pk_mul_f32 v[80:81], v[58:59], v[164:165]
	s_mov_b64 s[0:1], 0x120000
	v_cvt_pk_bf16_f32 v85, v80, v81
	global_store_dwordx2 v[68:69], v[84:85], off offset:16
	v_cvt_pk_bf16_f32 v84, v28, v29
	v_pk_mul_f32 v[80:81], v[30:31], v[136:137]
	s_nop 0
	v_cvt_pk_bf16_f32 v85, v80, v81
	global_store_dwordx2 v[68:69], v[84:85], off offset:256
	v_cvt_pk_bf16_f32 v84, v24, v25
	v_pk_mul_f32 v[80:81], v[26:27], v[128:129]
	s_nop 0
	v_cvt_pk_bf16_f32 v85, v80, v81
	global_store_dwordx2 v[68:69], v[84:85], off offset:272
	v_add_co_u32_e32 v84, vcc, s49, v64
	v_pk_mul_f32 v[68:69], v[54:55], v[162:163]
	v_cvt_pk_bf16_f32 v80, v52, v53
	s_nop 0
	v_addc_co_u32_e32 v85, vcc, 0, v65, vcc
	v_cvt_pk_bf16_f32 v81, v68, v69
	v_lshl_add_u64 v[68:69], v[64:65], 0, s[0:1]
	global_store_dwordx2 v[84:85], v[80:81], off
	v_pk_mul_f32 v[80:81], v[50:51], v[164:165]
	v_cvt_pk_bf16_f32 v84, v48, v49
	s_mov_b64 s[0:1], 0x140000
	v_cvt_pk_bf16_f32 v85, v80, v81
	global_store_dwordx2 v[68:69], v[84:85], off offset:16
	v_pk_mul_f32 v[80:81], v[22:23], v[136:137]
	v_cvt_pk_bf16_f32 v84, v20, v21
	s_nop 0
	v_cvt_pk_bf16_f32 v85, v80, v81
	global_store_dwordx2 v[68:69], v[84:85], off offset:256
	v_pk_mul_f32 v[80:81], v[18:19], v[128:129]
	v_cvt_pk_bf16_f32 v84, v16, v17
	s_nop 0
	v_cvt_pk_bf16_f32 v85, v80, v81
	global_store_dwordx2 v[68:69], v[84:85], off offset:272
	v_pk_mul_f32 v[68:69], v[46:47], v[162:163]
	v_cvt_pk_bf16_f32 v80, v44, v45
	s_nop 0
	v_cvt_pk_bf16_f32 v81, v68, v69
	v_lshl_add_u64 v[68:69], v[64:65], 0, s[0:1]
	s_mov_b32 s0, 0x140000
	v_add_co_u32_e32 v84, vcc, s0, v64
	s_mov_b64 s[0:1], 0x160000
	s_nop 0
	v_addc_co_u32_e32 v85, vcc, 0, v65, vcc
	global_store_dwordx2 v[84:85], v[80:81], off
	v_pk_mul_f32 v[80:81], v[42:43], v[164:165]
	v_cvt_pk_bf16_f32 v84, v40, v41
	s_nop 0
	v_cvt_pk_bf16_f32 v85, v80, v81
	global_store_dwordx2 v[68:69], v[84:85], off offset:16
	v_pk_mul_f32 v[80:81], v[14:15], v[136:137]
	v_cvt_pk_bf16_f32 v84, v12, v13
	s_nop 0
	v_cvt_pk_bf16_f32 v85, v80, v81
	global_store_dwordx2 v[68:69], v[84:85], off offset:256
	v_pk_mul_f32 v[80:81], v[10:11], v[128:129]
	v_cvt_pk_bf16_f32 v84, v8, v9
	s_nop 0
	v_cvt_pk_bf16_f32 v85, v80, v81
	global_store_dwordx2 v[68:69], v[84:85], off offset:272
	v_pk_mul_f32 v[68:69], v[38:39], v[162:163]
	v_cvt_pk_bf16_f32 v80, v36, v37
	s_nop 0
	v_cvt_pk_bf16_f32 v81, v68, v69
	v_lshl_add_u64 v[68:69], v[64:65], 0, s[0:1]
	s_mov_b32 s0, 0x160000
	v_add_co_u32_e32 v64, vcc, s0, v64
	s_mov_b64 s[0:1], 0
	s_nop 0
	v_addc_co_u32_e32 v65, vcc, 0, v65, vcc
	global_store_dwordx2 v[64:65], v[80:81], off
	v_pk_mul_f32 v[64:65], v[34:35], v[164:165]
	v_cvt_pk_bf16_f32 v80, v32, v33
	s_nop 0
	v_cvt_pk_bf16_f32 v81, v64, v65
	global_store_dwordx2 v[68:69], v[80:81], off offset:16
	v_pk_mul_f32 v[64:65], v[6:7], v[136:137]
	v_cvt_pk_bf16_f32 v80, v4, v5
	s_nop 0
	v_cvt_pk_bf16_f32 v81, v64, v65
	global_store_dwordx2 v[68:69], v[80:81], off offset:256
	v_pk_mul_f32 v[64:65], v[2:3], v[128:129]
	v_cvt_pk_bf16_f32 v80, v0, v1
	s_nop 0
	v_cvt_pk_bf16_f32 v81, v64, v65
	s_nop 1
	global_store_dwordx2 v[68:69], v[80:81], off offset:272
